# bf16 norm phases: two rows of loads kept in flight per wave (row r+2 requested once row r is unpacked), table loads issued together; counted waits
# baseline (speedup 1.0000x reference)
; __device__ __forceinline__ v4u pk8(f32x4 a, f32x4 b) { v4u w; w.x = pk2(a[0], a[1]); w.y = pk2(a[2], a[3]); w.z = pk2(b[0], b[1]); w.w = pk2(b[2], b[3]); return w; }
; __device__ __forceinline__ float ssq8(const f32x4& a, const f32x4& b) { return ((a[0] * a[0] + a[1] * a[1]) + (a[2] * a[2] + a[3] * a[3])) + ((b[0] * b[0] + b[1] * b[1]) + (b[2] * b[2] + b[3] * b[3])); }
; template <int XF32> __device__ __forceinline__ void norm_mod_phase(const void* x, const float* modl, int ch_shift, int ch_scale, bf16* H, int gw, int NGW, int lane) {
;     ...
;         const int r0 = blk * 8, b = r0 >> 12;
;         const f32x4* shp = (const f32x4*)(modl + (size_t)b * MODW + ch_shift * DM); const f32x4* scp = (const f32x4*)(modl + (size_t)b * MODW + ch_scale * DM);
;         f32x4 sh[4][2], sc[4][2];
; #pragma unroll
;         for (int j = 0; j < 4; ++j)
; #pragma unroll
;             for (int q = 0; q < 2; ++q) { sh[j][q] = shp[2 * (lane + 64 * j) + q]; sc[j][q] = scp[2 * (lane + 64 * j) + q] + 1.f; }
;         for (int rr = 0; rr < 8; ++rr) {
;             const unsigned char* xr = (const unsigned char*)x + (size_t)(r0 + rr) * rowb; f32x4 v[4][2]; float s = 0.f;
; #pragma unroll
;             for (int j = 0; j < 4; ++j) ld_row8<XF32>(xr, lane, j, v[j][0], v[j][1]);
; #pragma unroll
;             for (int j = 0; j < 4; ++j) s += ssq8(v[j][0], v[j][1]);
;             const float rstd = 1.f / sqrtf(wave_sum(s) * (1.f / DM) + EPS);
;             v4u* o = (v4u*)(H + (size_t)(r0 + rr) * DM);
; #pragma unroll
;             for (int j = 0; j < 4; ++j) o[lane + 64 * j] = pk8(v[j][0] * rstd * sc[j][0] + sh[j][0], v[j][1] * rstd * sc[j][1] + sh[j][1]);
.LBB0_161:
	s_ashr_i32 s0, s3, 9
	s_mul_hi_i32 s1, s0, 0x12000
	s_mul_i32 s0, s0, 0x12000
	s_add_u32 s64, s24, s0
	s_addc_u32 s65, s26, s1
	s_add_u32 s4, s64, 0x2000
	s_addc_u32 s5, s65, 0
	v_lshl_add_u64 v[16:17], s[64:65], 0, v[38:39]
	v_lshl_add_u64 v[4:5], s[4:5], 0, v[38:39]
	global_load_dwordx4 v[8:11], v[16:17], off offset:16
	global_load_dwordx4 v[12:15], v[16:17], off
	global_load_dwordx4 v[178:181], v[4:5], off offset:16
	s_nop 0
	global_load_dwordx4 v[182:185], v[4:5], off
	v_lshl_add_u64 v[20:21], v[32:33], 4, s[4:5]
	v_lshl_add_u64 v[28:29], s[4:5], 0, v[40:41]
	v_lshl_add_u64 v[68:69], s[4:5], 0, v[42:43]
	s_add_i32 s0, s8, -7
	s_ashr_i32 s1, s0, 31
	s_ashr_i32 s9, s8, 31
	s_add_i32 s3, s3, s58
	global_load_dwordx4 v[0:3], v[16:17], off offset:2064
	global_load_dwordx4 v[4:7], v[16:17], off offset:2048
	s_nop 0
	global_load_dwordx4 v[186:189], v[20:21], off offset:16
	s_nop 0
	global_load_dwordx4 v[190:193], v[20:21], off
	v_lshl_add_u64 v[20:21], s[64:65], 0, v[40:41]
	global_load_dwordx4 v[16:19], v[20:21], off offset:16
	s_nop 0
	global_load_dwordx4 v[20:23], v[20:21], off
	s_nop 0
	global_load_dwordx4 v[194:197], v[28:29], off offset:16
	s_nop 0
	global_load_dwordx4 v[198:201], v[28:29], off
	v_lshl_add_u64 v[28:29], s[64:65], 0, v[42:43]
	global_load_dwordx4 v[24:27], v[28:29], off offset:16
	s_nop 0
	global_load_dwordx4 v[28:31], v[28:29], off
	s_nop 0
	global_load_dwordx4 v[202:205], v[68:69], off offset:16
	s_nop 0
	global_load_dwordx4 v[206:209], v[68:69], off
	s_lshl_b64 s[64:65], s[0:1], 12
	v_lshl_add_u64 v[88:89], v[34:35], 0, s[64:65]
	global_load_dwordx4 v[76:79], v[88:89], off
	global_load_dwordx4 v[80:83], v[88:89], off offset:1024
	global_load_dwordx4 v[84:87], v[88:89], off offset:2048
	s_nop 0
	global_load_dwordx4 v[88:91], v[88:89], off offset:3072
	s_waitcnt vmcnt(4)
	v_pk_add_f32 v[52:53], v[180:181], 1.0 op_sel_hi:[1,0]
	v_pk_add_f32 v[56:57], v[184:185], 1.0 op_sel_hi:[1,0]
	v_pk_add_f32 v[58:59], v[182:183], 1.0 op_sel_hi:[1,0]
	v_pk_add_f32 v[54:55], v[178:179], 1.0 op_sel_hi:[1,0]
	v_pk_add_f32 v[44:45], v[188:189], 1.0 op_sel_hi:[1,0]
	v_pk_add_f32 v[50:51], v[190:191], 1.0 op_sel_hi:[1,0]
	v_pk_add_f32 v[48:49], v[192:193], 1.0 op_sel_hi:[1,0]
	v_pk_add_f32 v[46:47], v[186:187], 1.0 op_sel_hi:[1,0]
	v_pk_add_f32 v[60:61], v[196:197], 1.0 op_sel_hi:[1,0]
	v_pk_add_f32 v[66:67], v[198:199], 1.0 op_sel_hi:[1,0]
	v_pk_add_f32 v[64:65], v[200:201], 1.0 op_sel_hi:[1,0]
	v_pk_add_f32 v[62:63], v[194:195], 1.0 op_sel_hi:[1,0]
	v_pk_add_f32 v[72:73], v[208:209], 1.0 op_sel_hi:[1,0]
	v_pk_add_f32 v[74:75], v[206:207], 1.0 op_sel_hi:[1,0]
	v_pk_add_f32 v[68:69], v[204:205], 1.0 op_sel_hi:[1,0]
	v_pk_add_f32 v[70:71], v[202:203], 1.0 op_sel_hi:[1,0]
	s_add_i32 s100, s8, -6
	s_ashr_i32 s101, s100, 31
	s_lshl_b64 s[100:101], s[100:101], 12
	v_lshl_add_u64 v[210:211], v[34:35], 0, s[100:101]
	s_nop 0
	global_load_dwordx4 v[194:197], v[210:211], off
	global_load_dwordx4 v[198:201], v[210:211], off offset:1024
	global_load_dwordx4 v[202:205], v[210:211], off offset:2048
	global_load_dwordx4 v[206:209], v[210:211], off offset:3072
	s_waitcnt vmcnt(7)
	v_lshlrev_b32_e32 v97, 16, v77
	v_lshlrev_b32_e32 v96, 16, v76
	v_and_b32_e32 v77, 0xffff0000, v77
	v_and_b32_e32 v76, 0xffff0000, v76
	v_lshlrev_b32_e32 v101, 16, v79
	v_lshlrev_b32_e32 v100, 16, v78
	v_and_b32_e32 v79, 0xffff0000, v79
	v_and_b32_e32 v78, 0xffff0000, v78
	v_pk_mul_f32 v[98:99], v[76:77], v[76:77]
	v_pk_mul_f32 v[102:103], v[78:79], v[78:79]
	s_waitcnt vmcnt(4)
	v_lshlrev_b32_e32 v92, 16, v88
	v_and_b32_e32 v93, 0xffff0000, v88
	v_pk_fma_f32 v[98:99], v[96:97], v[96:97], v[98:99]
	v_pk_fma_f32 v[102:103], v[100:101], v[100:101], v[102:103]
	v_lshlrev_b32_e32 v105, 16, v81
	v_lshlrev_b32_e32 v104, 16, v80
	v_and_b32_e32 v81, 0xffff0000, v81
	v_and_b32_e32 v80, 0xffff0000, v80
	v_lshlrev_b32_e32 v109, 16, v83
	v_lshlrev_b32_e32 v108, 16, v82
	v_and_b32_e32 v83, 0xffff0000, v83
	v_and_b32_e32 v82, 0xffff0000, v82
	v_pk_mul_f32 v[106:107], v[80:81], v[80:81]
	v_pk_mul_f32 v[110:111], v[82:83], v[82:83]
	v_mul_f32_e32 v116, v92, v92
	v_mul_f32_e32 v117, v93, v93
	v_pk_add_f32 v[98:99], v[98:99], v[98:99] op_sel:[0,1] op_sel_hi:[1,0]
	v_pk_add_f32 v[102:103], v[102:103], v[102:103] op_sel:[0,1] op_sel_hi:[1,0]
	v_lshlrev_b32_e32 v88, 16, v89
	v_and_b32_e32 v89, 0xffff0000, v89
	v_pk_fma_f32 v[106:107], v[104:105], v[104:105], v[106:107]
	v_pk_fma_f32 v[110:111], v[108:109], v[108:109], v[110:111]
	v_mov_b32_e32 v99, v116
	v_mov_b32_e32 v103, v117
	v_mul_f32_e32 v118, v88, v88
	v_mul_f32_e32 v119, v89, v89
	v_pk_add_f32 v[98:99], v[98:99], v[102:103]
	v_pk_add_f32 v[102:103], v[106:107], v[106:107] op_sel:[0,1] op_sel_hi:[1,0]
	v_pk_add_f32 v[106:107], v[110:111], v[110:111] op_sel:[0,1] op_sel_hi:[1,0]
	v_mov_b32_e32 v103, v118
	v_mov_b32_e32 v107, v119
	v_lshlrev_b32_e32 v112, 16, v84
	v_and_b32_e32 v113, 0xffff0000, v84
	v_lshlrev_b32_e32 v84, 16, v85
	v_and_b32_e32 v85, 0xffff0000, v85
	v_pk_add_f32 v[102:103], v[102:103], v[106:107]
	v_lshlrev_b32_e32 v94, 16, v90
	v_and_b32_e32 v95, 0xffff0000, v90
	v_pk_add_f32 v[98:99], v[98:99], v[102:103]
	v_mul_f32_e32 v102, v113, v113
	v_mul_f32_e32 v106, v85, v85
	v_mul_f32_e32 v120, v94, v94
	v_mul_f32_e32 v121, v95, v95
	v_pk_fma_f32 v[102:103], v[112:113], v[112:113], v[102:103] op_sel_hi:[1,1,0]
	v_pk_fma_f32 v[106:107], v[84:85], v[84:85], v[106:107] op_sel_hi:[1,1,0]
	v_lshlrev_b32_e32 v114, 16, v86
	v_and_b32_e32 v115, 0xffff0000, v86
	v_lshlrev_b32_e32 v86, 16, v87
	v_and_b32_e32 v87, 0xffff0000, v87
	v_mov_b32_e32 v103, v120
	v_mov_b32_e32 v107, v121
	v_lshlrev_b32_e32 v90, 16, v91
	v_and_b32_e32 v91, 0xffff0000, v91
	s_add_i32 s100, s8, -5
	s_ashr_i32 s101, s100, 31
	s_lshl_b64 s[100:101], s[100:101], 12
	v_lshl_add_u64 v[210:211], v[34:35], 0, s[100:101]
	s_nop 0
	global_load_dwordx4 v[178:181], v[210:211], off
	global_load_dwordx4 v[182:185], v[210:211], off offset:1024
	global_load_dwordx4 v[186:189], v[210:211], off offset:2048
	global_load_dwordx4 v[190:193], v[210:211], off offset:3072
	v_pk_add_f32 v[102:103], v[102:103], v[106:107]
	v_mul_f32_e32 v106, v115, v115
	v_mul_f32_e32 v110, v87, v87
	v_mul_f32_e32 v122, v90, v90
	v_mul_f32_e32 v123, v91, v91
	v_pk_fma_f32 v[106:107], v[114:115], v[114:115], v[106:107] op_sel_hi:[1,1,0]
	v_pk_fma_f32 v[110:111], v[86:87], v[86:87], v[110:111] op_sel_hi:[1,1,0]
	v_mov_b32_e32 v107, v122
	v_mov_b32_e32 v111, v123
	v_pk_add_f32 v[106:107], v[106:107], v[110:111]
	s_nop 0
	v_pk_add_f32 v[102:103], v[102:103], v[106:107]
	s_nop 0
	v_pk_add_f32 v[98:99], v[98:99], v[102:103]
	s_nop 0
	v_add_f32_e32 v98, v98, v99
	v_mbcnt_lo_u32_b32 v99, -1, 0
	v_mbcnt_hi_u32_b32 v99, -1, v99
	s_nop 0
	v_lshlrev_b32_e32 v99, 2, v99
	v_xor_b32_e32 v99, 4, v99
	ds_bpermute_b32 v99, v99, v98
	s_waitcnt lgkmcnt(0)
; __device__ __forceinline__ v4u pk8(f32x4 a, f32x4 b) { v4u w; w.x = pk2(a[0], a[1]); w.y = pk2(a[2], a[3]); w.z = pk2(b[0], b[1]); w.w = pk2(b[2], b[3]); return w; }
; __device__ __forceinline__ float ssq8(const f32x4& a, const f32x4& b) { return ((a[0] * a[0] + a[1] * a[1]) + (a[2] * a[2] + a[3] * a[3])) + ((b[0] * b[0] + b[1] * b[1]) + (b[2] * b[2] + b[3] * b[3])); }
; __device__ __forceinline__ float shfl_xor_f(float v, int o) {
;     int l; asm volatile("v_mbcnt_lo_u32_b32 %0, -1, 0\n\tv_mbcnt_hi_u32_b32 %0, -1, %0" : "=v"(l));
;     return __builtin_bit_cast(float, __builtin_amdgcn_ds_bpermute((l ^ o) << 2, __builtin_bit_cast(int, v)));
; }
; __device__ __forceinline__ float wave_sum(float v) {
; #pragma unroll
;     for (int o = 1; o < 64; o <<= 1) v += shfl_xor_f(v, o);
; template <int XF32> __device__ __forceinline__ void norm_mod_phase(const void* x, const float* modl, int ch_shift, int ch_scale, bf16* H, int gw, int NGW, int lane) {
;     ...
;         for (int rr = 0; rr < 8; ++rr) {
;             const unsigned char* xr = (const unsigned char*)x + (size_t)(r0 + rr) * rowb; f32x4 v[4][2]; float s = 0.f;
; #pragma unroll
;             for (int j = 0; j < 4; ++j) ld_row8<XF32>(xr, lane, j, v[j][0], v[j][1]);
; #pragma unroll
;             for (int j = 0; j < 4; ++j) s += ssq8(v[j][0], v[j][1]);
;             const float rstd = 1.f / sqrtf(wave_sum(s) * (1.f / DM) + EPS);
;             v4u* o = (v4u*)(H + (size_t)(r0 + rr) * DM);
; #pragma unroll
;             for (int j = 0; j < 4; ++j) o[lane + 64 * j] = pk8(v[j][0] * rstd * sc[j][0] + sh[j][0], v[j][1] * rstd * sc[j][1] + sh[j][1]);
	v_add_f32_e32 v98, v98, v99
	v_mbcnt_lo_u32_b32 v99, -1, 0
	v_mbcnt_hi_u32_b32 v99, -1, v99
	s_nop 0
	v_lshlrev_b32_e32 v99, 2, v99
	v_xor_b32_e32 v99, 8, v99
	ds_bpermute_b32 v99, v99, v98
	s_waitcnt lgkmcnt(0)
	v_add_f32_e32 v98, v98, v99
	v_mbcnt_lo_u32_b32 v99, -1, 0
	v_mbcnt_hi_u32_b32 v99, -1, v99
	s_nop 0
	v_lshlrev_b32_e32 v99, 2, v99
	v_xor_b32_e32 v99, 16, v99
	ds_bpermute_b32 v99, v99, v98
	s_waitcnt lgkmcnt(0)
	v_add_f32_e32 v98, v98, v99
	v_mbcnt_lo_u32_b32 v99, -1, 0
	v_mbcnt_hi_u32_b32 v99, -1, v99
	s_nop 0
	v_lshlrev_b32_e32 v99, 2, v99
	v_xor_b32_e32 v99, 32, v99
	ds_bpermute_b32 v99, v99, v98
	s_waitcnt lgkmcnt(0)
	v_add_f32_e32 v98, v98, v99
	v_mbcnt_lo_u32_b32 v99, -1, 0
	v_mbcnt_hi_u32_b32 v99, -1, v99
	s_nop 0
	v_lshlrev_b32_e32 v99, 2, v99
	v_xor_b32_e32 v99, 64, v99
	ds_bpermute_b32 v99, v99, v98
	s_waitcnt lgkmcnt(0)
	v_add_f32_e32 v98, v98, v99
	v_mbcnt_lo_u32_b32 v99, -1, 0
	v_mbcnt_hi_u32_b32 v99, -1, v99
	s_nop 0
	v_lshlrev_b32_e32 v99, 2, v99
	v_xor_b32_e32 v99, 0x80, v99
	ds_bpermute_b32 v99, v99, v98
	s_waitcnt lgkmcnt(0)
	v_add_f32_e32 v98, v98, v99
	v_fmamk_f32 v98, v98, 0x3a000000, v224
	v_cmp_gt_f32_e32 vcc, s41, v98
	v_mul_f32_e32 v99, 0x4f800000, v98
	s_nop 0
	v_cndmask_b32_e32 v98, v98, v99, vcc
	v_sqrt_f32_e32 v99, v98
	s_nop 0
	v_add_u32_e32 v102, -1, v99
	v_fma_f32 v103, -v102, v99, v98
	v_cmp_ge_f32_e64 s[4:5], 0, v103
	v_add_u32_e32 v103, 1, v99
	s_nop 0
	v_cndmask_b32_e64 v102, v99, v102, s[4:5]
	v_fma_f32 v99, -v103, v99, v98
	v_cmp_lt_f32_e64 s[4:5], 0, v99
	s_nop 1
	v_cndmask_b32_e64 v99, v102, v103, s[4:5]
	v_mul_f32_e32 v102, 0x37800000, v99
	v_cndmask_b32_e32 v99, v99, v102, vcc
	v_cmp_class_f32_e32 vcc, v98, v225
	s_nop 1
	v_cndmask_b32_e32 v98, v99, v98, vcc
	v_div_scale_f32 v99, s[0:1], v98, v98, 1.0
	v_rcp_f32_e32 v102, v99
	s_add_i32 s0, s8, -6
	s_ashr_i32 s1, s0, 31
	v_fma_f32 v103, -v99, v102, 1.0
	v_fmac_f32_e32 v102, v103, v102
	v_div_scale_f32 v103, vcc, 1.0, v98, 1.0
	v_mul_f32_e32 v106, v103, v102
	v_fma_f32 v107, -v99, v106, v103
	v_fmac_f32_e32 v106, v107, v102
	v_fma_f32 v99, -v99, v106, v103
	v_div_fmas_f32 v99, v99, v102, v106
	v_div_fixup_f32 v98, v99, v98, 1.0
	v_mov_b32_e32 v102, v96
	v_mov_b32_e32 v103, v76
	v_mov_b32_e32 v76, v97
	v_pk_mul_f32 v[102:103], v[98:99], v[102:103] op_sel_hi:[0,1]
	v_pk_mul_f32 v[76:77], v[98:99], v[76:77] op_sel_hi:[0,1]
	v_pk_fma_f32 v[96:97], v[56:57], v[76:77], v[14:15]
	v_pk_fma_f32 v[76:77], v[58:59], v[102:103], v[12:13]
	v_mov_b32_e32 v102, v100
	v_mov_b32_e32 v103, v78
	v_mov_b32_e32 v78, v101
	v_pk_mul_f32 v[102:103], v[98:99], v[102:103] op_sel_hi:[0,1]
	v_pk_mul_f32 v[78:79], v[98:99], v[78:79] op_sel_hi:[0,1]
	v_pk_fma_f32 v[100:101], v[52:53], v[78:79], v[10:11]
	v_pk_fma_f32 v[78:79], v[54:55], v[102:103], v[8:9]
	v_cvt_pk_bf16_f32 v76, v76, v77
	v_cvt_pk_bf16_f32 v77, v96, v97
	v_cvt_pk_bf16_f32 v78, v78, v79
	v_cvt_pk_bf16_f32 v79, v100, v101
	v_lshl_add_u64 v[96:97], v[36:37], 0, s[64:65]
	global_store_dwordx4 v[96:97], v[76:79], off
	s_lshl_b64 s[64:65], s[0:1], 12
	s_nop 0
	v_mov_b32_e32 v77, v80
	v_mov_b32_e32 v80, v105
	v_mov_b32_e32 v76, v104
	v_pk_mul_f32 v[78:79], v[98:99], v[80:81] op_sel_hi:[0,1]
	v_mov_b32_e32 v80, v108
	v_mov_b32_e32 v81, v82
	v_mov_b32_e32 v82, v109
	v_pk_mul_f32 v[76:77], v[98:99], v[76:77] op_sel_hi:[0,1]
	v_pk_mul_f32 v[80:81], v[98:99], v[80:81] op_sel_hi:[0,1]
	v_pk_mul_f32 v[82:83], v[98:99], v[82:83] op_sel_hi:[0,1]
	v_pk_fma_f32 v[78:79], v[48:49], v[78:79], v[6:7]
	v_pk_fma_f32 v[76:77], v[50:51], v[76:77], v[4:5]
	v_pk_fma_f32 v[82:83], v[44:45], v[82:83], v[2:3]
	v_pk_fma_f32 v[80:81], v[46:47], v[80:81], v[0:1]
	v_cvt_pk_bf16_f32 v76, v76, v77
	v_cvt_pk_bf16_f32 v77, v78, v79
	v_cvt_pk_bf16_f32 v78, v80, v81
	v_cvt_pk_bf16_f32 v79, v82, v83
	global_store_dwordx4 v[96:97], v[76:79], off offset:1024
	v_pk_mul_f32 v[80:81], v[98:99], v[114:115] op_sel_hi:[0,1]
	v_pk_mul_f32 v[82:83], v[98:99], v[86:87] op_sel_hi:[0,1]
	v_pk_mul_f32 v[76:77], v[98:99], v[112:113] op_sel_hi:[0,1]
	v_pk_mul_f32 v[78:79], v[98:99], v[84:85] op_sel_hi:[0,1]
	v_pk_fma_f32 v[78:79], v[64:65], v[78:79], v[22:23]
	v_pk_fma_f32 v[76:77], v[66:67], v[76:77], v[20:21]
	v_pk_fma_f32 v[82:83], v[60:61], v[82:83], v[18:19]
	v_pk_fma_f32 v[80:81], v[62:63], v[80:81], v[16:17]
	v_cvt_pk_bf16_f32 v76, v76, v77
	v_cvt_pk_bf16_f32 v77, v78, v79
	v_cvt_pk_bf16_f32 v78, v80, v81
	v_cvt_pk_bf16_f32 v79, v82, v83
	global_store_dwordx4 v[96:97], v[76:79], off offset:2048
	v_pk_mul_f32 v[80:81], v[94:95], v[98:99] op_sel_hi:[1,0]
	v_pk_mul_f32 v[82:83], v[90:91], v[98:99] op_sel_hi:[1,0]
	v_pk_mul_f32 v[76:77], v[92:93], v[98:99] op_sel_hi:[1,0]
	v_pk_mul_f32 v[78:79], v[88:89], v[98:99] op_sel_hi:[1,0]
	v_pk_fma_f32 v[76:77], v[74:75], v[76:77], v[28:29]
	v_pk_fma_f32 v[78:79], v[72:73], v[78:79], v[30:31]
	v_pk_fma_f32 v[82:83], v[68:69], v[82:83], v[26:27]
	v_pk_fma_f32 v[80:81], v[70:71], v[80:81], v[24:25]
	v_cvt_pk_bf16_f32 v76, v76, v77
	v_cvt_pk_bf16_f32 v77, v78, v79
	v_cvt_pk_bf16_f32 v78, v80, v81
	v_cvt_pk_bf16_f32 v79, v82, v83
	global_store_dwordx4 v[96:97], v[76:79], off offset:3072
	s_waitcnt vmcnt(11)
	v_lshlrev_b32_e32 v97, 16, v195
	v_lshlrev_b32_e32 v96, 16, v194
	v_and_b32_e32 v77, 0xffff0000, v195
	v_and_b32_e32 v76, 0xffff0000, v194
	v_lshlrev_b32_e32 v101, 16, v197
	v_lshlrev_b32_e32 v100, 16, v196
	v_and_b32_e32 v79, 0xffff0000, v197
	v_and_b32_e32 v78, 0xffff0000, v196
	v_pk_mul_f32 v[98:99], v[76:77], v[76:77]
	v_pk_mul_f32 v[102:103], v[78:79], v[78:79]
	s_waitcnt vmcnt(8)
; __device__ __forceinline__ v4u pk8(f32x4 a, f32x4 b) { v4u w; w.x = pk2(a[0], a[1]); w.y = pk2(a[2], a[3]); w.z = pk2(b[0], b[1]); w.w = pk2(b[2], b[3]); return w; }
; __device__ __forceinline__ float ssq8(const f32x4& a, const f32x4& b) { return ((a[0] * a[0] + a[1] * a[1]) + (a[2] * a[2] + a[3] * a[3])) + ((b[0] * b[0] + b[1] * b[1]) + (b[2] * b[2] + b[3] * b[3])); }
; __device__ __forceinline__ float shfl_xor_f(float v, int o) {
;     int l; asm volatile("v_mbcnt_lo_u32_b32 %0, -1, 0\n\tv_mbcnt_hi_u32_b32 %0, -1, %0" : "=v"(l));
;     return __builtin_bit_cast(float, __builtin_amdgcn_ds_bpermute((l ^ o) << 2, __builtin_bit_cast(int, v)));
; }
; __device__ __forceinline__ float wave_sum(float v) {
; #pragma unroll
;     for (int o = 1; o < 64; o <<= 1) v += shfl_xor_f(v, o);
; template <int XF32> __device__ __forceinline__ void norm_mod_phase(const void* x, const float* modl, int ch_shift, int ch_scale, bf16* H, int gw, int NGW, int lane) {
;     ...
;         for (int rr = 0; rr < 8; ++rr) {
;             const unsigned char* xr = (const unsigned char*)x + (size_t)(r0 + rr) * rowb; f32x4 v[4][2]; float s = 0.f;
; #pragma unroll
;             for (int j = 0; j < 4; ++j) ld_row8<XF32>(xr, lane, j, v[j][0], v[j][1]);
; #pragma unroll
;             for (int j = 0; j < 4; ++j) s += ssq8(v[j][0], v[j][1]);
;             const float rstd = 1.f / sqrtf(wave_sum(s) * (1.f / DM) + EPS);
;             v4u* o = (v4u*)(H + (size_t)(r0 + rr) * DM);
; #pragma unroll
;             for (int j = 0; j < 4; ++j) o[lane + 64 * j] = pk8(v[j][0] * rstd * sc[j][0] + sh[j][0], v[j][1] * rstd * sc[j][1] + sh[j][1]);
	v_lshlrev_b32_e32 v92, 16, v206
	v_and_b32_e32 v93, 0xffff0000, v206
	v_pk_fma_f32 v[98:99], v[96:97], v[96:97], v[98:99]
	v_pk_fma_f32 v[102:103], v[100:101], v[100:101], v[102:103]
	v_lshlrev_b32_e32 v105, 16, v199
	v_lshlrev_b32_e32 v104, 16, v198
	v_and_b32_e32 v81, 0xffff0000, v199
	v_and_b32_e32 v80, 0xffff0000, v198
	v_lshlrev_b32_e32 v109, 16, v201
	v_lshlrev_b32_e32 v108, 16, v200
	v_and_b32_e32 v83, 0xffff0000, v201
	v_and_b32_e32 v82, 0xffff0000, v200
	v_pk_mul_f32 v[106:107], v[80:81], v[80:81]
	v_pk_mul_f32 v[110:111], v[82:83], v[82:83]
	v_mul_f32_e32 v116, v92, v92
	v_mul_f32_e32 v117, v93, v93
	v_pk_add_f32 v[98:99], v[98:99], v[98:99] op_sel:[0,1] op_sel_hi:[1,0]
	v_pk_add_f32 v[102:103], v[102:103], v[102:103] op_sel:[0,1] op_sel_hi:[1,0]
	v_lshlrev_b32_e32 v88, 16, v207
	v_and_b32_e32 v89, 0xffff0000, v207
	v_pk_fma_f32 v[106:107], v[104:105], v[104:105], v[106:107]
	v_pk_fma_f32 v[110:111], v[108:109], v[108:109], v[110:111]
	v_mov_b32_e32 v99, v116
	v_mov_b32_e32 v103, v117
	v_mul_f32_e32 v118, v88, v88
	v_mul_f32_e32 v119, v89, v89
	v_pk_add_f32 v[98:99], v[98:99], v[102:103]
	v_pk_add_f32 v[102:103], v[106:107], v[106:107] op_sel:[0,1] op_sel_hi:[1,0]
	v_pk_add_f32 v[106:107], v[110:111], v[110:111] op_sel:[0,1] op_sel_hi:[1,0]
	v_mov_b32_e32 v103, v118
	v_mov_b32_e32 v107, v119
	v_lshlrev_b32_e32 v112, 16, v202
	v_and_b32_e32 v113, 0xffff0000, v202
	v_lshlrev_b32_e32 v84, 16, v203
	v_and_b32_e32 v85, 0xffff0000, v203
	v_pk_add_f32 v[102:103], v[102:103], v[106:107]
	v_lshlrev_b32_e32 v94, 16, v208
	v_and_b32_e32 v95, 0xffff0000, v208
	v_pk_add_f32 v[98:99], v[98:99], v[102:103]
	v_mul_f32_e32 v102, v113, v113
	v_mul_f32_e32 v106, v85, v85
	v_mul_f32_e32 v120, v94, v94
	v_mul_f32_e32 v121, v95, v95
	v_pk_fma_f32 v[102:103], v[112:113], v[112:113], v[102:103] op_sel_hi:[1,1,0]
	v_pk_fma_f32 v[106:107], v[84:85], v[84:85], v[106:107] op_sel_hi:[1,1,0]
	v_lshlrev_b32_e32 v114, 16, v204
	v_and_b32_e32 v115, 0xffff0000, v204
	v_lshlrev_b32_e32 v86, 16, v205
	v_and_b32_e32 v87, 0xffff0000, v205
	v_mov_b32_e32 v103, v120
	v_mov_b32_e32 v107, v121
	v_lshlrev_b32_e32 v90, 16, v209
	v_and_b32_e32 v91, 0xffff0000, v209
	s_add_i32 s100, s8, -4
	s_ashr_i32 s101, s100, 31
	s_lshl_b64 s[100:101], s[100:101], 12
	v_lshl_add_u64 v[210:211], v[34:35], 0, s[100:101]
	s_nop 0
	global_load_dwordx4 v[194:197], v[210:211], off
	global_load_dwordx4 v[198:201], v[210:211], off offset:1024
	global_load_dwordx4 v[202:205], v[210:211], off offset:2048
	global_load_dwordx4 v[206:209], v[210:211], off offset:3072
	v_pk_add_f32 v[102:103], v[102:103], v[106:107]
	v_mul_f32_e32 v106, v115, v115
	v_mul_f32_e32 v110, v87, v87
	v_mul_f32_e32 v122, v90, v90
	v_mul_f32_e32 v123, v91, v91
	v_pk_fma_f32 v[106:107], v[114:115], v[114:115], v[106:107] op_sel_hi:[1,1,0]
	v_pk_fma_f32 v[110:111], v[86:87], v[86:87], v[110:111] op_sel_hi:[1,1,0]
	v_mov_b32_e32 v107, v122
	v_mov_b32_e32 v111, v123
	v_pk_add_f32 v[106:107], v[106:107], v[110:111]
	s_nop 0
	v_pk_add_f32 v[102:103], v[102:103], v[106:107]
	s_nop 0
	v_pk_add_f32 v[98:99], v[98:99], v[102:103]
	s_nop 0
	v_add_f32_e32 v98, v98, v99
	v_mbcnt_lo_u32_b32 v99, -1, 0
	v_mbcnt_hi_u32_b32 v99, -1, v99
	s_nop 0
	v_lshlrev_b32_e32 v99, 2, v99
	v_xor_b32_e32 v99, 4, v99
	ds_bpermute_b32 v99, v99, v98
	s_waitcnt lgkmcnt(0)
	v_add_f32_e32 v98, v98, v99
	v_mbcnt_lo_u32_b32 v99, -1, 0
	v_mbcnt_hi_u32_b32 v99, -1, v99
	s_nop 0
	v_lshlrev_b32_e32 v99, 2, v99
	v_xor_b32_e32 v99, 8, v99
	ds_bpermute_b32 v99, v99, v98
	s_waitcnt lgkmcnt(0)
	v_add_f32_e32 v98, v98, v99
	v_mbcnt_lo_u32_b32 v99, -1, 0
	v_mbcnt_hi_u32_b32 v99, -1, v99
	s_nop 0
	v_lshlrev_b32_e32 v99, 2, v99
	v_xor_b32_e32 v99, 16, v99
	ds_bpermute_b32 v99, v99, v98
	s_waitcnt lgkmcnt(0)
	v_add_f32_e32 v98, v98, v99
	v_mbcnt_lo_u32_b32 v99, -1, 0
	v_mbcnt_hi_u32_b32 v99, -1, v99
	s_nop 0
	v_lshlrev_b32_e32 v99, 2, v99
	v_xor_b32_e32 v99, 32, v99
	ds_bpermute_b32 v99, v99, v98
	s_waitcnt lgkmcnt(0)
	v_add_f32_e32 v98, v98, v99
	v_mbcnt_lo_u32_b32 v99, -1, 0
	v_mbcnt_hi_u32_b32 v99, -1, v99
	s_nop 0
	v_lshlrev_b32_e32 v99, 2, v99
	v_xor_b32_e32 v99, 64, v99
	ds_bpermute_b32 v99, v99, v98
	s_waitcnt lgkmcnt(0)
	v_add_f32_e32 v98, v98, v99
	v_mbcnt_lo_u32_b32 v99, -1, 0
	v_mbcnt_hi_u32_b32 v99, -1, v99
	s_nop 0
	v_lshlrev_b32_e32 v99, 2, v99
	v_xor_b32_e32 v99, 0x80, v99
	ds_bpermute_b32 v99, v99, v98
	s_waitcnt lgkmcnt(0)
; __device__ __forceinline__ v4u pk8(f32x4 a, f32x4 b) { v4u w; w.x = pk2(a[0], a[1]); w.y = pk2(a[2], a[3]); w.z = pk2(b[0], b[1]); w.w = pk2(b[2], b[3]); return w; }
; __device__ __forceinline__ float ssq8(const f32x4& a, const f32x4& b) { return ((a[0] * a[0] + a[1] * a[1]) + (a[2] * a[2] + a[3] * a[3])) + ((b[0] * b[0] + b[1] * b[1]) + (b[2] * b[2] + b[3] * b[3])); }
; template <int XF32> __device__ __forceinline__ void norm_mod_phase(const void* x, const float* modl, int ch_shift, int ch_scale, bf16* H, int gw, int NGW, int lane) {
;     ...
;         for (int rr = 0; rr < 8; ++rr) {
;             const unsigned char* xr = (const unsigned char*)x + (size_t)(r0 + rr) * rowb; f32x4 v[4][2]; float s = 0.f;
; #pragma unroll
;             for (int j = 0; j < 4; ++j) ld_row8<XF32>(xr, lane, j, v[j][0], v[j][1]);
; #pragma unroll
;             for (int j = 0; j < 4; ++j) s += ssq8(v[j][0], v[j][1]);
;             const float rstd = 1.f / sqrtf(wave_sum(s) * (1.f / DM) + EPS);
;             v4u* o = (v4u*)(H + (size_t)(r0 + rr) * DM);
; #pragma unroll
;             for (int j = 0; j < 4; ++j) o[lane + 64 * j] = pk8(v[j][0] * rstd * sc[j][0] + sh[j][0], v[j][1] * rstd * sc[j][1] + sh[j][1]);
	v_add_f32_e32 v98, v98, v99
	v_fmamk_f32 v98, v98, 0x3a000000, v224
	v_cmp_gt_f32_e32 vcc, s41, v98
	v_mul_f32_e32 v99, 0x4f800000, v98
	s_nop 0
	v_cndmask_b32_e32 v98, v98, v99, vcc
	v_sqrt_f32_e32 v99, v98
	s_nop 0
	v_add_u32_e32 v102, -1, v99
	v_fma_f32 v103, -v102, v99, v98
	v_cmp_ge_f32_e64 s[4:5], 0, v103
	v_add_u32_e32 v103, 1, v99
	s_nop 0
	v_cndmask_b32_e64 v102, v99, v102, s[4:5]
	v_fma_f32 v99, -v103, v99, v98
	v_cmp_lt_f32_e64 s[4:5], 0, v99
	s_nop 1
	v_cndmask_b32_e64 v99, v102, v103, s[4:5]
	v_mul_f32_e32 v102, 0x37800000, v99
	v_cndmask_b32_e32 v99, v99, v102, vcc
	v_cmp_class_f32_e32 vcc, v98, v225
	s_nop 1
	v_cndmask_b32_e32 v98, v99, v98, vcc
	v_div_scale_f32 v99, s[0:1], v98, v98, 1.0
	v_rcp_f32_e32 v102, v99
	s_add_i32 s0, s8, -5
	s_ashr_i32 s1, s0, 31
	v_fma_f32 v103, -v99, v102, 1.0
	v_fmac_f32_e32 v102, v103, v102
	v_div_scale_f32 v103, vcc, 1.0, v98, 1.0
	v_mul_f32_e32 v106, v103, v102
	v_fma_f32 v107, -v99, v106, v103
	v_fmac_f32_e32 v106, v107, v102
	v_fma_f32 v99, -v99, v106, v103
	v_div_fmas_f32 v99, v99, v102, v106
	v_div_fixup_f32 v98, v99, v98, 1.0
	v_mov_b32_e32 v102, v96
	v_mov_b32_e32 v103, v76
	v_mov_b32_e32 v76, v97
	v_pk_mul_f32 v[102:103], v[98:99], v[102:103] op_sel_hi:[0,1]
	v_pk_mul_f32 v[76:77], v[98:99], v[76:77] op_sel_hi:[0,1]
	v_pk_fma_f32 v[96:97], v[56:57], v[76:77], v[14:15]
	v_pk_fma_f32 v[76:77], v[58:59], v[102:103], v[12:13]
	v_mov_b32_e32 v102, v100
	v_mov_b32_e32 v103, v78
	v_mov_b32_e32 v78, v101
	v_pk_mul_f32 v[102:103], v[98:99], v[102:103] op_sel_hi:[0,1]
	v_pk_mul_f32 v[78:79], v[98:99], v[78:79] op_sel_hi:[0,1]
	v_pk_fma_f32 v[100:101], v[52:53], v[78:79], v[10:11]
	v_pk_fma_f32 v[78:79], v[54:55], v[102:103], v[8:9]
	v_cvt_pk_bf16_f32 v76, v76, v77
	v_cvt_pk_bf16_f32 v77, v96, v97
	v_cvt_pk_bf16_f32 v78, v78, v79
	v_cvt_pk_bf16_f32 v79, v100, v101
	v_lshl_add_u64 v[96:97], v[36:37], 0, s[64:65]
	global_store_dwordx4 v[96:97], v[76:79], off
	s_lshl_b64 s[64:65], s[0:1], 12
	s_nop 0
	v_mov_b32_e32 v77, v80
	v_mov_b32_e32 v80, v105
	v_mov_b32_e32 v76, v104
	v_pk_mul_f32 v[78:79], v[98:99], v[80:81] op_sel_hi:[0,1]
	v_mov_b32_e32 v80, v108
	v_mov_b32_e32 v81, v82
	v_mov_b32_e32 v82, v109
	v_pk_mul_f32 v[76:77], v[98:99], v[76:77] op_sel_hi:[0,1]
	v_pk_mul_f32 v[80:81], v[98:99], v[80:81] op_sel_hi:[0,1]
	v_pk_mul_f32 v[82:83], v[98:99], v[82:83] op_sel_hi:[0,1]
	v_pk_fma_f32 v[78:79], v[48:49], v[78:79], v[6:7]
	v_pk_fma_f32 v[76:77], v[50:51], v[76:77], v[4:5]
	v_pk_fma_f32 v[82:83], v[44:45], v[82:83], v[2:3]
	v_pk_fma_f32 v[80:81], v[46:47], v[80:81], v[0:1]
	v_cvt_pk_bf16_f32 v76, v76, v77
	v_cvt_pk_bf16_f32 v77, v78, v79
	v_cvt_pk_bf16_f32 v78, v80, v81
	v_cvt_pk_bf16_f32 v79, v82, v83
	global_store_dwordx4 v[96:97], v[76:79], off offset:1024
	v_pk_mul_f32 v[80:81], v[98:99], v[114:115] op_sel_hi:[0,1]
	v_pk_mul_f32 v[82:83], v[98:99], v[86:87] op_sel_hi:[0,1]
	v_pk_mul_f32 v[76:77], v[98:99], v[112:113] op_sel_hi:[0,1]
	v_pk_mul_f32 v[78:79], v[98:99], v[84:85] op_sel_hi:[0,1]
	v_pk_fma_f32 v[78:79], v[64:65], v[78:79], v[22:23]
	v_pk_fma_f32 v[76:77], v[66:67], v[76:77], v[20:21]
	v_pk_fma_f32 v[82:83], v[60:61], v[82:83], v[18:19]
	v_pk_fma_f32 v[80:81], v[62:63], v[80:81], v[16:17]
	v_cvt_pk_bf16_f32 v76, v76, v77
	v_cvt_pk_bf16_f32 v77, v78, v79
	v_cvt_pk_bf16_f32 v78, v80, v81
	v_cvt_pk_bf16_f32 v79, v82, v83
	global_store_dwordx4 v[96:97], v[76:79], off offset:2048
	v_pk_mul_f32 v[80:81], v[94:95], v[98:99] op_sel_hi:[1,0]
	v_pk_mul_f32 v[82:83], v[90:91], v[98:99] op_sel_hi:[1,0]
	v_pk_mul_f32 v[76:77], v[92:93], v[98:99] op_sel_hi:[1,0]
	v_pk_mul_f32 v[78:79], v[88:89], v[98:99] op_sel_hi:[1,0]
	v_pk_fma_f32 v[76:77], v[74:75], v[76:77], v[28:29]
	v_pk_fma_f32 v[78:79], v[72:73], v[78:79], v[30:31]
	v_pk_fma_f32 v[82:83], v[68:69], v[82:83], v[26:27]
	v_pk_fma_f32 v[80:81], v[70:71], v[80:81], v[24:25]
	v_cvt_pk_bf16_f32 v76, v76, v77
	v_cvt_pk_bf16_f32 v77, v78, v79
	v_cvt_pk_bf16_f32 v78, v80, v81
	v_cvt_pk_bf16_f32 v79, v82, v83
	global_store_dwordx4 v[96:97], v[76:79], off offset:3072
	s_waitcnt vmcnt(11)
	v_lshlrev_b32_e32 v97, 16, v179
	v_lshlrev_b32_e32 v96, 16, v178
	v_and_b32_e32 v77, 0xffff0000, v179
	v_and_b32_e32 v76, 0xffff0000, v178
	v_lshlrev_b32_e32 v101, 16, v181
	v_lshlrev_b32_e32 v100, 16, v180
	v_and_b32_e32 v79, 0xffff0000, v181
	v_and_b32_e32 v78, 0xffff0000, v180
	v_pk_mul_f32 v[98:99], v[76:77], v[76:77]
	v_pk_mul_f32 v[102:103], v[78:79], v[78:79]
	s_waitcnt vmcnt(8)
; __device__ __forceinline__ v4u pk8(f32x4 a, f32x4 b) { v4u w; w.x = pk2(a[0], a[1]); w.y = pk2(a[2], a[3]); w.z = pk2(b[0], b[1]); w.w = pk2(b[2], b[3]); return w; }
; __device__ __forceinline__ float ssq8(const f32x4& a, const f32x4& b) { return ((a[0] * a[0] + a[1] * a[1]) + (a[2] * a[2] + a[3] * a[3])) + ((b[0] * b[0] + b[1] * b[1]) + (b[2] * b[2] + b[3] * b[3])); }
; __device__ __forceinline__ float shfl_xor_f(float v, int o) {
;     int l; asm volatile("v_mbcnt_lo_u32_b32 %0, -1, 0\n\tv_mbcnt_hi_u32_b32 %0, -1, %0" : "=v"(l));
;     return __builtin_bit_cast(float, __builtin_amdgcn_ds_bpermute((l ^ o) << 2, __builtin_bit_cast(int, v)));
; }
; __device__ __forceinline__ float wave_sum(float v) {
; #pragma unroll
;     for (int o = 1; o < 64; o <<= 1) v += shfl_xor_f(v, o);
; template <int XF32> __device__ __forceinline__ void norm_mod_phase(const void* x, const float* modl, int ch_shift, int ch_scale, bf16* H, int gw, int NGW, int lane) {
;     ...
;         for (int rr = 0; rr < 8; ++rr) {
;             const unsigned char* xr = (const unsigned char*)x + (size_t)(r0 + rr) * rowb; f32x4 v[4][2]; float s = 0.f;
; #pragma unroll
;             for (int j = 0; j < 4; ++j) ld_row8<XF32>(xr, lane, j, v[j][0], v[j][1]);
; #pragma unroll
;             for (int j = 0; j < 4; ++j) s += ssq8(v[j][0], v[j][1]);
;             const float rstd = 1.f / sqrtf(wave_sum(s) * (1.f / DM) + EPS);
;             v4u* o = (v4u*)(H + (size_t)(r0 + rr) * DM);
; #pragma unroll
;             for (int j = 0; j < 4; ++j) o[lane + 64 * j] = pk8(v[j][0] * rstd * sc[j][0] + sh[j][0], v[j][1] * rstd * sc[j][1] + sh[j][1]);
	v_lshlrev_b32_e32 v92, 16, v190
	v_and_b32_e32 v93, 0xffff0000, v190
	v_pk_fma_f32 v[98:99], v[96:97], v[96:97], v[98:99]
	v_pk_fma_f32 v[102:103], v[100:101], v[100:101], v[102:103]
	v_lshlrev_b32_e32 v105, 16, v183
	v_lshlrev_b32_e32 v104, 16, v182
	v_and_b32_e32 v81, 0xffff0000, v183
	v_and_b32_e32 v80, 0xffff0000, v182
	v_lshlrev_b32_e32 v109, 16, v185
	v_lshlrev_b32_e32 v108, 16, v184
	v_and_b32_e32 v83, 0xffff0000, v185
	v_and_b32_e32 v82, 0xffff0000, v184
	v_pk_mul_f32 v[106:107], v[80:81], v[80:81]
	v_pk_mul_f32 v[110:111], v[82:83], v[82:83]
	v_mul_f32_e32 v116, v92, v92
	v_mul_f32_e32 v117, v93, v93
	v_pk_add_f32 v[98:99], v[98:99], v[98:99] op_sel:[0,1] op_sel_hi:[1,0]
	v_pk_add_f32 v[102:103], v[102:103], v[102:103] op_sel:[0,1] op_sel_hi:[1,0]
	v_lshlrev_b32_e32 v88, 16, v191
	v_and_b32_e32 v89, 0xffff0000, v191
	v_pk_fma_f32 v[106:107], v[104:105], v[104:105], v[106:107]
	v_pk_fma_f32 v[110:111], v[108:109], v[108:109], v[110:111]
	v_mov_b32_e32 v99, v116
	v_mov_b32_e32 v103, v117
	v_mul_f32_e32 v118, v88, v88
	v_mul_f32_e32 v119, v89, v89
	v_pk_add_f32 v[98:99], v[98:99], v[102:103]
	v_pk_add_f32 v[102:103], v[106:107], v[106:107] op_sel:[0,1] op_sel_hi:[1,0]
	v_pk_add_f32 v[106:107], v[110:111], v[110:111] op_sel:[0,1] op_sel_hi:[1,0]
	v_mov_b32_e32 v103, v118
	v_mov_b32_e32 v107, v119
	v_lshlrev_b32_e32 v112, 16, v186
	v_and_b32_e32 v113, 0xffff0000, v186
	v_lshlrev_b32_e32 v84, 16, v187
	v_and_b32_e32 v85, 0xffff0000, v187
	v_pk_add_f32 v[102:103], v[102:103], v[106:107]
	v_lshlrev_b32_e32 v94, 16, v192
	v_and_b32_e32 v95, 0xffff0000, v192
	v_pk_add_f32 v[98:99], v[98:99], v[102:103]
	v_mul_f32_e32 v102, v113, v113
	v_mul_f32_e32 v106, v85, v85
	v_mul_f32_e32 v120, v94, v94
	v_mul_f32_e32 v121, v95, v95
	v_pk_fma_f32 v[102:103], v[112:113], v[112:113], v[102:103] op_sel_hi:[1,1,0]
	v_pk_fma_f32 v[106:107], v[84:85], v[84:85], v[106:107] op_sel_hi:[1,1,0]
	v_lshlrev_b32_e32 v114, 16, v188
	v_and_b32_e32 v115, 0xffff0000, v188
	v_lshlrev_b32_e32 v86, 16, v189
	v_and_b32_e32 v87, 0xffff0000, v189
	v_mov_b32_e32 v103, v120
	v_mov_b32_e32 v107, v121
	v_lshlrev_b32_e32 v90, 16, v193
	v_and_b32_e32 v91, 0xffff0000, v193
	s_add_i32 s100, s8, -3
	s_ashr_i32 s101, s100, 31
	s_lshl_b64 s[100:101], s[100:101], 12
	v_lshl_add_u64 v[210:211], v[34:35], 0, s[100:101]
	s_nop 0
	global_load_dwordx4 v[178:181], v[210:211], off
	global_load_dwordx4 v[182:185], v[210:211], off offset:1024
	global_load_dwordx4 v[186:189], v[210:211], off offset:2048
	global_load_dwordx4 v[190:193], v[210:211], off offset:3072
	v_pk_add_f32 v[102:103], v[102:103], v[106:107]
	v_mul_f32_e32 v106, v115, v115
	v_mul_f32_e32 v110, v87, v87
	v_mul_f32_e32 v122, v90, v90
	v_mul_f32_e32 v123, v91, v91
	v_pk_fma_f32 v[106:107], v[114:115], v[114:115], v[106:107] op_sel_hi:[1,1,0]
	v_pk_fma_f32 v[110:111], v[86:87], v[86:87], v[110:111] op_sel_hi:[1,1,0]
	v_mov_b32_e32 v107, v122
	v_mov_b32_e32 v111, v123
	v_pk_add_f32 v[106:107], v[106:107], v[110:111]
	s_nop 0
	v_pk_add_f32 v[102:103], v[102:103], v[106:107]
	s_nop 0
	v_pk_add_f32 v[98:99], v[98:99], v[102:103]
	s_nop 0
	v_add_f32_e32 v98, v98, v99
	v_mbcnt_lo_u32_b32 v99, -1, 0
	v_mbcnt_hi_u32_b32 v99, -1, v99
	s_nop 0
	v_lshlrev_b32_e32 v99, 2, v99
	v_xor_b32_e32 v99, 4, v99
	ds_bpermute_b32 v99, v99, v98
	s_waitcnt lgkmcnt(0)
	v_add_f32_e32 v98, v98, v99
	v_mbcnt_lo_u32_b32 v99, -1, 0
	v_mbcnt_hi_u32_b32 v99, -1, v99
	s_nop 0
	v_lshlrev_b32_e32 v99, 2, v99
	v_xor_b32_e32 v99, 8, v99
	ds_bpermute_b32 v99, v99, v98
	s_waitcnt lgkmcnt(0)
	v_add_f32_e32 v98, v98, v99
	v_mbcnt_lo_u32_b32 v99, -1, 0
	v_mbcnt_hi_u32_b32 v99, -1, v99
	s_nop 0
	v_lshlrev_b32_e32 v99, 2, v99
	v_xor_b32_e32 v99, 16, v99
	ds_bpermute_b32 v99, v99, v98
	s_waitcnt lgkmcnt(0)
	v_add_f32_e32 v98, v98, v99
	v_mbcnt_lo_u32_b32 v99, -1, 0
	v_mbcnt_hi_u32_b32 v99, -1, v99
	s_nop 0
	v_lshlrev_b32_e32 v99, 2, v99
	v_xor_b32_e32 v99, 32, v99
	ds_bpermute_b32 v99, v99, v98
	s_waitcnt lgkmcnt(0)
	v_add_f32_e32 v98, v98, v99
	v_mbcnt_lo_u32_b32 v99, -1, 0
	v_mbcnt_hi_u32_b32 v99, -1, v99
	s_nop 0
	v_lshlrev_b32_e32 v99, 2, v99
	v_xor_b32_e32 v99, 64, v99
	ds_bpermute_b32 v99, v99, v98
	s_waitcnt lgkmcnt(0)
	v_add_f32_e32 v98, v98, v99
	v_mbcnt_lo_u32_b32 v99, -1, 0
	v_mbcnt_hi_u32_b32 v99, -1, v99
	s_nop 0
	v_lshlrev_b32_e32 v99, 2, v99
	v_xor_b32_e32 v99, 0x80, v99
	ds_bpermute_b32 v99, v99, v98
	s_waitcnt lgkmcnt(0)
; __device__ __forceinline__ v4u pk8(f32x4 a, f32x4 b) { v4u w; w.x = pk2(a[0], a[1]); w.y = pk2(a[2], a[3]); w.z = pk2(b[0], b[1]); w.w = pk2(b[2], b[3]); return w; }
; __device__ __forceinline__ float ssq8(const f32x4& a, const f32x4& b) { return ((a[0] * a[0] + a[1] * a[1]) + (a[2] * a[2] + a[3] * a[3])) + ((b[0] * b[0] + b[1] * b[1]) + (b[2] * b[2] + b[3] * b[3])); }
; template <int XF32> __device__ __forceinline__ void norm_mod_phase(const void* x, const float* modl, int ch_shift, int ch_scale, bf16* H, int gw, int NGW, int lane) {
;     ...
;         for (int rr = 0; rr < 8; ++rr) {
;             const unsigned char* xr = (const unsigned char*)x + (size_t)(r0 + rr) * rowb; f32x4 v[4][2]; float s = 0.f;
; #pragma unroll
;             for (int j = 0; j < 4; ++j) ld_row8<XF32>(xr, lane, j, v[j][0], v[j][1]);
; #pragma unroll
;             for (int j = 0; j < 4; ++j) s += ssq8(v[j][0], v[j][1]);
;             const float rstd = 1.f / sqrtf(wave_sum(s) * (1.f / DM) + EPS);
;             v4u* o = (v4u*)(H + (size_t)(r0 + rr) * DM);
; #pragma unroll
;             for (int j = 0; j < 4; ++j) o[lane + 64 * j] = pk8(v[j][0] * rstd * sc[j][0] + sh[j][0], v[j][1] * rstd * sc[j][1] + sh[j][1]);
	v_add_f32_e32 v98, v98, v99
	v_fmamk_f32 v98, v98, 0x3a000000, v224
	v_cmp_gt_f32_e32 vcc, s41, v98
	v_mul_f32_e32 v99, 0x4f800000, v98
	s_nop 0
	v_cndmask_b32_e32 v98, v98, v99, vcc
	v_sqrt_f32_e32 v99, v98
	s_nop 0
	v_add_u32_e32 v102, -1, v99
	v_fma_f32 v103, -v102, v99, v98
	v_cmp_ge_f32_e64 s[4:5], 0, v103
	v_add_u32_e32 v103, 1, v99
	s_nop 0
	v_cndmask_b32_e64 v102, v99, v102, s[4:5]
	v_fma_f32 v99, -v103, v99, v98
	v_cmp_lt_f32_e64 s[4:5], 0, v99
	s_nop 1
	v_cndmask_b32_e64 v99, v102, v103, s[4:5]
	v_mul_f32_e32 v102, 0x37800000, v99
	v_cndmask_b32_e32 v99, v99, v102, vcc
	v_cmp_class_f32_e32 vcc, v98, v225
	s_nop 1
	v_cndmask_b32_e32 v98, v99, v98, vcc
	v_div_scale_f32 v99, s[0:1], v98, v98, 1.0
	v_rcp_f32_e32 v102, v99
	s_add_i32 s0, s8, -4
	s_ashr_i32 s1, s0, 31
	v_fma_f32 v103, -v99, v102, 1.0
	v_fmac_f32_e32 v102, v103, v102
	v_div_scale_f32 v103, vcc, 1.0, v98, 1.0
	v_mul_f32_e32 v106, v103, v102
	v_fma_f32 v107, -v99, v106, v103
	v_fmac_f32_e32 v106, v107, v102
	v_fma_f32 v99, -v99, v106, v103
	v_div_fmas_f32 v99, v99, v102, v106
	v_div_fixup_f32 v98, v99, v98, 1.0
	v_mov_b32_e32 v102, v96
	v_mov_b32_e32 v103, v76
	v_mov_b32_e32 v76, v97
	v_pk_mul_f32 v[102:103], v[98:99], v[102:103] op_sel_hi:[0,1]
	v_pk_mul_f32 v[76:77], v[98:99], v[76:77] op_sel_hi:[0,1]
	v_pk_fma_f32 v[96:97], v[56:57], v[76:77], v[14:15]
	v_pk_fma_f32 v[76:77], v[58:59], v[102:103], v[12:13]
	v_mov_b32_e32 v102, v100
	v_mov_b32_e32 v103, v78
	v_mov_b32_e32 v78, v101
	v_pk_mul_f32 v[102:103], v[98:99], v[102:103] op_sel_hi:[0,1]
	v_pk_mul_f32 v[78:79], v[98:99], v[78:79] op_sel_hi:[0,1]
	v_pk_fma_f32 v[100:101], v[52:53], v[78:79], v[10:11]
	v_pk_fma_f32 v[78:79], v[54:55], v[102:103], v[8:9]
	v_cvt_pk_bf16_f32 v76, v76, v77
	v_cvt_pk_bf16_f32 v77, v96, v97
	v_cvt_pk_bf16_f32 v78, v78, v79
	v_cvt_pk_bf16_f32 v79, v100, v101
	v_lshl_add_u64 v[96:97], v[36:37], 0, s[64:65]
	global_store_dwordx4 v[96:97], v[76:79], off
	s_lshl_b64 s[64:65], s[0:1], 12
	s_nop 0
	v_mov_b32_e32 v77, v80
	v_mov_b32_e32 v80, v105
	v_mov_b32_e32 v76, v104
	v_pk_mul_f32 v[78:79], v[98:99], v[80:81] op_sel_hi:[0,1]
	v_mov_b32_e32 v80, v108
	v_mov_b32_e32 v81, v82
	v_mov_b32_e32 v82, v109
	v_pk_mul_f32 v[76:77], v[98:99], v[76:77] op_sel_hi:[0,1]
	v_pk_mul_f32 v[80:81], v[98:99], v[80:81] op_sel_hi:[0,1]
	v_pk_mul_f32 v[82:83], v[98:99], v[82:83] op_sel_hi:[0,1]
	v_pk_fma_f32 v[78:79], v[48:49], v[78:79], v[6:7]
	v_pk_fma_f32 v[76:77], v[50:51], v[76:77], v[4:5]
	v_pk_fma_f32 v[82:83], v[44:45], v[82:83], v[2:3]
	v_pk_fma_f32 v[80:81], v[46:47], v[80:81], v[0:1]
	v_cvt_pk_bf16_f32 v76, v76, v77
	v_cvt_pk_bf16_f32 v77, v78, v79
	v_cvt_pk_bf16_f32 v78, v80, v81
	v_cvt_pk_bf16_f32 v79, v82, v83
	global_store_dwordx4 v[96:97], v[76:79], off offset:1024
	v_pk_mul_f32 v[80:81], v[98:99], v[114:115] op_sel_hi:[0,1]
	v_pk_mul_f32 v[82:83], v[98:99], v[86:87] op_sel_hi:[0,1]
	v_pk_mul_f32 v[76:77], v[98:99], v[112:113] op_sel_hi:[0,1]
	v_pk_mul_f32 v[78:79], v[98:99], v[84:85] op_sel_hi:[0,1]
	v_pk_fma_f32 v[78:79], v[64:65], v[78:79], v[22:23]
	v_pk_fma_f32 v[76:77], v[66:67], v[76:77], v[20:21]
	v_pk_fma_f32 v[82:83], v[60:61], v[82:83], v[18:19]
	v_pk_fma_f32 v[80:81], v[62:63], v[80:81], v[16:17]
	v_cvt_pk_bf16_f32 v76, v76, v77
	v_cvt_pk_bf16_f32 v77, v78, v79
	v_cvt_pk_bf16_f32 v78, v80, v81
	v_cvt_pk_bf16_f32 v79, v82, v83
	global_store_dwordx4 v[96:97], v[76:79], off offset:2048
	v_pk_mul_f32 v[80:81], v[94:95], v[98:99] op_sel_hi:[1,0]
	v_pk_mul_f32 v[82:83], v[90:91], v[98:99] op_sel_hi:[1,0]
	v_pk_mul_f32 v[76:77], v[92:93], v[98:99] op_sel_hi:[1,0]
	v_pk_mul_f32 v[78:79], v[88:89], v[98:99] op_sel_hi:[1,0]
	v_pk_fma_f32 v[76:77], v[74:75], v[76:77], v[28:29]
	v_pk_fma_f32 v[78:79], v[72:73], v[78:79], v[30:31]
	v_pk_fma_f32 v[82:83], v[68:69], v[82:83], v[26:27]
	v_pk_fma_f32 v[80:81], v[70:71], v[80:81], v[24:25]
	v_cvt_pk_bf16_f32 v76, v76, v77
	v_cvt_pk_bf16_f32 v77, v78, v79
	v_cvt_pk_bf16_f32 v78, v80, v81
	v_cvt_pk_bf16_f32 v79, v82, v83
	global_store_dwordx4 v[96:97], v[76:79], off offset:3072
	s_waitcnt vmcnt(11)
	v_lshlrev_b32_e32 v97, 16, v195
	v_lshlrev_b32_e32 v96, 16, v194
	v_and_b32_e32 v77, 0xffff0000, v195
	v_and_b32_e32 v76, 0xffff0000, v194
	v_lshlrev_b32_e32 v101, 16, v197
	v_lshlrev_b32_e32 v100, 16, v196
	v_and_b32_e32 v79, 0xffff0000, v197
	v_and_b32_e32 v78, 0xffff0000, v196
	v_pk_mul_f32 v[98:99], v[76:77], v[76:77]
	v_pk_mul_f32 v[102:103], v[78:79], v[78:79]
	s_waitcnt vmcnt(8)
; __device__ __forceinline__ v4u pk8(f32x4 a, f32x4 b) { v4u w; w.x = pk2(a[0], a[1]); w.y = pk2(a[2], a[3]); w.z = pk2(b[0], b[1]); w.w = pk2(b[2], b[3]); return w; }
; __device__ __forceinline__ float ssq8(const f32x4& a, const f32x4& b) { return ((a[0] * a[0] + a[1] * a[1]) + (a[2] * a[2] + a[3] * a[3])) + ((b[0] * b[0] + b[1] * b[1]) + (b[2] * b[2] + b[3] * b[3])); }
; __device__ __forceinline__ float shfl_xor_f(float v, int o) {
;     int l; asm volatile("v_mbcnt_lo_u32_b32 %0, -1, 0\n\tv_mbcnt_hi_u32_b32 %0, -1, %0" : "=v"(l));
;     return __builtin_bit_cast(float, __builtin_amdgcn_ds_bpermute((l ^ o) << 2, __builtin_bit_cast(int, v)));
; }
; __device__ __forceinline__ float wave_sum(float v) {
; #pragma unroll
;     for (int o = 1; o < 64; o <<= 1) v += shfl_xor_f(v, o);
; template <int XF32> __device__ __forceinline__ void norm_mod_phase(const void* x, const float* modl, int ch_shift, int ch_scale, bf16* H, int gw, int NGW, int lane) {
;     ...
;         for (int rr = 0; rr < 8; ++rr) {
;             const unsigned char* xr = (const unsigned char*)x + (size_t)(r0 + rr) * rowb; f32x4 v[4][2]; float s = 0.f;
; #pragma unroll
;             for (int j = 0; j < 4; ++j) ld_row8<XF32>(xr, lane, j, v[j][0], v[j][1]);
; #pragma unroll
;             for (int j = 0; j < 4; ++j) s += ssq8(v[j][0], v[j][1]);
;             const float rstd = 1.f / sqrtf(wave_sum(s) * (1.f / DM) + EPS);
;             v4u* o = (v4u*)(H + (size_t)(r0 + rr) * DM);
; #pragma unroll
;             for (int j = 0; j < 4; ++j) o[lane + 64 * j] = pk8(v[j][0] * rstd * sc[j][0] + sh[j][0], v[j][1] * rstd * sc[j][1] + sh[j][1]);
	v_lshlrev_b32_e32 v92, 16, v206
	v_and_b32_e32 v93, 0xffff0000, v206
	v_pk_fma_f32 v[98:99], v[96:97], v[96:97], v[98:99]
	v_pk_fma_f32 v[102:103], v[100:101], v[100:101], v[102:103]
	v_lshlrev_b32_e32 v105, 16, v199
	v_lshlrev_b32_e32 v104, 16, v198
	v_and_b32_e32 v81, 0xffff0000, v199
	v_and_b32_e32 v80, 0xffff0000, v198
	v_lshlrev_b32_e32 v109, 16, v201
	v_lshlrev_b32_e32 v108, 16, v200
	v_and_b32_e32 v83, 0xffff0000, v201
	v_and_b32_e32 v82, 0xffff0000, v200
	v_pk_mul_f32 v[106:107], v[80:81], v[80:81]
	v_pk_mul_f32 v[110:111], v[82:83], v[82:83]
	v_mul_f32_e32 v116, v92, v92
	v_mul_f32_e32 v117, v93, v93
	v_pk_add_f32 v[98:99], v[98:99], v[98:99] op_sel:[0,1] op_sel_hi:[1,0]
	v_pk_add_f32 v[102:103], v[102:103], v[102:103] op_sel:[0,1] op_sel_hi:[1,0]
	v_lshlrev_b32_e32 v88, 16, v207
	v_and_b32_e32 v89, 0xffff0000, v207
	v_pk_fma_f32 v[106:107], v[104:105], v[104:105], v[106:107]
	v_pk_fma_f32 v[110:111], v[108:109], v[108:109], v[110:111]
	v_mov_b32_e32 v99, v116
	v_mov_b32_e32 v103, v117
	v_mul_f32_e32 v118, v88, v88
	v_mul_f32_e32 v119, v89, v89
	v_pk_add_f32 v[98:99], v[98:99], v[102:103]
	v_pk_add_f32 v[102:103], v[106:107], v[106:107] op_sel:[0,1] op_sel_hi:[1,0]
	v_pk_add_f32 v[106:107], v[110:111], v[110:111] op_sel:[0,1] op_sel_hi:[1,0]
	v_mov_b32_e32 v103, v118
	v_mov_b32_e32 v107, v119
	v_lshlrev_b32_e32 v112, 16, v202
	v_and_b32_e32 v113, 0xffff0000, v202
	v_lshlrev_b32_e32 v84, 16, v203
	v_and_b32_e32 v85, 0xffff0000, v203
	v_pk_add_f32 v[102:103], v[102:103], v[106:107]
	v_lshlrev_b32_e32 v94, 16, v208
	v_and_b32_e32 v95, 0xffff0000, v208
	v_pk_add_f32 v[98:99], v[98:99], v[102:103]
	v_mul_f32_e32 v102, v113, v113
	v_mul_f32_e32 v106, v85, v85
	v_mul_f32_e32 v120, v94, v94
	v_mul_f32_e32 v121, v95, v95
	v_pk_fma_f32 v[102:103], v[112:113], v[112:113], v[102:103] op_sel_hi:[1,1,0]
	v_pk_fma_f32 v[106:107], v[84:85], v[84:85], v[106:107] op_sel_hi:[1,1,0]
	v_lshlrev_b32_e32 v114, 16, v204
	v_and_b32_e32 v115, 0xffff0000, v204
	v_lshlrev_b32_e32 v86, 16, v205
	v_and_b32_e32 v87, 0xffff0000, v205
	v_mov_b32_e32 v103, v120
	v_mov_b32_e32 v107, v121
	v_lshlrev_b32_e32 v90, 16, v209
	v_and_b32_e32 v91, 0xffff0000, v209
	s_add_i32 s100, s8, -2
	s_ashr_i32 s101, s100, 31
	s_lshl_b64 s[100:101], s[100:101], 12
	v_lshl_add_u64 v[210:211], v[34:35], 0, s[100:101]
	s_nop 0
	global_load_dwordx4 v[194:197], v[210:211], off
	global_load_dwordx4 v[198:201], v[210:211], off offset:1024
	global_load_dwordx4 v[202:205], v[210:211], off offset:2048
	global_load_dwordx4 v[206:209], v[210:211], off offset:3072
	v_pk_add_f32 v[102:103], v[102:103], v[106:107]
	v_mul_f32_e32 v106, v115, v115
	v_mul_f32_e32 v110, v87, v87
	v_mul_f32_e32 v122, v90, v90
	v_mul_f32_e32 v123, v91, v91
	v_pk_fma_f32 v[106:107], v[114:115], v[114:115], v[106:107] op_sel_hi:[1,1,0]
	v_pk_fma_f32 v[110:111], v[86:87], v[86:87], v[110:111] op_sel_hi:[1,1,0]
	v_mov_b32_e32 v107, v122
	v_mov_b32_e32 v111, v123
	v_pk_add_f32 v[106:107], v[106:107], v[110:111]
	s_nop 0
	v_pk_add_f32 v[102:103], v[102:103], v[106:107]
	s_nop 0
	v_pk_add_f32 v[98:99], v[98:99], v[102:103]
	s_nop 0
	v_add_f32_e32 v98, v98, v99
	v_mbcnt_lo_u32_b32 v99, -1, 0
	v_mbcnt_hi_u32_b32 v99, -1, v99
	s_nop 0
	v_lshlrev_b32_e32 v99, 2, v99
	v_xor_b32_e32 v99, 4, v99
	ds_bpermute_b32 v99, v99, v98
	s_waitcnt lgkmcnt(0)
	v_add_f32_e32 v98, v98, v99
	v_mbcnt_lo_u32_b32 v99, -1, 0
	v_mbcnt_hi_u32_b32 v99, -1, v99
	s_nop 0
	v_lshlrev_b32_e32 v99, 2, v99
	v_xor_b32_e32 v99, 8, v99
	ds_bpermute_b32 v99, v99, v98
	s_waitcnt lgkmcnt(0)
	v_add_f32_e32 v98, v98, v99
	v_mbcnt_lo_u32_b32 v99, -1, 0
	v_mbcnt_hi_u32_b32 v99, -1, v99
	s_nop 0
	v_lshlrev_b32_e32 v99, 2, v99
	v_xor_b32_e32 v99, 16, v99
	ds_bpermute_b32 v99, v99, v98
	s_waitcnt lgkmcnt(0)
	v_add_f32_e32 v98, v98, v99
	v_mbcnt_lo_u32_b32 v99, -1, 0
	v_mbcnt_hi_u32_b32 v99, -1, v99
	s_nop 0
	v_lshlrev_b32_e32 v99, 2, v99
	v_xor_b32_e32 v99, 32, v99
	ds_bpermute_b32 v99, v99, v98
	s_waitcnt lgkmcnt(0)
	v_add_f32_e32 v98, v98, v99
	v_mbcnt_lo_u32_b32 v99, -1, 0
	v_mbcnt_hi_u32_b32 v99, -1, v99
	s_nop 0
	v_lshlrev_b32_e32 v99, 2, v99
	v_xor_b32_e32 v99, 64, v99
	ds_bpermute_b32 v99, v99, v98
	s_waitcnt lgkmcnt(0)
	v_add_f32_e32 v98, v98, v99
	v_mbcnt_lo_u32_b32 v99, -1, 0
	v_mbcnt_hi_u32_b32 v99, -1, v99
	s_nop 0
	v_lshlrev_b32_e32 v99, 2, v99
	v_xor_b32_e32 v99, 0x80, v99
	ds_bpermute_b32 v99, v99, v98
	s_waitcnt lgkmcnt(0)
; __device__ __forceinline__ v4u pk8(f32x4 a, f32x4 b) { v4u w; w.x = pk2(a[0], a[1]); w.y = pk2(a[2], a[3]); w.z = pk2(b[0], b[1]); w.w = pk2(b[2], b[3]); return w; }
; __device__ __forceinline__ float ssq8(const f32x4& a, const f32x4& b) { return ((a[0] * a[0] + a[1] * a[1]) + (a[2] * a[2] + a[3] * a[3])) + ((b[0] * b[0] + b[1] * b[1]) + (b[2] * b[2] + b[3] * b[3])); }
; template <int XF32> __device__ __forceinline__ void norm_mod_phase(const void* x, const float* modl, int ch_shift, int ch_scale, bf16* H, int gw, int NGW, int lane) {
;     ...
;         for (int rr = 0; rr < 8; ++rr) {
;             const unsigned char* xr = (const unsigned char*)x + (size_t)(r0 + rr) * rowb; f32x4 v[4][2]; float s = 0.f;
; #pragma unroll
;             for (int j = 0; j < 4; ++j) ld_row8<XF32>(xr, lane, j, v[j][0], v[j][1]);
; #pragma unroll
;             for (int j = 0; j < 4; ++j) s += ssq8(v[j][0], v[j][1]);
;             const float rstd = 1.f / sqrtf(wave_sum(s) * (1.f / DM) + EPS);
;             v4u* o = (v4u*)(H + (size_t)(r0 + rr) * DM);
; #pragma unroll
;             for (int j = 0; j < 4; ++j) o[lane + 64 * j] = pk8(v[j][0] * rstd * sc[j][0] + sh[j][0], v[j][1] * rstd * sc[j][1] + sh[j][1]);
	v_add_f32_e32 v98, v98, v99
	v_fmamk_f32 v98, v98, 0x3a000000, v224
	v_cmp_gt_f32_e32 vcc, s41, v98
	v_mul_f32_e32 v99, 0x4f800000, v98
	s_nop 0
	v_cndmask_b32_e32 v98, v98, v99, vcc
	v_sqrt_f32_e32 v99, v98
	s_nop 0
	v_add_u32_e32 v102, -1, v99
	v_fma_f32 v103, -v102, v99, v98
	v_cmp_ge_f32_e64 s[4:5], 0, v103
	v_add_u32_e32 v103, 1, v99
	s_nop 0
	v_cndmask_b32_e64 v102, v99, v102, s[4:5]
	v_fma_f32 v99, -v103, v99, v98
	v_cmp_lt_f32_e64 s[4:5], 0, v99
	s_nop 1
	v_cndmask_b32_e64 v99, v102, v103, s[4:5]
	v_mul_f32_e32 v102, 0x37800000, v99
	v_cndmask_b32_e32 v99, v99, v102, vcc
	v_cmp_class_f32_e32 vcc, v98, v225
	s_nop 1
	v_cndmask_b32_e32 v98, v99, v98, vcc
	v_div_scale_f32 v99, s[0:1], v98, v98, 1.0
	v_rcp_f32_e32 v102, v99
	s_add_i32 s0, s8, -3
	s_ashr_i32 s1, s0, 31
	v_fma_f32 v103, -v99, v102, 1.0
	v_fmac_f32_e32 v102, v103, v102
	v_div_scale_f32 v103, vcc, 1.0, v98, 1.0
	v_mul_f32_e32 v106, v103, v102
	v_fma_f32 v107, -v99, v106, v103
	v_fmac_f32_e32 v106, v107, v102
	v_fma_f32 v99, -v99, v106, v103
	v_div_fmas_f32 v99, v99, v102, v106
	v_div_fixup_f32 v98, v99, v98, 1.0
	v_mov_b32_e32 v102, v96
	v_mov_b32_e32 v103, v76
	v_mov_b32_e32 v76, v97
	v_pk_mul_f32 v[102:103], v[98:99], v[102:103] op_sel_hi:[0,1]
	v_pk_mul_f32 v[76:77], v[98:99], v[76:77] op_sel_hi:[0,1]
	v_pk_fma_f32 v[96:97], v[56:57], v[76:77], v[14:15]
	v_pk_fma_f32 v[76:77], v[58:59], v[102:103], v[12:13]
	v_mov_b32_e32 v102, v100
	v_mov_b32_e32 v103, v78
	v_mov_b32_e32 v78, v101
	v_pk_mul_f32 v[102:103], v[98:99], v[102:103] op_sel_hi:[0,1]
	v_pk_mul_f32 v[78:79], v[98:99], v[78:79] op_sel_hi:[0,1]
	v_pk_fma_f32 v[100:101], v[52:53], v[78:79], v[10:11]
	v_pk_fma_f32 v[78:79], v[54:55], v[102:103], v[8:9]
	v_cvt_pk_bf16_f32 v76, v76, v77
	v_cvt_pk_bf16_f32 v77, v96, v97
	v_cvt_pk_bf16_f32 v78, v78, v79
	v_cvt_pk_bf16_f32 v79, v100, v101
	v_lshl_add_u64 v[96:97], v[36:37], 0, s[64:65]
	global_store_dwordx4 v[96:97], v[76:79], off
	s_lshl_b64 s[64:65], s[0:1], 12
	s_nop 0
	v_mov_b32_e32 v77, v80
	v_mov_b32_e32 v80, v105
	v_mov_b32_e32 v76, v104
	v_pk_mul_f32 v[78:79], v[98:99], v[80:81] op_sel_hi:[0,1]
	v_mov_b32_e32 v80, v108
	v_mov_b32_e32 v81, v82
	v_mov_b32_e32 v82, v109
	v_pk_mul_f32 v[76:77], v[98:99], v[76:77] op_sel_hi:[0,1]
	v_pk_mul_f32 v[80:81], v[98:99], v[80:81] op_sel_hi:[0,1]
	v_pk_mul_f32 v[82:83], v[98:99], v[82:83] op_sel_hi:[0,1]
	v_pk_fma_f32 v[78:79], v[48:49], v[78:79], v[6:7]
	v_pk_fma_f32 v[76:77], v[50:51], v[76:77], v[4:5]
	v_pk_fma_f32 v[82:83], v[44:45], v[82:83], v[2:3]
	v_pk_fma_f32 v[80:81], v[46:47], v[80:81], v[0:1]
	v_cvt_pk_bf16_f32 v76, v76, v77
	v_cvt_pk_bf16_f32 v77, v78, v79
	v_cvt_pk_bf16_f32 v78, v80, v81
	v_cvt_pk_bf16_f32 v79, v82, v83
	global_store_dwordx4 v[96:97], v[76:79], off offset:1024
	v_pk_mul_f32 v[80:81], v[98:99], v[114:115] op_sel_hi:[0,1]
	v_pk_mul_f32 v[82:83], v[98:99], v[86:87] op_sel_hi:[0,1]
	v_pk_mul_f32 v[76:77], v[98:99], v[112:113] op_sel_hi:[0,1]
	v_pk_mul_f32 v[78:79], v[98:99], v[84:85] op_sel_hi:[0,1]
	v_pk_fma_f32 v[78:79], v[64:65], v[78:79], v[22:23]
	v_pk_fma_f32 v[76:77], v[66:67], v[76:77], v[20:21]
	v_pk_fma_f32 v[82:83], v[60:61], v[82:83], v[18:19]
	v_pk_fma_f32 v[80:81], v[62:63], v[80:81], v[16:17]
	v_cvt_pk_bf16_f32 v76, v76, v77
	v_cvt_pk_bf16_f32 v77, v78, v79
	v_cvt_pk_bf16_f32 v78, v80, v81
	v_cvt_pk_bf16_f32 v79, v82, v83
	global_store_dwordx4 v[96:97], v[76:79], off offset:2048
	v_pk_mul_f32 v[80:81], v[94:95], v[98:99] op_sel_hi:[1,0]
	v_pk_mul_f32 v[82:83], v[90:91], v[98:99] op_sel_hi:[1,0]
	v_pk_mul_f32 v[76:77], v[92:93], v[98:99] op_sel_hi:[1,0]
	v_pk_mul_f32 v[78:79], v[88:89], v[98:99] op_sel_hi:[1,0]
	v_pk_fma_f32 v[76:77], v[74:75], v[76:77], v[28:29]
	v_pk_fma_f32 v[78:79], v[72:73], v[78:79], v[30:31]
	v_pk_fma_f32 v[82:83], v[68:69], v[82:83], v[26:27]
	v_pk_fma_f32 v[80:81], v[70:71], v[80:81], v[24:25]
	v_cvt_pk_bf16_f32 v76, v76, v77
	v_cvt_pk_bf16_f32 v77, v78, v79
	v_cvt_pk_bf16_f32 v78, v80, v81
	v_cvt_pk_bf16_f32 v79, v82, v83
	global_store_dwordx4 v[96:97], v[76:79], off offset:3072
	s_waitcnt vmcnt(11)
	v_lshlrev_b32_e32 v97, 16, v179
	v_lshlrev_b32_e32 v96, 16, v178
	v_and_b32_e32 v77, 0xffff0000, v179
	v_and_b32_e32 v76, 0xffff0000, v178
	v_lshlrev_b32_e32 v101, 16, v181
	v_lshlrev_b32_e32 v100, 16, v180
	v_and_b32_e32 v79, 0xffff0000, v181
	v_and_b32_e32 v78, 0xffff0000, v180
	v_pk_mul_f32 v[98:99], v[76:77], v[76:77]
	v_pk_mul_f32 v[102:103], v[78:79], v[78:79]
	s_waitcnt vmcnt(8)
; __device__ __forceinline__ v4u pk8(f32x4 a, f32x4 b) { v4u w; w.x = pk2(a[0], a[1]); w.y = pk2(a[2], a[3]); w.z = pk2(b[0], b[1]); w.w = pk2(b[2], b[3]); return w; }
; __device__ __forceinline__ float ssq8(const f32x4& a, const f32x4& b) { return ((a[0] * a[0] + a[1] * a[1]) + (a[2] * a[2] + a[3] * a[3])) + ((b[0] * b[0] + b[1] * b[1]) + (b[2] * b[2] + b[3] * b[3])); }
; __device__ __forceinline__ float shfl_xor_f(float v, int o) {
;     int l; asm volatile("v_mbcnt_lo_u32_b32 %0, -1, 0\n\tv_mbcnt_hi_u32_b32 %0, -1, %0" : "=v"(l));
;     return __builtin_bit_cast(float, __builtin_amdgcn_ds_bpermute((l ^ o) << 2, __builtin_bit_cast(int, v)));
; }
; __device__ __forceinline__ float wave_sum(float v) {
; #pragma unroll
;     for (int o = 1; o < 64; o <<= 1) v += shfl_xor_f(v, o);
; template <int XF32> __device__ __forceinline__ void norm_mod_phase(const void* x, const float* modl, int ch_shift, int ch_scale, bf16* H, int gw, int NGW, int lane) {
;     ...
;         for (int rr = 0; rr < 8; ++rr) {
;             const unsigned char* xr = (const unsigned char*)x + (size_t)(r0 + rr) * rowb; f32x4 v[4][2]; float s = 0.f;
; #pragma unroll
;             for (int j = 0; j < 4; ++j) ld_row8<XF32>(xr, lane, j, v[j][0], v[j][1]);
; #pragma unroll
;             for (int j = 0; j < 4; ++j) s += ssq8(v[j][0], v[j][1]);
;             const float rstd = 1.f / sqrtf(wave_sum(s) * (1.f / DM) + EPS);
;             v4u* o = (v4u*)(H + (size_t)(r0 + rr) * DM);
; #pragma unroll
;             for (int j = 0; j < 4; ++j) o[lane + 64 * j] = pk8(v[j][0] * rstd * sc[j][0] + sh[j][0], v[j][1] * rstd * sc[j][1] + sh[j][1]);
	v_lshlrev_b32_e32 v92, 16, v190
	v_and_b32_e32 v93, 0xffff0000, v190
	v_pk_fma_f32 v[98:99], v[96:97], v[96:97], v[98:99]
	v_pk_fma_f32 v[102:103], v[100:101], v[100:101], v[102:103]
	v_lshlrev_b32_e32 v105, 16, v183
	v_lshlrev_b32_e32 v104, 16, v182
	v_and_b32_e32 v81, 0xffff0000, v183
	v_and_b32_e32 v80, 0xffff0000, v182
	v_lshlrev_b32_e32 v109, 16, v185
	v_lshlrev_b32_e32 v108, 16, v184
	v_and_b32_e32 v83, 0xffff0000, v185
	v_and_b32_e32 v82, 0xffff0000, v184
	v_pk_mul_f32 v[106:107], v[80:81], v[80:81]
	v_pk_mul_f32 v[110:111], v[82:83], v[82:83]
	v_mul_f32_e32 v116, v92, v92
	v_mul_f32_e32 v117, v93, v93
	v_pk_add_f32 v[98:99], v[98:99], v[98:99] op_sel:[0,1] op_sel_hi:[1,0]
	v_pk_add_f32 v[102:103], v[102:103], v[102:103] op_sel:[0,1] op_sel_hi:[1,0]
	v_lshlrev_b32_e32 v88, 16, v191
	v_and_b32_e32 v89, 0xffff0000, v191
	v_pk_fma_f32 v[106:107], v[104:105], v[104:105], v[106:107]
	v_pk_fma_f32 v[110:111], v[108:109], v[108:109], v[110:111]
	v_mov_b32_e32 v99, v116
	v_mov_b32_e32 v103, v117
	v_mul_f32_e32 v118, v88, v88
	v_mul_f32_e32 v119, v89, v89
	v_pk_add_f32 v[98:99], v[98:99], v[102:103]
	v_pk_add_f32 v[102:103], v[106:107], v[106:107] op_sel:[0,1] op_sel_hi:[1,0]
	v_pk_add_f32 v[106:107], v[110:111], v[110:111] op_sel:[0,1] op_sel_hi:[1,0]
	v_mov_b32_e32 v103, v118
	v_mov_b32_e32 v107, v119
	v_lshlrev_b32_e32 v112, 16, v186
	v_and_b32_e32 v113, 0xffff0000, v186
	v_lshlrev_b32_e32 v84, 16, v187
	v_and_b32_e32 v85, 0xffff0000, v187
	v_pk_add_f32 v[102:103], v[102:103], v[106:107]
	v_lshlrev_b32_e32 v94, 16, v192
	v_and_b32_e32 v95, 0xffff0000, v192
	v_pk_add_f32 v[98:99], v[98:99], v[102:103]
	v_mul_f32_e32 v102, v113, v113
	v_mul_f32_e32 v106, v85, v85
	v_mul_f32_e32 v120, v94, v94
	v_mul_f32_e32 v121, v95, v95
	v_pk_fma_f32 v[102:103], v[112:113], v[112:113], v[102:103] op_sel_hi:[1,1,0]
	v_pk_fma_f32 v[106:107], v[84:85], v[84:85], v[106:107] op_sel_hi:[1,1,0]
	v_lshlrev_b32_e32 v114, 16, v188
	v_and_b32_e32 v115, 0xffff0000, v188
	v_lshlrev_b32_e32 v86, 16, v189
	v_and_b32_e32 v87, 0xffff0000, v189
	v_mov_b32_e32 v103, v120
	v_mov_b32_e32 v107, v121
	v_lshlrev_b32_e32 v90, 16, v193
	v_and_b32_e32 v91, 0xffff0000, v193
	s_add_i32 s100, s8, -1
	s_ashr_i32 s101, s100, 31
	s_lshl_b64 s[100:101], s[100:101], 12
	v_lshl_add_u64 v[210:211], v[34:35], 0, s[100:101]
	s_nop 0
	global_load_dwordx4 v[178:181], v[210:211], off
	global_load_dwordx4 v[182:185], v[210:211], off offset:1024
	global_load_dwordx4 v[186:189], v[210:211], off offset:2048
	global_load_dwordx4 v[190:193], v[210:211], off offset:3072
	v_pk_add_f32 v[102:103], v[102:103], v[106:107]
	v_mul_f32_e32 v106, v115, v115
	v_mul_f32_e32 v110, v87, v87
	v_mul_f32_e32 v122, v90, v90
	v_mul_f32_e32 v123, v91, v91
	v_pk_fma_f32 v[106:107], v[114:115], v[114:115], v[106:107] op_sel_hi:[1,1,0]
	v_pk_fma_f32 v[110:111], v[86:87], v[86:87], v[110:111] op_sel_hi:[1,1,0]
	v_mov_b32_e32 v107, v122
	v_mov_b32_e32 v111, v123
	v_pk_add_f32 v[106:107], v[106:107], v[110:111]
	s_nop 0
	v_pk_add_f32 v[102:103], v[102:103], v[106:107]
	s_nop 0
	v_pk_add_f32 v[98:99], v[98:99], v[102:103]
	s_nop 0
	v_add_f32_e32 v98, v98, v99
	v_mbcnt_lo_u32_b32 v99, -1, 0
	v_mbcnt_hi_u32_b32 v99, -1, v99
	s_nop 0
	v_lshlrev_b32_e32 v99, 2, v99
	v_xor_b32_e32 v99, 4, v99
	ds_bpermute_b32 v99, v99, v98
	s_waitcnt lgkmcnt(0)
	v_add_f32_e32 v98, v98, v99
	v_mbcnt_lo_u32_b32 v99, -1, 0
	v_mbcnt_hi_u32_b32 v99, -1, v99
	s_nop 0
	v_lshlrev_b32_e32 v99, 2, v99
	v_xor_b32_e32 v99, 8, v99
	ds_bpermute_b32 v99, v99, v98
	s_waitcnt lgkmcnt(0)
	v_add_f32_e32 v98, v98, v99
	v_mbcnt_lo_u32_b32 v99, -1, 0
	v_mbcnt_hi_u32_b32 v99, -1, v99
	s_nop 0
	v_lshlrev_b32_e32 v99, 2, v99
	v_xor_b32_e32 v99, 16, v99
	ds_bpermute_b32 v99, v99, v98
	s_waitcnt lgkmcnt(0)
	v_add_f32_e32 v98, v98, v99
	v_mbcnt_lo_u32_b32 v99, -1, 0
	v_mbcnt_hi_u32_b32 v99, -1, v99
	s_nop 0
	v_lshlrev_b32_e32 v99, 2, v99
	v_xor_b32_e32 v99, 32, v99
	ds_bpermute_b32 v99, v99, v98
	s_waitcnt lgkmcnt(0)
	v_add_f32_e32 v98, v98, v99
	v_mbcnt_lo_u32_b32 v99, -1, 0
	v_mbcnt_hi_u32_b32 v99, -1, v99
	s_nop 0
	v_lshlrev_b32_e32 v99, 2, v99
	v_xor_b32_e32 v99, 64, v99
	ds_bpermute_b32 v99, v99, v98
	s_waitcnt lgkmcnt(0)
	v_add_f32_e32 v98, v98, v99
	v_mbcnt_lo_u32_b32 v99, -1, 0
	v_mbcnt_hi_u32_b32 v99, -1, v99
	s_nop 0
	v_lshlrev_b32_e32 v99, 2, v99
	v_xor_b32_e32 v99, 0x80, v99
	ds_bpermute_b32 v99, v99, v98
	s_waitcnt lgkmcnt(0)
; __device__ __forceinline__ v4u pk8(f32x4 a, f32x4 b) { v4u w; w.x = pk2(a[0], a[1]); w.y = pk2(a[2], a[3]); w.z = pk2(b[0], b[1]); w.w = pk2(b[2], b[3]); return w; }
; __device__ __forceinline__ float ssq8(const f32x4& a, const f32x4& b) { return ((a[0] * a[0] + a[1] * a[1]) + (a[2] * a[2] + a[3] * a[3])) + ((b[0] * b[0] + b[1] * b[1]) + (b[2] * b[2] + b[3] * b[3])); }
; template <int XF32> __device__ __forceinline__ void norm_mod_phase(const void* x, const float* modl, int ch_shift, int ch_scale, bf16* H, int gw, int NGW, int lane) {
;     ...
;         for (int rr = 0; rr < 8; ++rr) {
;             const unsigned char* xr = (const unsigned char*)x + (size_t)(r0 + rr) * rowb; f32x4 v[4][2]; float s = 0.f;
; #pragma unroll
;             for (int j = 0; j < 4; ++j) ld_row8<XF32>(xr, lane, j, v[j][0], v[j][1]);
; #pragma unroll
;             for (int j = 0; j < 4; ++j) s += ssq8(v[j][0], v[j][1]);
;             const float rstd = 1.f / sqrtf(wave_sum(s) * (1.f / DM) + EPS);
;             v4u* o = (v4u*)(H + (size_t)(r0 + rr) * DM);
; #pragma unroll
;             for (int j = 0; j < 4; ++j) o[lane + 64 * j] = pk8(v[j][0] * rstd * sc[j][0] + sh[j][0], v[j][1] * rstd * sc[j][1] + sh[j][1]);
	v_add_f32_e32 v98, v98, v99
	v_fmamk_f32 v98, v98, 0x3a000000, v224
	v_cmp_gt_f32_e32 vcc, s41, v98
	v_mul_f32_e32 v99, 0x4f800000, v98
	s_nop 0
	v_cndmask_b32_e32 v98, v98, v99, vcc
	v_sqrt_f32_e32 v99, v98
	s_nop 0
	v_add_u32_e32 v102, -1, v99
	v_fma_f32 v103, -v102, v99, v98
	v_cmp_ge_f32_e64 s[4:5], 0, v103
	v_add_u32_e32 v103, 1, v99
	s_nop 0
	v_cndmask_b32_e64 v102, v99, v102, s[4:5]
	v_fma_f32 v99, -v103, v99, v98
	v_cmp_lt_f32_e64 s[4:5], 0, v99
	s_nop 1
	v_cndmask_b32_e64 v99, v102, v103, s[4:5]
	v_mul_f32_e32 v102, 0x37800000, v99
	v_cndmask_b32_e32 v99, v99, v102, vcc
	v_cmp_class_f32_e32 vcc, v98, v225
	s_nop 1
	v_cndmask_b32_e32 v98, v99, v98, vcc
	v_div_scale_f32 v99, s[0:1], v98, v98, 1.0
	v_rcp_f32_e32 v102, v99
	s_add_i32 s0, s8, -2
	s_ashr_i32 s1, s0, 31
	v_fma_f32 v103, -v99, v102, 1.0
	v_fmac_f32_e32 v102, v103, v102
	v_div_scale_f32 v103, vcc, 1.0, v98, 1.0
	v_mul_f32_e32 v106, v103, v102
	v_fma_f32 v107, -v99, v106, v103
	v_fmac_f32_e32 v106, v107, v102
	v_fma_f32 v99, -v99, v106, v103
	v_div_fmas_f32 v99, v99, v102, v106
	v_div_fixup_f32 v98, v99, v98, 1.0
	v_mov_b32_e32 v102, v96
	v_mov_b32_e32 v103, v76
	v_mov_b32_e32 v76, v97
	v_pk_mul_f32 v[102:103], v[98:99], v[102:103] op_sel_hi:[0,1]
	v_pk_mul_f32 v[76:77], v[98:99], v[76:77] op_sel_hi:[0,1]
	v_pk_fma_f32 v[96:97], v[56:57], v[76:77], v[14:15]
	v_pk_fma_f32 v[76:77], v[58:59], v[102:103], v[12:13]
	v_mov_b32_e32 v102, v100
	v_mov_b32_e32 v103, v78
	v_mov_b32_e32 v78, v101
	v_pk_mul_f32 v[102:103], v[98:99], v[102:103] op_sel_hi:[0,1]
	v_pk_mul_f32 v[78:79], v[98:99], v[78:79] op_sel_hi:[0,1]
	v_pk_fma_f32 v[100:101], v[52:53], v[78:79], v[10:11]
	v_pk_fma_f32 v[78:79], v[54:55], v[102:103], v[8:9]
	v_cvt_pk_bf16_f32 v76, v76, v77
	v_cvt_pk_bf16_f32 v77, v96, v97
	v_cvt_pk_bf16_f32 v78, v78, v79
	v_cvt_pk_bf16_f32 v79, v100, v101
	v_lshl_add_u64 v[96:97], v[36:37], 0, s[64:65]
	global_store_dwordx4 v[96:97], v[76:79], off
	s_lshl_b64 s[64:65], s[0:1], 12
	s_nop 0
	v_mov_b32_e32 v77, v80
	v_mov_b32_e32 v80, v105
	v_mov_b32_e32 v76, v104
	v_pk_mul_f32 v[78:79], v[98:99], v[80:81] op_sel_hi:[0,1]
	v_mov_b32_e32 v80, v108
	v_mov_b32_e32 v81, v82
	v_mov_b32_e32 v82, v109
	v_pk_mul_f32 v[76:77], v[98:99], v[76:77] op_sel_hi:[0,1]
	v_pk_mul_f32 v[80:81], v[98:99], v[80:81] op_sel_hi:[0,1]
	v_pk_mul_f32 v[82:83], v[98:99], v[82:83] op_sel_hi:[0,1]
	v_pk_fma_f32 v[78:79], v[48:49], v[78:79], v[6:7]
	v_pk_fma_f32 v[76:77], v[50:51], v[76:77], v[4:5]
	v_pk_fma_f32 v[82:83], v[44:45], v[82:83], v[2:3]
	v_pk_fma_f32 v[80:81], v[46:47], v[80:81], v[0:1]
	v_cvt_pk_bf16_f32 v76, v76, v77
	v_cvt_pk_bf16_f32 v77, v78, v79
	v_cvt_pk_bf16_f32 v78, v80, v81
	v_cvt_pk_bf16_f32 v79, v82, v83
	global_store_dwordx4 v[96:97], v[76:79], off offset:1024
	v_pk_mul_f32 v[80:81], v[98:99], v[114:115] op_sel_hi:[0,1]
	v_pk_mul_f32 v[82:83], v[98:99], v[86:87] op_sel_hi:[0,1]
	v_pk_mul_f32 v[76:77], v[98:99], v[112:113] op_sel_hi:[0,1]
	v_pk_mul_f32 v[78:79], v[98:99], v[84:85] op_sel_hi:[0,1]
	v_pk_fma_f32 v[78:79], v[64:65], v[78:79], v[22:23]
	v_pk_fma_f32 v[76:77], v[66:67], v[76:77], v[20:21]
	v_pk_fma_f32 v[82:83], v[60:61], v[82:83], v[18:19]
	v_pk_fma_f32 v[80:81], v[62:63], v[80:81], v[16:17]
	v_cvt_pk_bf16_f32 v76, v76, v77
	v_cvt_pk_bf16_f32 v77, v78, v79
	v_cvt_pk_bf16_f32 v78, v80, v81
	v_cvt_pk_bf16_f32 v79, v82, v83
	global_store_dwordx4 v[96:97], v[76:79], off offset:2048
	v_pk_mul_f32 v[80:81], v[94:95], v[98:99] op_sel_hi:[1,0]
	v_pk_mul_f32 v[82:83], v[90:91], v[98:99] op_sel_hi:[1,0]
	v_pk_mul_f32 v[76:77], v[92:93], v[98:99] op_sel_hi:[1,0]
	v_pk_mul_f32 v[78:79], v[88:89], v[98:99] op_sel_hi:[1,0]
	v_pk_fma_f32 v[76:77], v[74:75], v[76:77], v[28:29]
	v_pk_fma_f32 v[78:79], v[72:73], v[78:79], v[30:31]
	v_pk_fma_f32 v[82:83], v[68:69], v[82:83], v[26:27]
	v_pk_fma_f32 v[80:81], v[70:71], v[80:81], v[24:25]
	v_cvt_pk_bf16_f32 v76, v76, v77
	v_cvt_pk_bf16_f32 v77, v78, v79
	v_cvt_pk_bf16_f32 v78, v80, v81
	v_cvt_pk_bf16_f32 v79, v82, v83
	global_store_dwordx4 v[96:97], v[76:79], off offset:3072
	s_waitcnt vmcnt(11)
	v_lshlrev_b32_e32 v97, 16, v195
	v_lshlrev_b32_e32 v96, 16, v194
	v_and_b32_e32 v77, 0xffff0000, v195
	v_and_b32_e32 v76, 0xffff0000, v194
	v_lshlrev_b32_e32 v101, 16, v197
	v_lshlrev_b32_e32 v100, 16, v196
	v_and_b32_e32 v79, 0xffff0000, v197
	v_and_b32_e32 v78, 0xffff0000, v196
	v_pk_mul_f32 v[98:99], v[76:77], v[76:77]
	v_pk_mul_f32 v[102:103], v[78:79], v[78:79]
	s_waitcnt vmcnt(8)
; __device__ __forceinline__ v4u pk8(f32x4 a, f32x4 b) { v4u w; w.x = pk2(a[0], a[1]); w.y = pk2(a[2], a[3]); w.z = pk2(b[0], b[1]); w.w = pk2(b[2], b[3]); return w; }
; __device__ __forceinline__ float ssq8(const f32x4& a, const f32x4& b) { return ((a[0] * a[0] + a[1] * a[1]) + (a[2] * a[2] + a[3] * a[3])) + ((b[0] * b[0] + b[1] * b[1]) + (b[2] * b[2] + b[3] * b[3])); }
; __device__ __forceinline__ float shfl_xor_f(float v, int o) {
;     int l; asm volatile("v_mbcnt_lo_u32_b32 %0, -1, 0\n\tv_mbcnt_hi_u32_b32 %0, -1, %0" : "=v"(l));
;     return __builtin_bit_cast(float, __builtin_amdgcn_ds_bpermute((l ^ o) << 2, __builtin_bit_cast(int, v)));
; }
; __device__ __forceinline__ float wave_sum(float v) {
; #pragma unroll
;     for (int o = 1; o < 64; o <<= 1) v += shfl_xor_f(v, o);
; template <int XF32> __device__ __forceinline__ void norm_mod_phase(const void* x, const float* modl, int ch_shift, int ch_scale, bf16* H, int gw, int NGW, int lane) {
;     ...
;         for (int rr = 0; rr < 8; ++rr) {
;             const unsigned char* xr = (const unsigned char*)x + (size_t)(r0 + rr) * rowb; f32x4 v[4][2]; float s = 0.f;
; #pragma unroll
;             for (int j = 0; j < 4; ++j) ld_row8<XF32>(xr, lane, j, v[j][0], v[j][1]);
; #pragma unroll
;             for (int j = 0; j < 4; ++j) s += ssq8(v[j][0], v[j][1]);
;             const float rstd = 1.f / sqrtf(wave_sum(s) * (1.f / DM) + EPS);
;             v4u* o = (v4u*)(H + (size_t)(r0 + rr) * DM);
; #pragma unroll
;             for (int j = 0; j < 4; ++j) o[lane + 64 * j] = pk8(v[j][0] * rstd * sc[j][0] + sh[j][0], v[j][1] * rstd * sc[j][1] + sh[j][1]);
	v_lshlrev_b32_e32 v92, 16, v206
	v_and_b32_e32 v93, 0xffff0000, v206
	v_pk_fma_f32 v[98:99], v[96:97], v[96:97], v[98:99]
	v_pk_fma_f32 v[102:103], v[100:101], v[100:101], v[102:103]
	v_lshlrev_b32_e32 v105, 16, v199
	v_lshlrev_b32_e32 v104, 16, v198
	v_and_b32_e32 v81, 0xffff0000, v199
	v_and_b32_e32 v80, 0xffff0000, v198
	v_lshlrev_b32_e32 v109, 16, v201
	v_lshlrev_b32_e32 v108, 16, v200
	v_and_b32_e32 v83, 0xffff0000, v201
	v_and_b32_e32 v82, 0xffff0000, v200
	v_pk_mul_f32 v[106:107], v[80:81], v[80:81]
	v_pk_mul_f32 v[110:111], v[82:83], v[82:83]
	v_mul_f32_e32 v116, v92, v92
	v_mul_f32_e32 v117, v93, v93
	v_pk_add_f32 v[98:99], v[98:99], v[98:99] op_sel:[0,1] op_sel_hi:[1,0]
	v_pk_add_f32 v[102:103], v[102:103], v[102:103] op_sel:[0,1] op_sel_hi:[1,0]
	v_lshlrev_b32_e32 v88, 16, v207
	v_and_b32_e32 v89, 0xffff0000, v207
	v_pk_fma_f32 v[106:107], v[104:105], v[104:105], v[106:107]
	v_pk_fma_f32 v[110:111], v[108:109], v[108:109], v[110:111]
	v_mov_b32_e32 v99, v116
	v_mov_b32_e32 v103, v117
	v_mul_f32_e32 v118, v88, v88
	v_mul_f32_e32 v119, v89, v89
	v_pk_add_f32 v[98:99], v[98:99], v[102:103]
	v_pk_add_f32 v[102:103], v[106:107], v[106:107] op_sel:[0,1] op_sel_hi:[1,0]
	v_pk_add_f32 v[106:107], v[110:111], v[110:111] op_sel:[0,1] op_sel_hi:[1,0]
	v_mov_b32_e32 v103, v118
	v_mov_b32_e32 v107, v119
	v_lshlrev_b32_e32 v112, 16, v202
	v_and_b32_e32 v113, 0xffff0000, v202
	v_lshlrev_b32_e32 v84, 16, v203
	v_and_b32_e32 v85, 0xffff0000, v203
	v_pk_add_f32 v[102:103], v[102:103], v[106:107]
	v_lshlrev_b32_e32 v94, 16, v208
	v_and_b32_e32 v95, 0xffff0000, v208
	v_pk_add_f32 v[98:99], v[98:99], v[102:103]
	v_mul_f32_e32 v102, v113, v113
	v_mul_f32_e32 v106, v85, v85
	v_mul_f32_e32 v120, v94, v94
	v_mul_f32_e32 v121, v95, v95
	v_pk_fma_f32 v[102:103], v[112:113], v[112:113], v[102:103] op_sel_hi:[1,1,0]
	v_pk_fma_f32 v[106:107], v[84:85], v[84:85], v[106:107] op_sel_hi:[1,1,0]
	v_lshlrev_b32_e32 v114, 16, v204
	v_and_b32_e32 v115, 0xffff0000, v204
	v_lshlrev_b32_e32 v86, 16, v205
	v_and_b32_e32 v87, 0xffff0000, v205
	v_mov_b32_e32 v103, v120
	v_mov_b32_e32 v107, v121
	v_lshlrev_b32_e32 v90, 16, v209
	v_and_b32_e32 v91, 0xffff0000, v209
	s_add_i32 s100, s8, 0
	s_ashr_i32 s101, s100, 31
	s_lshl_b64 s[100:101], s[100:101], 12
	v_lshl_add_u64 v[210:211], v[34:35], 0, s[100:101]
	s_nop 0
	global_load_dwordx4 v[194:197], v[210:211], off
	global_load_dwordx4 v[198:201], v[210:211], off offset:1024
	global_load_dwordx4 v[202:205], v[210:211], off offset:2048
	global_load_dwordx4 v[206:209], v[210:211], off offset:3072
	v_pk_add_f32 v[102:103], v[102:103], v[106:107]
	v_mul_f32_e32 v106, v115, v115
	v_mul_f32_e32 v110, v87, v87
	v_mul_f32_e32 v122, v90, v90
	v_mul_f32_e32 v123, v91, v91
	v_pk_fma_f32 v[106:107], v[114:115], v[114:115], v[106:107] op_sel_hi:[1,1,0]
	v_pk_fma_f32 v[110:111], v[86:87], v[86:87], v[110:111] op_sel_hi:[1,1,0]
	v_mov_b32_e32 v107, v122
	v_mov_b32_e32 v111, v123
	v_pk_add_f32 v[106:107], v[106:107], v[110:111]
	s_nop 0
	v_pk_add_f32 v[102:103], v[102:103], v[106:107]
	s_nop 0
	v_pk_add_f32 v[98:99], v[98:99], v[102:103]
	s_nop 0
	v_add_f32_e32 v98, v98, v99
	v_mbcnt_lo_u32_b32 v99, -1, 0
	v_mbcnt_hi_u32_b32 v99, -1, v99
	s_nop 0
	v_lshlrev_b32_e32 v99, 2, v99
	v_xor_b32_e32 v99, 4, v99
	ds_bpermute_b32 v99, v99, v98
	s_waitcnt lgkmcnt(0)
	v_add_f32_e32 v98, v98, v99
	v_mbcnt_lo_u32_b32 v99, -1, 0
	v_mbcnt_hi_u32_b32 v99, -1, v99
	s_nop 0
	v_lshlrev_b32_e32 v99, 2, v99
	v_xor_b32_e32 v99, 8, v99
	ds_bpermute_b32 v99, v99, v98
	s_waitcnt lgkmcnt(0)
	v_add_f32_e32 v98, v98, v99
	v_mbcnt_lo_u32_b32 v99, -1, 0
	v_mbcnt_hi_u32_b32 v99, -1, v99
	s_nop 0
	v_lshlrev_b32_e32 v99, 2, v99
	v_xor_b32_e32 v99, 16, v99
	ds_bpermute_b32 v99, v99, v98
	s_waitcnt lgkmcnt(0)
	v_add_f32_e32 v98, v98, v99
	v_mbcnt_lo_u32_b32 v99, -1, 0
	v_mbcnt_hi_u32_b32 v99, -1, v99
	s_nop 0
	v_lshlrev_b32_e32 v99, 2, v99
	v_xor_b32_e32 v99, 32, v99
	ds_bpermute_b32 v99, v99, v98
	s_waitcnt lgkmcnt(0)
	v_add_f32_e32 v98, v98, v99
	v_mbcnt_lo_u32_b32 v99, -1, 0
	v_mbcnt_hi_u32_b32 v99, -1, v99
	s_nop 0
	v_lshlrev_b32_e32 v99, 2, v99
	v_xor_b32_e32 v99, 64, v99
	ds_bpermute_b32 v99, v99, v98
	s_waitcnt lgkmcnt(0)
	v_add_f32_e32 v98, v98, v99
	v_mbcnt_lo_u32_b32 v99, -1, 0
	v_mbcnt_hi_u32_b32 v99, -1, v99
	s_nop 0
	v_lshlrev_b32_e32 v99, 2, v99
	v_xor_b32_e32 v99, 0x80, v99
	ds_bpermute_b32 v99, v99, v98
	s_waitcnt lgkmcnt(0)
; __device__ __forceinline__ v4u pk8(f32x4 a, f32x4 b) { v4u w; w.x = pk2(a[0], a[1]); w.y = pk2(a[2], a[3]); w.z = pk2(b[0], b[1]); w.w = pk2(b[2], b[3]); return w; }
; __device__ __forceinline__ float ssq8(const f32x4& a, const f32x4& b) { return ((a[0] * a[0] + a[1] * a[1]) + (a[2] * a[2] + a[3] * a[3])) + ((b[0] * b[0] + b[1] * b[1]) + (b[2] * b[2] + b[3] * b[3])); }
; template <int XF32> __device__ __forceinline__ void norm_mod_phase(const void* x, const float* modl, int ch_shift, int ch_scale, bf16* H, int gw, int NGW, int lane) {
;     ...
;         for (int rr = 0; rr < 8; ++rr) {
;             const unsigned char* xr = (const unsigned char*)x + (size_t)(r0 + rr) * rowb; f32x4 v[4][2]; float s = 0.f;
; #pragma unroll
;             for (int j = 0; j < 4; ++j) ld_row8<XF32>(xr, lane, j, v[j][0], v[j][1]);
; #pragma unroll
;             for (int j = 0; j < 4; ++j) s += ssq8(v[j][0], v[j][1]);
;             const float rstd = 1.f / sqrtf(wave_sum(s) * (1.f / DM) + EPS);
;             v4u* o = (v4u*)(H + (size_t)(r0 + rr) * DM);
; #pragma unroll
;             for (int j = 0; j < 4; ++j) o[lane + 64 * j] = pk8(v[j][0] * rstd * sc[j][0] + sh[j][0], v[j][1] * rstd * sc[j][1] + sh[j][1]);
	v_add_f32_e32 v98, v98, v99
	v_fmamk_f32 v98, v98, 0x3a000000, v224
	v_cmp_gt_f32_e32 vcc, s41, v98
	v_mul_f32_e32 v99, 0x4f800000, v98
	s_nop 0
	v_cndmask_b32_e32 v98, v98, v99, vcc
	v_sqrt_f32_e32 v99, v98
	s_nop 0
	v_add_u32_e32 v102, -1, v99
	v_fma_f32 v103, -v102, v99, v98
	v_cmp_ge_f32_e64 s[4:5], 0, v103
	v_add_u32_e32 v103, 1, v99
	s_nop 0
	v_cndmask_b32_e64 v102, v99, v102, s[4:5]
	v_fma_f32 v99, -v103, v99, v98
	v_cmp_lt_f32_e64 s[4:5], 0, v99
	s_nop 1
	v_cndmask_b32_e64 v99, v102, v103, s[4:5]
	v_mul_f32_e32 v102, 0x37800000, v99
	v_cndmask_b32_e32 v99, v99, v102, vcc
	v_cmp_class_f32_e32 vcc, v98, v225
	s_nop 1
	v_cndmask_b32_e32 v98, v99, v98, vcc
	v_div_scale_f32 v99, s[0:1], v98, v98, 1.0
	v_rcp_f32_e32 v102, v99
	s_add_i32 s0, s8, -1
	s_ashr_i32 s1, s0, 31
	v_fma_f32 v103, -v99, v102, 1.0
	v_fmac_f32_e32 v102, v103, v102
	v_div_scale_f32 v103, vcc, 1.0, v98, 1.0
	v_mul_f32_e32 v106, v103, v102
	v_fma_f32 v107, -v99, v106, v103
	v_fmac_f32_e32 v106, v107, v102
	v_fma_f32 v99, -v99, v106, v103
	v_div_fmas_f32 v99, v99, v102, v106
	v_div_fixup_f32 v98, v99, v98, 1.0
	v_mov_b32_e32 v102, v96
	v_mov_b32_e32 v103, v76
	v_mov_b32_e32 v76, v97
	v_pk_mul_f32 v[102:103], v[98:99], v[102:103] op_sel_hi:[0,1]
	v_pk_mul_f32 v[76:77], v[98:99], v[76:77] op_sel_hi:[0,1]
	v_pk_fma_f32 v[96:97], v[56:57], v[76:77], v[14:15]
	v_pk_fma_f32 v[76:77], v[58:59], v[102:103], v[12:13]
	v_mov_b32_e32 v102, v100
	v_mov_b32_e32 v103, v78
	v_mov_b32_e32 v78, v101
	v_pk_mul_f32 v[102:103], v[98:99], v[102:103] op_sel_hi:[0,1]
	v_pk_mul_f32 v[78:79], v[98:99], v[78:79] op_sel_hi:[0,1]
	v_pk_fma_f32 v[100:101], v[52:53], v[78:79], v[10:11]
	v_pk_fma_f32 v[78:79], v[54:55], v[102:103], v[8:9]
	v_cvt_pk_bf16_f32 v76, v76, v77
	v_cvt_pk_bf16_f32 v77, v96, v97
	v_cvt_pk_bf16_f32 v78, v78, v79
	v_cvt_pk_bf16_f32 v79, v100, v101
	v_lshl_add_u64 v[96:97], v[36:37], 0, s[64:65]
	global_store_dwordx4 v[96:97], v[76:79], off
	s_lshl_b64 s[64:65], s[0:1], 12
	s_nop 0
	v_mov_b32_e32 v77, v80
	v_mov_b32_e32 v80, v105
	v_mov_b32_e32 v76, v104
	v_pk_mul_f32 v[78:79], v[98:99], v[80:81] op_sel_hi:[0,1]
	v_mov_b32_e32 v80, v108
	v_mov_b32_e32 v81, v82
	v_mov_b32_e32 v82, v109
	v_pk_mul_f32 v[76:77], v[98:99], v[76:77] op_sel_hi:[0,1]
	v_pk_mul_f32 v[80:81], v[98:99], v[80:81] op_sel_hi:[0,1]
	v_pk_mul_f32 v[82:83], v[98:99], v[82:83] op_sel_hi:[0,1]
	v_pk_fma_f32 v[78:79], v[48:49], v[78:79], v[6:7]
	v_pk_fma_f32 v[76:77], v[50:51], v[76:77], v[4:5]
	v_pk_fma_f32 v[82:83], v[44:45], v[82:83], v[2:3]
	v_pk_fma_f32 v[80:81], v[46:47], v[80:81], v[0:1]
	v_cvt_pk_bf16_f32 v76, v76, v77
	v_cvt_pk_bf16_f32 v77, v78, v79
	v_cvt_pk_bf16_f32 v78, v80, v81
	v_cvt_pk_bf16_f32 v79, v82, v83
	global_store_dwordx4 v[96:97], v[76:79], off offset:1024
	v_pk_mul_f32 v[80:81], v[98:99], v[114:115] op_sel_hi:[0,1]
	v_pk_mul_f32 v[82:83], v[98:99], v[86:87] op_sel_hi:[0,1]
	v_pk_mul_f32 v[76:77], v[98:99], v[112:113] op_sel_hi:[0,1]
	v_pk_mul_f32 v[78:79], v[98:99], v[84:85] op_sel_hi:[0,1]
	v_pk_fma_f32 v[78:79], v[64:65], v[78:79], v[22:23]
	v_pk_fma_f32 v[76:77], v[66:67], v[76:77], v[20:21]
	v_pk_fma_f32 v[82:83], v[60:61], v[82:83], v[18:19]
	v_pk_fma_f32 v[80:81], v[62:63], v[80:81], v[16:17]
	v_cvt_pk_bf16_f32 v76, v76, v77
	v_cvt_pk_bf16_f32 v77, v78, v79
	v_cvt_pk_bf16_f32 v78, v80, v81
	v_cvt_pk_bf16_f32 v79, v82, v83
	global_store_dwordx4 v[96:97], v[76:79], off offset:2048
	v_pk_mul_f32 v[80:81], v[94:95], v[98:99] op_sel_hi:[1,0]
	v_pk_mul_f32 v[82:83], v[90:91], v[98:99] op_sel_hi:[1,0]
	v_pk_mul_f32 v[76:77], v[92:93], v[98:99] op_sel_hi:[1,0]
	v_pk_mul_f32 v[78:79], v[88:89], v[98:99] op_sel_hi:[1,0]
	v_pk_fma_f32 v[76:77], v[74:75], v[76:77], v[28:29]
	v_pk_fma_f32 v[78:79], v[72:73], v[78:79], v[30:31]
	v_pk_fma_f32 v[82:83], v[68:69], v[82:83], v[26:27]
	v_pk_fma_f32 v[80:81], v[70:71], v[80:81], v[24:25]
	v_cvt_pk_bf16_f32 v76, v76, v77
	v_cvt_pk_bf16_f32 v77, v78, v79
	v_cvt_pk_bf16_f32 v78, v80, v81
	v_cvt_pk_bf16_f32 v79, v82, v83
	global_store_dwordx4 v[96:97], v[76:79], off offset:3072
	s_waitcnt vmcnt(11)
	v_lshlrev_b32_e32 v97, 16, v179
	v_lshlrev_b32_e32 v96, 16, v178
	v_and_b32_e32 v77, 0xffff0000, v179
	v_and_b32_e32 v76, 0xffff0000, v178
	v_lshlrev_b32_e32 v101, 16, v181
	v_lshlrev_b32_e32 v100, 16, v180
	v_and_b32_e32 v79, 0xffff0000, v181
	v_and_b32_e32 v78, 0xffff0000, v180
	v_pk_mul_f32 v[98:99], v[76:77], v[76:77]
	v_pk_mul_f32 v[102:103], v[78:79], v[78:79]
	s_waitcnt vmcnt(8)
	v_lshlrev_b32_e32 v92, 16, v190
	v_and_b32_e32 v93, 0xffff0000, v190
	v_pk_fma_f32 v[98:99], v[96:97], v[96:97], v[98:99]
	v_pk_fma_f32 v[102:103], v[100:101], v[100:101], v[102:103]
	v_lshlrev_b32_e32 v105, 16, v183
	v_lshlrev_b32_e32 v104, 16, v182
	v_and_b32_e32 v81, 0xffff0000, v183
	v_and_b32_e32 v80, 0xffff0000, v182
	v_lshlrev_b32_e32 v109, 16, v185
	v_lshlrev_b32_e32 v108, 16, v184
	v_and_b32_e32 v83, 0xffff0000, v185
	v_and_b32_e32 v82, 0xffff0000, v184
	v_pk_mul_f32 v[106:107], v[80:81], v[80:81]
	v_pk_mul_f32 v[110:111], v[82:83], v[82:83]
	v_mul_f32_e32 v116, v92, v92
	v_mul_f32_e32 v117, v93, v93
	v_pk_add_f32 v[98:99], v[98:99], v[98:99] op_sel:[0,1] op_sel_hi:[1,0]
	v_pk_add_f32 v[102:103], v[102:103], v[102:103] op_sel:[0,1] op_sel_hi:[1,0]
	v_lshlrev_b32_e32 v88, 16, v191
	v_and_b32_e32 v89, 0xffff0000, v191
	v_pk_fma_f32 v[106:107], v[104:105], v[104:105], v[106:107]
	v_pk_fma_f32 v[110:111], v[108:109], v[108:109], v[110:111]
	v_mov_b32_e32 v99, v116
	v_mov_b32_e32 v103, v117
	v_mul_f32_e32 v118, v88, v88
	v_mul_f32_e32 v119, v89, v89
	v_pk_add_f32 v[98:99], v[98:99], v[102:103]
	v_pk_add_f32 v[102:103], v[106:107], v[106:107] op_sel:[0,1] op_sel_hi:[1,0]
	v_pk_add_f32 v[106:107], v[110:111], v[110:111] op_sel:[0,1] op_sel_hi:[1,0]
	v_mov_b32_e32 v103, v118
	v_mov_b32_e32 v107, v119
	v_lshlrev_b32_e32 v112, 16, v186
	v_and_b32_e32 v113, 0xffff0000, v186
	v_lshlrev_b32_e32 v84, 16, v187
	v_and_b32_e32 v85, 0xffff0000, v187
	v_pk_add_f32 v[102:103], v[102:103], v[106:107]
	v_lshlrev_b32_e32 v94, 16, v192
	v_and_b32_e32 v95, 0xffff0000, v192
	v_pk_add_f32 v[98:99], v[98:99], v[102:103]
	v_mul_f32_e32 v102, v113, v113
	v_mul_f32_e32 v106, v85, v85
	v_mul_f32_e32 v120, v94, v94
	v_mul_f32_e32 v121, v95, v95
	v_pk_fma_f32 v[102:103], v[112:113], v[112:113], v[102:103] op_sel_hi:[1,1,0]
	v_pk_fma_f32 v[106:107], v[84:85], v[84:85], v[106:107] op_sel_hi:[1,1,0]
	v_lshlrev_b32_e32 v114, 16, v188
	v_and_b32_e32 v115, 0xffff0000, v188
	v_lshlrev_b32_e32 v86, 16, v189
	v_and_b32_e32 v87, 0xffff0000, v189
	v_mov_b32_e32 v103, v120
	v_mov_b32_e32 v107, v121
	v_lshlrev_b32_e32 v90, 16, v193
	v_and_b32_e32 v91, 0xffff0000, v193
	v_pk_add_f32 v[102:103], v[102:103], v[106:107]
	v_mul_f32_e32 v106, v115, v115
	v_mul_f32_e32 v110, v87, v87
	v_mul_f32_e32 v122, v90, v90
	v_mul_f32_e32 v123, v91, v91
	v_pk_fma_f32 v[106:107], v[114:115], v[114:115], v[106:107] op_sel_hi:[1,1,0]
	v_pk_fma_f32 v[110:111], v[86:87], v[86:87], v[110:111] op_sel_hi:[1,1,0]
	v_mov_b32_e32 v107, v122
	v_mov_b32_e32 v111, v123
	v_pk_add_f32 v[106:107], v[106:107], v[110:111]
	s_nop 0
	v_pk_add_f32 v[102:103], v[102:103], v[106:107]
	s_nop 0
	v_pk_add_f32 v[98:99], v[98:99], v[102:103]
	s_nop 0
	v_add_f32_e32 v98, v98, v99
	v_mbcnt_lo_u32_b32 v99, -1, 0
	v_mbcnt_hi_u32_b32 v99, -1, v99
	s_nop 0
	v_lshlrev_b32_e32 v99, 2, v99
	v_xor_b32_e32 v99, 4, v99
	ds_bpermute_b32 v99, v99, v98
	s_waitcnt lgkmcnt(0)
	v_add_f32_e32 v98, v98, v99
	v_mbcnt_lo_u32_b32 v99, -1, 0
	v_mbcnt_hi_u32_b32 v99, -1, v99
	s_nop 0
	v_lshlrev_b32_e32 v99, 2, v99
	v_xor_b32_e32 v99, 8, v99
	ds_bpermute_b32 v99, v99, v98
	s_waitcnt lgkmcnt(0)
	v_add_f32_e32 v98, v98, v99
	v_mbcnt_lo_u32_b32 v99, -1, 0
	v_mbcnt_hi_u32_b32 v99, -1, v99
	s_nop 0
	v_lshlrev_b32_e32 v99, 2, v99
	v_xor_b32_e32 v99, 16, v99
	ds_bpermute_b32 v99, v99, v98
	s_waitcnt lgkmcnt(0)
	v_add_f32_e32 v98, v98, v99
	v_mbcnt_lo_u32_b32 v99, -1, 0
	v_mbcnt_hi_u32_b32 v99, -1, v99
	s_nop 0
	v_lshlrev_b32_e32 v99, 2, v99
	v_xor_b32_e32 v99, 32, v99
	ds_bpermute_b32 v99, v99, v98
	s_waitcnt lgkmcnt(0)
	v_add_f32_e32 v98, v98, v99
	v_mbcnt_lo_u32_b32 v99, -1, 0
	v_mbcnt_hi_u32_b32 v99, -1, v99
	s_nop 0
	v_lshlrev_b32_e32 v99, 2, v99
	v_xor_b32_e32 v99, 64, v99
	ds_bpermute_b32 v99, v99, v98
	s_waitcnt lgkmcnt(0)
	v_add_f32_e32 v98, v98, v99
	v_mbcnt_lo_u32_b32 v99, -1, 0
	v_mbcnt_hi_u32_b32 v99, -1, v99
	s_nop 0
	v_lshlrev_b32_e32 v99, 2, v99
	v_xor_b32_e32 v99, 0x80, v99
	ds_bpermute_b32 v99, v99, v98
	s_waitcnt lgkmcnt(0)
	v_add_f32_e32 v98, v98, v99
	v_fmamk_f32 v98, v98, 0x3a000000, v224
	v_cmp_gt_f32_e32 vcc, s41, v98
	v_mul_f32_e32 v99, 0x4f800000, v98
	s_nop 0
	v_cndmask_b32_e32 v98, v98, v99, vcc
	v_sqrt_f32_e32 v99, v98
	s_nop 0
	v_add_u32_e32 v102, -1, v99
	v_fma_f32 v103, -v102, v99, v98
	v_cmp_ge_f32_e64 s[4:5], 0, v103
	v_add_u32_e32 v103, 1, v99
	s_nop 0
	v_cndmask_b32_e64 v102, v99, v102, s[4:5]
	v_fma_f32 v99, -v103, v99, v98
	v_cmp_lt_f32_e64 s[4:5], 0, v99
	s_nop 1
	v_cndmask_b32_e64 v99, v102, v103, s[4:5]
	v_mul_f32_e32 v102, 0x37800000, v99
	v_cndmask_b32_e32 v99, v99, v102, vcc
	v_cmp_class_f32_e32 vcc, v98, v225
	s_nop 1
	v_cndmask_b32_e32 v98, v99, v98, vcc
	v_div_scale_f32 v99, s[0:1], v98, v98, 1.0
	v_rcp_f32_e32 v102, v99
	s_nop 0
	v_fma_f32 v103, -v99, v102, 1.0
	v_fmac_f32_e32 v102, v103, v102
	v_div_scale_f32 v103, vcc, 1.0, v98, 1.0
	v_mul_f32_e32 v106, v103, v102
	v_fma_f32 v107, -v99, v106, v103
	v_fmac_f32_e32 v106, v107, v102
	v_fma_f32 v99, -v99, v106, v103
	v_div_fmas_f32 v99, v99, v102, v106
	v_div_fixup_f32 v98, v99, v98, 1.0
	v_mov_b32_e32 v102, v96
	v_mov_b32_e32 v103, v76
	v_mov_b32_e32 v76, v97
	v_pk_mul_f32 v[102:103], v[98:99], v[102:103] op_sel_hi:[0,1]
	v_pk_mul_f32 v[76:77], v[98:99], v[76:77] op_sel_hi:[0,1]
	v_pk_fma_f32 v[96:97], v[56:57], v[76:77], v[14:15]
	v_pk_fma_f32 v[76:77], v[58:59], v[102:103], v[12:13]
	v_mov_b32_e32 v102, v100
	v_mov_b32_e32 v103, v78
	v_mov_b32_e32 v78, v101
	v_pk_mul_f32 v[102:103], v[98:99], v[102:103] op_sel_hi:[0,1]
	v_pk_mul_f32 v[78:79], v[98:99], v[78:79] op_sel_hi:[0,1]
	v_pk_fma_f32 v[100:101], v[52:53], v[78:79], v[10:11]
	v_pk_fma_f32 v[78:79], v[54:55], v[102:103], v[8:9]
	v_cvt_pk_bf16_f32 v76, v76, v77
	v_cvt_pk_bf16_f32 v77, v96, v97
	v_cvt_pk_bf16_f32 v78, v78, v79
	v_cvt_pk_bf16_f32 v79, v100, v101
	v_lshl_add_u64 v[96:97], v[36:37], 0, s[64:65]
	global_store_dwordx4 v[96:97], v[76:79], off
	s_lshl_b64 s[64:65], s[8:9], 12
	s_add_i32 s8, s8, s2
	v_mov_b32_e32 v77, v80
	v_mov_b32_e32 v80, v105
	v_mov_b32_e32 v76, v104
	v_pk_mul_f32 v[78:79], v[98:99], v[80:81] op_sel_hi:[0,1]
	v_mov_b32_e32 v80, v108
	v_mov_b32_e32 v81, v82
	v_mov_b32_e32 v82, v109
	v_pk_mul_f32 v[76:77], v[98:99], v[76:77] op_sel_hi:[0,1]
	v_pk_mul_f32 v[80:81], v[98:99], v[80:81] op_sel_hi:[0,1]
	v_pk_mul_f32 v[82:83], v[98:99], v[82:83] op_sel_hi:[0,1]
	v_pk_fma_f32 v[78:79], v[48:49], v[78:79], v[6:7]
	v_pk_fma_f32 v[76:77], v[50:51], v[76:77], v[4:5]
	v_pk_fma_f32 v[82:83], v[44:45], v[82:83], v[2:3]
	v_pk_fma_f32 v[80:81], v[46:47], v[80:81], v[0:1]
	v_cvt_pk_bf16_f32 v76, v76, v77
	v_cvt_pk_bf16_f32 v77, v78, v79
	v_cvt_pk_bf16_f32 v78, v80, v81
	v_cvt_pk_bf16_f32 v79, v82, v83
	global_store_dwordx4 v[96:97], v[76:79], off offset:1024
	v_pk_mul_f32 v[80:81], v[98:99], v[114:115] op_sel_hi:[0,1]
	v_pk_mul_f32 v[82:83], v[98:99], v[86:87] op_sel_hi:[0,1]
	v_pk_mul_f32 v[76:77], v[98:99], v[112:113] op_sel_hi:[0,1]
	v_pk_mul_f32 v[78:79], v[98:99], v[84:85] op_sel_hi:[0,1]
	v_pk_fma_f32 v[78:79], v[64:65], v[78:79], v[22:23]
	v_pk_fma_f32 v[76:77], v[66:67], v[76:77], v[20:21]
	v_pk_fma_f32 v[82:83], v[60:61], v[82:83], v[18:19]
	v_pk_fma_f32 v[80:81], v[62:63], v[80:81], v[16:17]
	v_cvt_pk_bf16_f32 v76, v76, v77
	v_cvt_pk_bf16_f32 v77, v78, v79
	v_cvt_pk_bf16_f32 v78, v80, v81
	v_cvt_pk_bf16_f32 v79, v82, v83
	global_store_dwordx4 v[96:97], v[76:79], off offset:2048
	v_pk_mul_f32 v[80:81], v[94:95], v[98:99] op_sel_hi:[1,0]
	v_pk_mul_f32 v[82:83], v[90:91], v[98:99] op_sel_hi:[1,0]
	v_pk_mul_f32 v[76:77], v[92:93], v[98:99] op_sel_hi:[1,0]
	v_pk_mul_f32 v[78:79], v[88:89], v[98:99] op_sel_hi:[1,0]
	v_pk_fma_f32 v[76:77], v[74:75], v[76:77], v[28:29]
	v_pk_fma_f32 v[78:79], v[72:73], v[78:79], v[30:31]
	v_pk_fma_f32 v[82:83], v[68:69], v[82:83], v[26:27]
	v_pk_fma_f32 v[80:81], v[70:71], v[80:81], v[24:25]
	v_cvt_pk_bf16_f32 v76, v76, v77
	v_cvt_pk_bf16_f32 v77, v78, v79
	v_cvt_pk_bf16_f32 v78, v80, v81
	v_cvt_pk_bf16_f32 v79, v82, v83
	global_store_dwordx4 v[96:97], v[76:79], off offset:3072
	s_cmpk_lt_i32 s3, 0x800
	s_waitcnt vmcnt(7)
	v_lshlrev_b32_e32 v97, 16, v195
	v_lshlrev_b32_e32 v96, 16, v194
	v_and_b32_e32 v77, 0xffff0000, v195
	v_and_b32_e32 v76, 0xffff0000, v194
	v_lshlrev_b32_e32 v101, 16, v197
	v_lshlrev_b32_e32 v100, 16, v196
	v_and_b32_e32 v79, 0xffff0000, v197
	v_and_b32_e32 v78, 0xffff0000, v196
	v_pk_mul_f32 v[98:99], v[76:77], v[76:77]
	v_pk_mul_f32 v[102:103], v[78:79], v[78:79]
	s_waitcnt vmcnt(4)
	v_lshlrev_b32_e32 v92, 16, v206
	v_and_b32_e32 v93, 0xffff0000, v206
	v_pk_fma_f32 v[98:99], v[96:97], v[96:97], v[98:99]
	v_pk_fma_f32 v[102:103], v[100:101], v[100:101], v[102:103]
	v_lshlrev_b32_e32 v105, 16, v199
	v_lshlrev_b32_e32 v104, 16, v198
	v_and_b32_e32 v81, 0xffff0000, v199
	v_and_b32_e32 v80, 0xffff0000, v198
	v_lshlrev_b32_e32 v109, 16, v201
	v_lshlrev_b32_e32 v108, 16, v200
	v_and_b32_e32 v83, 0xffff0000, v201
	v_and_b32_e32 v82, 0xffff0000, v200
	v_pk_mul_f32 v[106:107], v[80:81], v[80:81]
	v_pk_mul_f32 v[110:111], v[82:83], v[82:83]
	v_mul_f32_e32 v116, v92, v92
	v_mul_f32_e32 v117, v93, v93
	v_pk_add_f32 v[98:99], v[98:99], v[98:99] op_sel:[0,1] op_sel_hi:[1,0]
	v_pk_add_f32 v[102:103], v[102:103], v[102:103] op_sel:[0,1] op_sel_hi:[1,0]
	v_lshlrev_b32_e32 v88, 16, v207
	v_and_b32_e32 v89, 0xffff0000, v207
	v_pk_fma_f32 v[106:107], v[104:105], v[104:105], v[106:107]
	v_pk_fma_f32 v[110:111], v[108:109], v[108:109], v[110:111]
	v_mov_b32_e32 v99, v116
	v_mov_b32_e32 v103, v117
	v_mul_f32_e32 v118, v88, v88
	v_mul_f32_e32 v119, v89, v89
	v_pk_add_f32 v[98:99], v[98:99], v[102:103]
	v_pk_add_f32 v[102:103], v[106:107], v[106:107] op_sel:[0,1] op_sel_hi:[1,0]
	v_pk_add_f32 v[106:107], v[110:111], v[110:111] op_sel:[0,1] op_sel_hi:[1,0]
	v_mov_b32_e32 v103, v118
	v_mov_b32_e32 v107, v119
	v_lshlrev_b32_e32 v112, 16, v202
	v_and_b32_e32 v113, 0xffff0000, v202
	v_lshlrev_b32_e32 v84, 16, v203
	v_and_b32_e32 v85, 0xffff0000, v203
	v_pk_add_f32 v[102:103], v[102:103], v[106:107]
	v_lshlrev_b32_e32 v94, 16, v208
	v_and_b32_e32 v95, 0xffff0000, v208
	v_pk_add_f32 v[98:99], v[98:99], v[102:103]
	v_mul_f32_e32 v102, v113, v113
	v_mul_f32_e32 v106, v85, v85
	v_mul_f32_e32 v120, v94, v94
	v_mul_f32_e32 v121, v95, v95
	v_pk_fma_f32 v[102:103], v[112:113], v[112:113], v[102:103] op_sel_hi:[1,1,0]
	v_pk_fma_f32 v[106:107], v[84:85], v[84:85], v[106:107] op_sel_hi:[1,1,0]
	v_lshlrev_b32_e32 v114, 16, v204
	v_and_b32_e32 v115, 0xffff0000, v204
	v_lshlrev_b32_e32 v86, 16, v205
	v_and_b32_e32 v87, 0xffff0000, v205
	v_mov_b32_e32 v103, v120
	v_mov_b32_e32 v107, v121
	v_lshlrev_b32_e32 v90, 16, v209
	v_and_b32_e32 v91, 0xffff0000, v209
	v_pk_add_f32 v[102:103], v[102:103], v[106:107]
	v_mul_f32_e32 v106, v115, v115
	v_mul_f32_e32 v110, v87, v87
	v_mul_f32_e32 v122, v90, v90
	v_mul_f32_e32 v123, v91, v91
	v_pk_fma_f32 v[106:107], v[114:115], v[114:115], v[106:107] op_sel_hi:[1,1,0]
	v_pk_fma_f32 v[110:111], v[86:87], v[86:87], v[110:111] op_sel_hi:[1,1,0]
	v_mov_b32_e32 v107, v122
	v_mov_b32_e32 v111, v123
	v_pk_add_f32 v[106:107], v[106:107], v[110:111]
	s_nop 0
	v_pk_add_f32 v[102:103], v[102:103], v[106:107]
	s_nop 0
	v_pk_add_f32 v[98:99], v[98:99], v[102:103]
	s_nop 0
	v_add_f32_e32 v98, v98, v99
	v_mbcnt_lo_u32_b32 v99, -1, 0
	v_mbcnt_hi_u32_b32 v99, -1, v99
	s_nop 0
	v_lshlrev_b32_e32 v99, 2, v99
	v_xor_b32_e32 v99, 4, v99
	ds_bpermute_b32 v99, v99, v98
	s_waitcnt lgkmcnt(0)
	v_add_f32_e32 v98, v98, v99
	v_mbcnt_lo_u32_b32 v99, -1, 0
	v_mbcnt_hi_u32_b32 v99, -1, v99
	s_nop 0
	v_lshlrev_b32_e32 v99, 2, v99
	v_xor_b32_e32 v99, 8, v99
	ds_bpermute_b32 v99, v99, v98
	s_waitcnt lgkmcnt(0)
	v_add_f32_e32 v98, v98, v99
	v_mbcnt_lo_u32_b32 v99, -1, 0
	v_mbcnt_hi_u32_b32 v99, -1, v99
	s_nop 0
	v_lshlrev_b32_e32 v99, 2, v99
	v_xor_b32_e32 v99, 16, v99
	ds_bpermute_b32 v99, v99, v98
	s_waitcnt lgkmcnt(0)
	v_add_f32_e32 v98, v98, v99
	v_mbcnt_lo_u32_b32 v99, -1, 0
	v_mbcnt_hi_u32_b32 v99, -1, v99
	s_nop 0
	v_lshlrev_b32_e32 v99, 2, v99
	v_xor_b32_e32 v99, 32, v99
	ds_bpermute_b32 v99, v99, v98
	s_waitcnt lgkmcnt(0)
	v_add_f32_e32 v98, v98, v99
	v_mbcnt_lo_u32_b32 v99, -1, 0
	v_mbcnt_hi_u32_b32 v99, -1, v99
	s_nop 0
	v_lshlrev_b32_e32 v99, 2, v99
	v_xor_b32_e32 v99, 64, v99
	ds_bpermute_b32 v99, v99, v98
	s_waitcnt lgkmcnt(0)
	v_add_f32_e32 v98, v98, v99
	v_mbcnt_lo_u32_b32 v99, -1, 0
	v_mbcnt_hi_u32_b32 v99, -1, v99
	s_nop 0
	v_lshlrev_b32_e32 v99, 2, v99
	v_xor_b32_e32 v99, 0x80, v99
	ds_bpermute_b32 v99, v99, v98
	s_waitcnt lgkmcnt(0)
	v_add_f32_e32 v98, v98, v99
	v_fmamk_f32 v98, v98, 0x3a000000, v224
	v_cmp_gt_f32_e32 vcc, s41, v98
	v_mul_f32_e32 v99, 0x4f800000, v98
	s_nop 0
	v_cndmask_b32_e32 v98, v98, v99, vcc
	v_sqrt_f32_e32 v99, v98
	s_nop 0
	v_add_u32_e32 v102, -1, v99
	v_fma_f32 v103, -v102, v99, v98
	v_cmp_ge_f32_e64 s[4:5], 0, v103
	v_add_u32_e32 v103, 1, v99
	s_nop 0
	v_cndmask_b32_e64 v102, v99, v102, s[4:5]
	v_fma_f32 v99, -v103, v99, v98
	v_cmp_lt_f32_e64 s[4:5], 0, v99
	s_nop 1
	v_cndmask_b32_e64 v99, v102, v103, s[4:5]
	v_mul_f32_e32 v102, 0x37800000, v99
	v_cndmask_b32_e32 v99, v99, v102, vcc
	v_cmp_class_f32_e32 vcc, v98, v225
	s_nop 1
	v_cndmask_b32_e32 v98, v99, v98, vcc
	v_div_scale_f32 v99, s[0:1], v98, v98, 1.0
	v_rcp_f32_e32 v102, v99
	s_nop 0
	v_fma_f32 v103, -v99, v102, 1.0
	v_fmac_f32_e32 v102, v103, v102
	v_div_scale_f32 v103, vcc, 1.0, v98, 1.0
	v_mul_f32_e32 v106, v103, v102
	v_fma_f32 v107, -v99, v106, v103
	v_fmac_f32_e32 v106, v107, v102
	v_fma_f32 v99, -v99, v106, v103
	v_div_fmas_f32 v99, v99, v102, v106
	v_div_fixup_f32 v98, v99, v98, 1.0
	v_mov_b32_e32 v103, v76
	v_mov_b32_e32 v76, v97
	v_mov_b32_e32 v102, v96
	v_pk_mul_f32 v[76:77], v[98:99], v[76:77] op_sel_hi:[0,1]
	v_pk_mul_f32 v[102:103], v[98:99], v[102:103] op_sel_hi:[0,1]
	v_pk_fma_f32 v[14:15], v[56:57], v[76:77], v[14:15]
	v_mov_b32_e32 v56, v100
	v_mov_b32_e32 v57, v78
	v_mov_b32_e32 v78, v101
	v_pk_fma_f32 v[12:13], v[58:59], v[102:103], v[12:13]
	v_pk_mul_f32 v[56:57], v[98:99], v[56:57] op_sel_hi:[0,1]
	v_pk_mul_f32 v[58:59], v[98:99], v[78:79] op_sel_hi:[0,1]
	v_pk_fma_f32 v[52:53], v[52:53], v[58:59], v[10:11]
	v_pk_fma_f32 v[10:11], v[54:55], v[56:57], v[8:9]
	v_cvt_pk_bf16_f32 v8, v12, v13
	v_cvt_pk_bf16_f32 v9, v14, v15
	v_cvt_pk_bf16_f32 v10, v10, v11
	v_cvt_pk_bf16_f32 v11, v52, v53
	v_lshl_add_u64 v[12:13], v[36:37], 0, s[64:65]
	global_store_dwordx4 v[12:13], v[8:11], off
	s_nop 1
	v_mov_b32_e32 v8, v104
	v_mov_b32_e32 v9, v80
	v_pk_mul_f32 v[8:9], v[98:99], v[8:9] op_sel_hi:[0,1]
	v_mov_b32_e32 v80, v105
	v_pk_mul_f32 v[10:11], v[98:99], v[80:81] op_sel_hi:[0,1]
	v_pk_fma_f32 v[4:5], v[50:51], v[8:9], v[4:5]
	v_mov_b32_e32 v8, v108
	v_mov_b32_e32 v9, v82
	v_mov_b32_e32 v82, v109
	v_pk_fma_f32 v[6:7], v[48:49], v[10:11], v[6:7]
	v_pk_mul_f32 v[8:9], v[98:99], v[8:9] op_sel_hi:[0,1]
	v_pk_mul_f32 v[10:11], v[98:99], v[82:83] op_sel_hi:[0,1]
	v_pk_fma_f32 v[10:11], v[44:45], v[10:11], v[2:3]
	v_pk_fma_f32 v[2:3], v[46:47], v[8:9], v[0:1]
	v_cvt_pk_bf16_f32 v0, v4, v5
	v_cvt_pk_bf16_f32 v1, v6, v7
	v_cvt_pk_bf16_f32 v2, v2, v3
	v_cvt_pk_bf16_f32 v3, v10, v11
	global_store_dwordx4 v[12:13], v[0:3], off offset:1024
	v_pk_mul_f32 v[4:5], v[98:99], v[114:115] op_sel_hi:[0,1]
	v_pk_mul_f32 v[6:7], v[98:99], v[86:87] op_sel_hi:[0,1]
	v_pk_mul_f32 v[0:1], v[98:99], v[112:113] op_sel_hi:[0,1]
	v_pk_mul_f32 v[2:3], v[98:99], v[84:85] op_sel_hi:[0,1]
	v_pk_fma_f32 v[2:3], v[64:65], v[2:3], v[22:23]
	v_pk_fma_f32 v[0:1], v[66:67], v[0:1], v[20:21]
	v_pk_fma_f32 v[6:7], v[60:61], v[6:7], v[18:19]
	v_pk_fma_f32 v[4:5], v[62:63], v[4:5], v[16:17]
	v_cvt_pk_bf16_f32 v0, v0, v1
	v_cvt_pk_bf16_f32 v1, v2, v3
	v_cvt_pk_bf16_f32 v2, v4, v5
	v_cvt_pk_bf16_f32 v3, v6, v7
	global_store_dwordx4 v[12:13], v[0:3], off offset:2048
	v_pk_mul_f32 v[4:5], v[94:95], v[98:99] op_sel_hi:[1,0]
	v_pk_mul_f32 v[6:7], v[90:91], v[98:99] op_sel_hi:[1,0]
	v_pk_mul_f32 v[0:1], v[92:93], v[98:99] op_sel_hi:[1,0]
	v_pk_mul_f32 v[2:3], v[88:89], v[98:99] op_sel_hi:[1,0]
	v_pk_fma_f32 v[0:1], v[74:75], v[0:1], v[28:29]
	v_pk_fma_f32 v[2:3], v[72:73], v[2:3], v[30:31]
	v_pk_fma_f32 v[6:7], v[68:69], v[6:7], v[26:27]
	v_pk_fma_f32 v[4:5], v[70:71], v[4:5], v[24:25]
	v_cvt_pk_bf16_f32 v0, v0, v1
	v_cvt_pk_bf16_f32 v1, v2, v3
	v_cvt_pk_bf16_f32 v2, v4, v5
	v_cvt_pk_bf16_f32 v3, v6, v7
	global_store_dwordx4 v[12:13], v[0:3], off offset:3072
	s_cbranch_scc1 .LBB0_161

.LBB0_919:
	s_ashr_i32 s0, s56, 9
	s_mul_hi_i32 s1, s0, 0x12000
	s_mul_i32 s0, s0, 0x12000
	s_add_u32 s0, s24, s0
	s_addc_u32 s1, s26, s1
	s_add_u32 s60, s0, 0xc000
	s_addc_u32 s61, s1, 0
	s_add_u32 s0, s0, 0xe000
	s_addc_u32 s1, s1, 0
	v_lshl_add_u64 v[4:5], s[60:61], 0, v[36:37]
	v_lshl_add_u64 v[12:13], s[0:1], 0, v[36:37]
	global_load_dwordx4 v[0:3], v[4:5], off offset:16
	s_nop 0
	global_load_dwordx4 v[4:7], v[4:5], off
	s_nop 0
	global_load_dwordx4 v[178:181], v[12:13], off offset:16
	s_nop 0
	global_load_dwordx4 v[182:185], v[12:13], off
	v_lshl_add_u64 v[20:21], s[0:1], 0, v[38:39]
	v_lshl_add_u64 v[28:29], s[0:1], 0, v[40:41]
	v_lshl_add_u64 v[68:69], s[0:1], 0, v[42:43]
	s_add_i32 s0, s4, -7
	s_ashr_i32 s1, s0, 31
	s_ashr_i32 s5, s4, 31
	s_add_i32 s56, s56, s58
	v_lshl_add_u64 v[12:13], s[60:61], 0, v[38:39]
	global_load_dwordx4 v[8:11], v[12:13], off offset:16
	s_nop 0
	global_load_dwordx4 v[12:15], v[12:13], off
	s_nop 0
	global_load_dwordx4 v[186:189], v[20:21], off offset:16
	s_nop 0
	global_load_dwordx4 v[190:193], v[20:21], off
	v_lshl_add_u64 v[20:21], s[60:61], 0, v[40:41]
	global_load_dwordx4 v[16:19], v[20:21], off offset:16
	s_nop 0
	global_load_dwordx4 v[20:23], v[20:21], off
	s_nop 0
	global_load_dwordx4 v[194:197], v[28:29], off offset:16
	s_nop 0
	global_load_dwordx4 v[198:201], v[28:29], off
	v_lshl_add_u64 v[28:29], s[60:61], 0, v[42:43]
	global_load_dwordx4 v[24:27], v[28:29], off offset:16
	s_nop 0
	global_load_dwordx4 v[28:31], v[28:29], off
	s_nop 0
	global_load_dwordx4 v[202:205], v[68:69], off offset:16
	s_nop 0
	global_load_dwordx4 v[206:209], v[68:69], off
	s_lshl_b64 s[60:61], s[0:1], 12
	v_lshl_add_u64 v[88:89], v[32:33], 0, s[60:61]
	global_load_dwordx4 v[76:79], v[88:89], off
	global_load_dwordx4 v[80:83], v[88:89], off offset:1024
	global_load_dwordx4 v[84:87], v[88:89], off offset:2048
	s_nop 0
	global_load_dwordx4 v[88:91], v[88:89], off offset:3072
	s_waitcnt vmcnt(4)
	v_pk_add_f32 v[44:45], v[180:181], 1.0 op_sel_hi:[1,0]
	v_pk_add_f32 v[50:51], v[182:183], 1.0 op_sel_hi:[1,0]
	v_pk_add_f32 v[48:49], v[184:185], 1.0 op_sel_hi:[1,0]
	v_pk_add_f32 v[46:47], v[178:179], 1.0 op_sel_hi:[1,0]
	v_pk_add_f32 v[52:53], v[188:189], 1.0 op_sel_hi:[1,0]
	v_pk_add_f32 v[58:59], v[190:191], 1.0 op_sel_hi:[1,0]
	v_pk_add_f32 v[56:57], v[192:193], 1.0 op_sel_hi:[1,0]
	v_pk_add_f32 v[54:55], v[186:187], 1.0 op_sel_hi:[1,0]
	v_pk_add_f32 v[60:61], v[196:197], 1.0 op_sel_hi:[1,0]
	v_pk_add_f32 v[66:67], v[198:199], 1.0 op_sel_hi:[1,0]
	v_pk_add_f32 v[64:65], v[200:201], 1.0 op_sel_hi:[1,0]
	v_pk_add_f32 v[62:63], v[194:195], 1.0 op_sel_hi:[1,0]
	v_pk_add_f32 v[72:73], v[208:209], 1.0 op_sel_hi:[1,0]
	v_pk_add_f32 v[74:75], v[206:207], 1.0 op_sel_hi:[1,0]
	v_pk_add_f32 v[68:69], v[204:205], 1.0 op_sel_hi:[1,0]
	v_pk_add_f32 v[70:71], v[202:203], 1.0 op_sel_hi:[1,0]
	s_add_i32 s100, s4, -6
	s_ashr_i32 s101, s100, 31
	s_lshl_b64 s[100:101], s[100:101], 12
	v_lshl_add_u64 v[210:211], v[32:33], 0, s[100:101]
	s_nop 0
	global_load_dwordx4 v[194:197], v[210:211], off
	global_load_dwordx4 v[198:201], v[210:211], off offset:1024
	global_load_dwordx4 v[202:205], v[210:211], off offset:2048
	global_load_dwordx4 v[206:209], v[210:211], off offset:3072
	s_waitcnt vmcnt(7)
	v_lshlrev_b32_e32 v97, 16, v77
	v_lshlrev_b32_e32 v96, 16, v76
	v_and_b32_e32 v77, 0xffff0000, v77
	v_and_b32_e32 v76, 0xffff0000, v76
	v_lshlrev_b32_e32 v101, 16, v79
	v_lshlrev_b32_e32 v100, 16, v78
	v_and_b32_e32 v79, 0xffff0000, v79
	v_and_b32_e32 v78, 0xffff0000, v78
	v_pk_mul_f32 v[98:99], v[76:77], v[76:77]
	v_pk_mul_f32 v[102:103], v[78:79], v[78:79]
	s_waitcnt vmcnt(4)
	v_lshlrev_b32_e32 v92, 16, v88
	v_and_b32_e32 v93, 0xffff0000, v88
	v_pk_fma_f32 v[98:99], v[96:97], v[96:97], v[98:99]
	v_pk_fma_f32 v[102:103], v[100:101], v[100:101], v[102:103]
	v_lshlrev_b32_e32 v105, 16, v81
	v_lshlrev_b32_e32 v104, 16, v80
	v_and_b32_e32 v81, 0xffff0000, v81
	v_and_b32_e32 v80, 0xffff0000, v80
	v_lshlrev_b32_e32 v109, 16, v83
	v_lshlrev_b32_e32 v108, 16, v82
	v_and_b32_e32 v83, 0xffff0000, v83
	v_and_b32_e32 v82, 0xffff0000, v82
	v_pk_mul_f32 v[106:107], v[80:81], v[80:81]
	v_pk_mul_f32 v[110:111], v[82:83], v[82:83]
	v_mul_f32_e32 v116, v92, v92
	v_mul_f32_e32 v117, v93, v93
	v_pk_add_f32 v[98:99], v[98:99], v[98:99] op_sel:[0,1] op_sel_hi:[1,0]
	v_pk_add_f32 v[102:103], v[102:103], v[102:103] op_sel:[0,1] op_sel_hi:[1,0]
	v_lshlrev_b32_e32 v88, 16, v89
	v_and_b32_e32 v89, 0xffff0000, v89
	v_pk_fma_f32 v[106:107], v[104:105], v[104:105], v[106:107]
	v_pk_fma_f32 v[110:111], v[108:109], v[108:109], v[110:111]
	v_mov_b32_e32 v99, v116
	v_mov_b32_e32 v103, v117
	v_mul_f32_e32 v118, v88, v88
	v_mul_f32_e32 v119, v89, v89
	v_pk_add_f32 v[98:99], v[98:99], v[102:103]
	v_pk_add_f32 v[102:103], v[106:107], v[106:107] op_sel:[0,1] op_sel_hi:[1,0]
	v_pk_add_f32 v[106:107], v[110:111], v[110:111] op_sel:[0,1] op_sel_hi:[1,0]
	v_mov_b32_e32 v103, v118
	v_mov_b32_e32 v107, v119
	v_lshlrev_b32_e32 v112, 16, v84
	v_and_b32_e32 v113, 0xffff0000, v84
	v_lshlrev_b32_e32 v84, 16, v85
	v_and_b32_e32 v85, 0xffff0000, v85
	v_pk_add_f32 v[102:103], v[102:103], v[106:107]
	v_lshlrev_b32_e32 v94, 16, v90
	v_and_b32_e32 v95, 0xffff0000, v90
	v_pk_add_f32 v[98:99], v[98:99], v[102:103]
	v_mul_f32_e32 v102, v113, v113
	v_mul_f32_e32 v106, v85, v85
	v_mul_f32_e32 v120, v94, v94
	v_mul_f32_e32 v121, v95, v95
	v_pk_fma_f32 v[102:103], v[112:113], v[112:113], v[102:103] op_sel_hi:[1,1,0]
	v_pk_fma_f32 v[106:107], v[84:85], v[84:85], v[106:107] op_sel_hi:[1,1,0]
	v_lshlrev_b32_e32 v114, 16, v86
	v_and_b32_e32 v115, 0xffff0000, v86
	v_lshlrev_b32_e32 v86, 16, v87
	v_and_b32_e32 v87, 0xffff0000, v87
	v_mov_b32_e32 v103, v120
	v_mov_b32_e32 v107, v121
	v_lshlrev_b32_e32 v90, 16, v91
	v_and_b32_e32 v91, 0xffff0000, v91
	s_add_i32 s100, s4, -5
	s_ashr_i32 s101, s100, 31
	s_lshl_b64 s[100:101], s[100:101], 12
	v_lshl_add_u64 v[210:211], v[32:33], 0, s[100:101]
	s_nop 0
	global_load_dwordx4 v[178:181], v[210:211], off
	global_load_dwordx4 v[182:185], v[210:211], off offset:1024
	global_load_dwordx4 v[186:189], v[210:211], off offset:2048
	global_load_dwordx4 v[190:193], v[210:211], off offset:3072
	v_pk_add_f32 v[102:103], v[102:103], v[106:107]
	v_mul_f32_e32 v106, v115, v115
	v_mul_f32_e32 v110, v87, v87
	v_mul_f32_e32 v122, v90, v90
	v_mul_f32_e32 v123, v91, v91
	v_pk_fma_f32 v[106:107], v[114:115], v[114:115], v[106:107] op_sel_hi:[1,1,0]
	v_pk_fma_f32 v[110:111], v[86:87], v[86:87], v[110:111] op_sel_hi:[1,1,0]
	v_mov_b32_e32 v107, v122
	v_mov_b32_e32 v111, v123
	v_pk_add_f32 v[106:107], v[106:107], v[110:111]
	s_nop 0
	v_pk_add_f32 v[102:103], v[102:103], v[106:107]
	s_nop 0
	v_pk_add_f32 v[98:99], v[98:99], v[102:103]
	s_nop 0
	v_add_f32_e32 v98, v98, v99
	v_mbcnt_lo_u32_b32 v99, -1, 0
	v_mbcnt_hi_u32_b32 v99, -1, v99
	s_nop 0
	v_lshlrev_b32_e32 v99, 2, v99
	v_xor_b32_e32 v99, 4, v99
	ds_bpermute_b32 v99, v99, v98
	s_waitcnt lgkmcnt(0)
	v_add_f32_e32 v98, v98, v99
	v_mbcnt_lo_u32_b32 v99, -1, 0
	v_mbcnt_hi_u32_b32 v99, -1, v99
	s_nop 0
	v_lshlrev_b32_e32 v99, 2, v99
	v_xor_b32_e32 v99, 8, v99
	ds_bpermute_b32 v99, v99, v98
	s_waitcnt lgkmcnt(0)
	v_add_f32_e32 v98, v98, v99
	v_mbcnt_lo_u32_b32 v99, -1, 0
	v_mbcnt_hi_u32_b32 v99, -1, v99
	s_nop 0
	v_lshlrev_b32_e32 v99, 2, v99
	v_xor_b32_e32 v99, 16, v99
	ds_bpermute_b32 v99, v99, v98
	s_waitcnt lgkmcnt(0)
	v_add_f32_e32 v98, v98, v99
	v_mbcnt_lo_u32_b32 v99, -1, 0
	v_mbcnt_hi_u32_b32 v99, -1, v99
	s_nop 0
	v_lshlrev_b32_e32 v99, 2, v99
	v_xor_b32_e32 v99, 32, v99
	ds_bpermute_b32 v99, v99, v98
	s_waitcnt lgkmcnt(0)
	v_add_f32_e32 v98, v98, v99
	v_mbcnt_lo_u32_b32 v99, -1, 0
	v_mbcnt_hi_u32_b32 v99, -1, v99
	s_nop 0
	v_lshlrev_b32_e32 v99, 2, v99
	v_xor_b32_e32 v99, 64, v99
	ds_bpermute_b32 v99, v99, v98
	s_waitcnt lgkmcnt(0)
	v_add_f32_e32 v98, v98, v99
	v_mbcnt_lo_u32_b32 v99, -1, 0
	v_mbcnt_hi_u32_b32 v99, -1, v99
	s_nop 0
	v_lshlrev_b32_e32 v99, 2, v99
	v_xor_b32_e32 v99, 0x80, v99
	ds_bpermute_b32 v99, v99, v98
	s_waitcnt lgkmcnt(0)
	v_add_f32_e32 v98, v98, v99
	v_fmamk_f32 v98, v98, 0x3a000000, v224
	v_cmp_gt_f32_e32 vcc, s41, v98
	v_mul_f32_e32 v99, 0x4f800000, v98
	s_nop 0
	v_cndmask_b32_e32 v98, v98, v99, vcc
	v_sqrt_f32_e32 v99, v98
	s_nop 0
	v_add_u32_e32 v102, -1, v99
	v_fma_f32 v103, -v102, v99, v98
	v_cmp_ge_f32_e64 s[0:1], 0, v103
	v_add_u32_e32 v103, 1, v99
	s_nop 0
	v_cndmask_b32_e64 v102, v99, v102, s[0:1]
	v_fma_f32 v99, -v103, v99, v98
	v_cmp_lt_f32_e64 s[0:1], 0, v99
	s_nop 1
	v_cndmask_b32_e64 v99, v102, v103, s[0:1]
	v_mul_f32_e32 v102, 0x37800000, v99
	v_cndmask_b32_e32 v99, v99, v102, vcc
	v_cmp_class_f32_e32 vcc, v98, v225
	s_nop 1
	v_cndmask_b32_e32 v98, v99, v98, vcc
	v_div_scale_f32 v99, s[0:1], v98, v98, 1.0
	v_rcp_f32_e32 v102, v99
	s_add_i32 s0, s4, -6
	s_ashr_i32 s1, s0, 31
	v_fma_f32 v103, -v99, v102, 1.0
	v_fmac_f32_e32 v102, v103, v102
	v_div_scale_f32 v103, vcc, 1.0, v98, 1.0
	v_mul_f32_e32 v106, v103, v102
	v_fma_f32 v107, -v99, v106, v103
	v_fmac_f32_e32 v106, v107, v102
	v_fma_f32 v99, -v99, v106, v103
	v_div_fmas_f32 v99, v99, v102, v106
	v_div_fixup_f32 v98, v99, v98, 1.0
	v_mov_b32_e32 v102, v96
	v_mov_b32_e32 v103, v76
	v_mov_b32_e32 v76, v97
	v_pk_mul_f32 v[102:103], v[98:99], v[102:103] op_sel_hi:[0,1]
	v_pk_mul_f32 v[76:77], v[98:99], v[76:77] op_sel_hi:[0,1]
	v_pk_fma_f32 v[96:97], v[48:49], v[76:77], v[6:7]
	v_pk_fma_f32 v[76:77], v[50:51], v[102:103], v[4:5]
	v_mov_b32_e32 v102, v100
	v_mov_b32_e32 v103, v78
	v_mov_b32_e32 v78, v101
	v_pk_mul_f32 v[102:103], v[98:99], v[102:103] op_sel_hi:[0,1]
	v_pk_mul_f32 v[78:79], v[98:99], v[78:79] op_sel_hi:[0,1]
	v_pk_fma_f32 v[100:101], v[44:45], v[78:79], v[2:3]
	v_pk_fma_f32 v[78:79], v[46:47], v[102:103], v[0:1]
	v_cvt_pk_bf16_f32 v76, v76, v77
	v_cvt_pk_bf16_f32 v77, v96, v97
	v_cvt_pk_bf16_f32 v78, v78, v79
	v_cvt_pk_bf16_f32 v79, v100, v101
	v_lshl_add_u64 v[96:97], v[34:35], 0, s[60:61]
	global_store_dwordx4 v[96:97], v[76:79], off
	s_lshl_b64 s[60:61], s[0:1], 12
	s_nop 0
	v_mov_b32_e32 v77, v80
	v_mov_b32_e32 v80, v105
	v_mov_b32_e32 v76, v104
	v_pk_mul_f32 v[78:79], v[98:99], v[80:81] op_sel_hi:[0,1]
	v_mov_b32_e32 v80, v108
	v_mov_b32_e32 v81, v82
	v_mov_b32_e32 v82, v109
	v_pk_mul_f32 v[76:77], v[98:99], v[76:77] op_sel_hi:[0,1]
	v_pk_mul_f32 v[80:81], v[98:99], v[80:81] op_sel_hi:[0,1]
	v_pk_mul_f32 v[82:83], v[98:99], v[82:83] op_sel_hi:[0,1]
	v_pk_fma_f32 v[78:79], v[56:57], v[78:79], v[14:15]
	v_pk_fma_f32 v[76:77], v[58:59], v[76:77], v[12:13]
	v_pk_fma_f32 v[82:83], v[52:53], v[82:83], v[10:11]
	v_pk_fma_f32 v[80:81], v[54:55], v[80:81], v[8:9]
	v_cvt_pk_bf16_f32 v76, v76, v77
	v_cvt_pk_bf16_f32 v77, v78, v79
	v_cvt_pk_bf16_f32 v78, v80, v81
	v_cvt_pk_bf16_f32 v79, v82, v83
	global_store_dwordx4 v[96:97], v[76:79], off offset:1024
	v_pk_mul_f32 v[80:81], v[98:99], v[114:115] op_sel_hi:[0,1]
	v_pk_mul_f32 v[82:83], v[98:99], v[86:87] op_sel_hi:[0,1]
	v_pk_mul_f32 v[76:77], v[98:99], v[112:113] op_sel_hi:[0,1]
	v_pk_mul_f32 v[78:79], v[98:99], v[84:85] op_sel_hi:[0,1]
	v_pk_fma_f32 v[78:79], v[64:65], v[78:79], v[22:23]
	v_pk_fma_f32 v[76:77], v[66:67], v[76:77], v[20:21]
	v_pk_fma_f32 v[82:83], v[60:61], v[82:83], v[18:19]
	v_pk_fma_f32 v[80:81], v[62:63], v[80:81], v[16:17]
	v_cvt_pk_bf16_f32 v76, v76, v77
	v_cvt_pk_bf16_f32 v77, v78, v79
	v_cvt_pk_bf16_f32 v78, v80, v81
	v_cvt_pk_bf16_f32 v79, v82, v83
	global_store_dwordx4 v[96:97], v[76:79], off offset:2048
	v_pk_mul_f32 v[80:81], v[94:95], v[98:99] op_sel_hi:[1,0]
	v_pk_mul_f32 v[82:83], v[90:91], v[98:99] op_sel_hi:[1,0]
	v_pk_mul_f32 v[76:77], v[92:93], v[98:99] op_sel_hi:[1,0]
	v_pk_mul_f32 v[78:79], v[88:89], v[98:99] op_sel_hi:[1,0]
	v_pk_fma_f32 v[76:77], v[74:75], v[76:77], v[28:29]
	v_pk_fma_f32 v[78:79], v[72:73], v[78:79], v[30:31]
	v_pk_fma_f32 v[82:83], v[68:69], v[82:83], v[26:27]
	v_pk_fma_f32 v[80:81], v[70:71], v[80:81], v[24:25]
	v_cvt_pk_bf16_f32 v76, v76, v77
	v_cvt_pk_bf16_f32 v77, v78, v79
	v_cvt_pk_bf16_f32 v78, v80, v81
	v_cvt_pk_bf16_f32 v79, v82, v83
	global_store_dwordx4 v[96:97], v[76:79], off offset:3072
	s_waitcnt vmcnt(11)
	v_lshlrev_b32_e32 v97, 16, v195
	v_lshlrev_b32_e32 v96, 16, v194
	v_and_b32_e32 v77, 0xffff0000, v195
	v_and_b32_e32 v76, 0xffff0000, v194
	v_lshlrev_b32_e32 v101, 16, v197
	v_lshlrev_b32_e32 v100, 16, v196
	v_and_b32_e32 v79, 0xffff0000, v197
	v_and_b32_e32 v78, 0xffff0000, v196
	v_pk_mul_f32 v[98:99], v[76:77], v[76:77]
	v_pk_mul_f32 v[102:103], v[78:79], v[78:79]
	s_waitcnt vmcnt(8)
	v_lshlrev_b32_e32 v92, 16, v206
	v_and_b32_e32 v93, 0xffff0000, v206
	v_pk_fma_f32 v[98:99], v[96:97], v[96:97], v[98:99]
	v_pk_fma_f32 v[102:103], v[100:101], v[100:101], v[102:103]
	v_lshlrev_b32_e32 v105, 16, v199
	v_lshlrev_b32_e32 v104, 16, v198
	v_and_b32_e32 v81, 0xffff0000, v199
	v_and_b32_e32 v80, 0xffff0000, v198
	v_lshlrev_b32_e32 v109, 16, v201
	v_lshlrev_b32_e32 v108, 16, v200
	v_and_b32_e32 v83, 0xffff0000, v201
	v_and_b32_e32 v82, 0xffff0000, v200
	v_pk_mul_f32 v[106:107], v[80:81], v[80:81]
	v_pk_mul_f32 v[110:111], v[82:83], v[82:83]
	v_mul_f32_e32 v116, v92, v92
	v_mul_f32_e32 v117, v93, v93
	v_pk_add_f32 v[98:99], v[98:99], v[98:99] op_sel:[0,1] op_sel_hi:[1,0]
	v_pk_add_f32 v[102:103], v[102:103], v[102:103] op_sel:[0,1] op_sel_hi:[1,0]
	v_lshlrev_b32_e32 v88, 16, v207
	v_and_b32_e32 v89, 0xffff0000, v207
	v_pk_fma_f32 v[106:107], v[104:105], v[104:105], v[106:107]
	v_pk_fma_f32 v[110:111], v[108:109], v[108:109], v[110:111]
	v_mov_b32_e32 v99, v116
	v_mov_b32_e32 v103, v117
	v_mul_f32_e32 v118, v88, v88
	v_mul_f32_e32 v119, v89, v89
	v_pk_add_f32 v[98:99], v[98:99], v[102:103]
	v_pk_add_f32 v[102:103], v[106:107], v[106:107] op_sel:[0,1] op_sel_hi:[1,0]
	v_pk_add_f32 v[106:107], v[110:111], v[110:111] op_sel:[0,1] op_sel_hi:[1,0]
	v_mov_b32_e32 v103, v118
	v_mov_b32_e32 v107, v119
	v_lshlrev_b32_e32 v112, 16, v202
	v_and_b32_e32 v113, 0xffff0000, v202
	v_lshlrev_b32_e32 v84, 16, v203
	v_and_b32_e32 v85, 0xffff0000, v203
	v_pk_add_f32 v[102:103], v[102:103], v[106:107]
	v_lshlrev_b32_e32 v94, 16, v208
	v_and_b32_e32 v95, 0xffff0000, v208
	v_pk_add_f32 v[98:99], v[98:99], v[102:103]
	v_mul_f32_e32 v102, v113, v113
	v_mul_f32_e32 v106, v85, v85
	v_mul_f32_e32 v120, v94, v94
	v_mul_f32_e32 v121, v95, v95
	v_pk_fma_f32 v[102:103], v[112:113], v[112:113], v[102:103] op_sel_hi:[1,1,0]
	v_pk_fma_f32 v[106:107], v[84:85], v[84:85], v[106:107] op_sel_hi:[1,1,0]
	v_lshlrev_b32_e32 v114, 16, v204
	v_and_b32_e32 v115, 0xffff0000, v204
	v_lshlrev_b32_e32 v86, 16, v205
	v_and_b32_e32 v87, 0xffff0000, v205
	v_mov_b32_e32 v103, v120
	v_mov_b32_e32 v107, v121
	v_lshlrev_b32_e32 v90, 16, v209
	v_and_b32_e32 v91, 0xffff0000, v209
	s_add_i32 s100, s4, -4
	s_ashr_i32 s101, s100, 31
	s_lshl_b64 s[100:101], s[100:101], 12
	v_lshl_add_u64 v[210:211], v[32:33], 0, s[100:101]
	s_nop 0
	global_load_dwordx4 v[194:197], v[210:211], off
	global_load_dwordx4 v[198:201], v[210:211], off offset:1024
	global_load_dwordx4 v[202:205], v[210:211], off offset:2048
	global_load_dwordx4 v[206:209], v[210:211], off offset:3072
	v_pk_add_f32 v[102:103], v[102:103], v[106:107]
	v_mul_f32_e32 v106, v115, v115
	v_mul_f32_e32 v110, v87, v87
	v_mul_f32_e32 v122, v90, v90
	v_mul_f32_e32 v123, v91, v91
	v_pk_fma_f32 v[106:107], v[114:115], v[114:115], v[106:107] op_sel_hi:[1,1,0]
	v_pk_fma_f32 v[110:111], v[86:87], v[86:87], v[110:111] op_sel_hi:[1,1,0]
	v_mov_b32_e32 v107, v122
	v_mov_b32_e32 v111, v123
	v_pk_add_f32 v[106:107], v[106:107], v[110:111]
	s_nop 0
	v_pk_add_f32 v[102:103], v[102:103], v[106:107]
	s_nop 0
	v_pk_add_f32 v[98:99], v[98:99], v[102:103]
	s_nop 0
	v_add_f32_e32 v98, v98, v99
	v_mbcnt_lo_u32_b32 v99, -1, 0
	v_mbcnt_hi_u32_b32 v99, -1, v99
	s_nop 0
	v_lshlrev_b32_e32 v99, 2, v99
	v_xor_b32_e32 v99, 4, v99
	ds_bpermute_b32 v99, v99, v98
	s_waitcnt lgkmcnt(0)
	v_add_f32_e32 v98, v98, v99
	v_mbcnt_lo_u32_b32 v99, -1, 0
	v_mbcnt_hi_u32_b32 v99, -1, v99
	s_nop 0
	v_lshlrev_b32_e32 v99, 2, v99
	v_xor_b32_e32 v99, 8, v99
	ds_bpermute_b32 v99, v99, v98
	s_waitcnt lgkmcnt(0)
	v_add_f32_e32 v98, v98, v99
	v_mbcnt_lo_u32_b32 v99, -1, 0
	v_mbcnt_hi_u32_b32 v99, -1, v99
	s_nop 0
	v_lshlrev_b32_e32 v99, 2, v99
	v_xor_b32_e32 v99, 16, v99
	ds_bpermute_b32 v99, v99, v98
	s_waitcnt lgkmcnt(0)
	v_add_f32_e32 v98, v98, v99
	v_mbcnt_lo_u32_b32 v99, -1, 0
	v_mbcnt_hi_u32_b32 v99, -1, v99
	s_nop 0
	v_lshlrev_b32_e32 v99, 2, v99
	v_xor_b32_e32 v99, 32, v99
	ds_bpermute_b32 v99, v99, v98
	s_waitcnt lgkmcnt(0)
	v_add_f32_e32 v98, v98, v99
	v_mbcnt_lo_u32_b32 v99, -1, 0
	v_mbcnt_hi_u32_b32 v99, -1, v99
	s_nop 0
	v_lshlrev_b32_e32 v99, 2, v99
	v_xor_b32_e32 v99, 64, v99
	ds_bpermute_b32 v99, v99, v98
	s_waitcnt lgkmcnt(0)
	v_add_f32_e32 v98, v98, v99
	v_mbcnt_lo_u32_b32 v99, -1, 0
	v_mbcnt_hi_u32_b32 v99, -1, v99
	s_nop 0
	v_lshlrev_b32_e32 v99, 2, v99
	v_xor_b32_e32 v99, 0x80, v99
	ds_bpermute_b32 v99, v99, v98
	s_waitcnt lgkmcnt(0)
	v_add_f32_e32 v98, v98, v99
	v_fmamk_f32 v98, v98, 0x3a000000, v224
	v_cmp_gt_f32_e32 vcc, s41, v98
	v_mul_f32_e32 v99, 0x4f800000, v98
	s_nop 0
	v_cndmask_b32_e32 v98, v98, v99, vcc
	v_sqrt_f32_e32 v99, v98
	s_nop 0
	v_add_u32_e32 v102, -1, v99
	v_fma_f32 v103, -v102, v99, v98
	v_cmp_ge_f32_e64 s[0:1], 0, v103
	v_add_u32_e32 v103, 1, v99
	s_nop 0
	v_cndmask_b32_e64 v102, v99, v102, s[0:1]
	v_fma_f32 v99, -v103, v99, v98
	v_cmp_lt_f32_e64 s[0:1], 0, v99
	s_nop 1
	v_cndmask_b32_e64 v99, v102, v103, s[0:1]
	v_mul_f32_e32 v102, 0x37800000, v99
	v_cndmask_b32_e32 v99, v99, v102, vcc
	v_cmp_class_f32_e32 vcc, v98, v225
	s_nop 1
	v_cndmask_b32_e32 v98, v99, v98, vcc
	v_div_scale_f32 v99, s[0:1], v98, v98, 1.0
	v_rcp_f32_e32 v102, v99
	s_add_i32 s0, s4, -5
	s_ashr_i32 s1, s0, 31
	v_fma_f32 v103, -v99, v102, 1.0
	v_fmac_f32_e32 v102, v103, v102
	v_div_scale_f32 v103, vcc, 1.0, v98, 1.0
	v_mul_f32_e32 v106, v103, v102
	v_fma_f32 v107, -v99, v106, v103
	v_fmac_f32_e32 v106, v107, v102
	v_fma_f32 v99, -v99, v106, v103
	v_div_fmas_f32 v99, v99, v102, v106
	v_div_fixup_f32 v98, v99, v98, 1.0
	v_mov_b32_e32 v102, v96
	v_mov_b32_e32 v103, v76
	v_mov_b32_e32 v76, v97
	v_pk_mul_f32 v[102:103], v[98:99], v[102:103] op_sel_hi:[0,1]
	v_pk_mul_f32 v[76:77], v[98:99], v[76:77] op_sel_hi:[0,1]
	v_pk_fma_f32 v[96:97], v[48:49], v[76:77], v[6:7]
	v_pk_fma_f32 v[76:77], v[50:51], v[102:103], v[4:5]
	v_mov_b32_e32 v102, v100
	v_mov_b32_e32 v103, v78
	v_mov_b32_e32 v78, v101
	v_pk_mul_f32 v[102:103], v[98:99], v[102:103] op_sel_hi:[0,1]
	v_pk_mul_f32 v[78:79], v[98:99], v[78:79] op_sel_hi:[0,1]
	v_pk_fma_f32 v[100:101], v[44:45], v[78:79], v[2:3]
	v_pk_fma_f32 v[78:79], v[46:47], v[102:103], v[0:1]
	v_cvt_pk_bf16_f32 v76, v76, v77
	v_cvt_pk_bf16_f32 v77, v96, v97
	v_cvt_pk_bf16_f32 v78, v78, v79
	v_cvt_pk_bf16_f32 v79, v100, v101
	v_lshl_add_u64 v[96:97], v[34:35], 0, s[60:61]
	global_store_dwordx4 v[96:97], v[76:79], off
	s_lshl_b64 s[60:61], s[0:1], 12
	s_nop 0
	v_mov_b32_e32 v77, v80
	v_mov_b32_e32 v80, v105
	v_mov_b32_e32 v76, v104
	v_pk_mul_f32 v[78:79], v[98:99], v[80:81] op_sel_hi:[0,1]
	v_mov_b32_e32 v80, v108
	v_mov_b32_e32 v81, v82
	v_mov_b32_e32 v82, v109
	v_pk_mul_f32 v[76:77], v[98:99], v[76:77] op_sel_hi:[0,1]
	v_pk_mul_f32 v[80:81], v[98:99], v[80:81] op_sel_hi:[0,1]
	v_pk_mul_f32 v[82:83], v[98:99], v[82:83] op_sel_hi:[0,1]
	v_pk_fma_f32 v[78:79], v[56:57], v[78:79], v[14:15]
	v_pk_fma_f32 v[76:77], v[58:59], v[76:77], v[12:13]
	v_pk_fma_f32 v[82:83], v[52:53], v[82:83], v[10:11]
	v_pk_fma_f32 v[80:81], v[54:55], v[80:81], v[8:9]
	v_cvt_pk_bf16_f32 v76, v76, v77
	v_cvt_pk_bf16_f32 v77, v78, v79
	v_cvt_pk_bf16_f32 v78, v80, v81
	v_cvt_pk_bf16_f32 v79, v82, v83
	global_store_dwordx4 v[96:97], v[76:79], off offset:1024
	v_pk_mul_f32 v[80:81], v[98:99], v[114:115] op_sel_hi:[0,1]
	v_pk_mul_f32 v[82:83], v[98:99], v[86:87] op_sel_hi:[0,1]
	v_pk_mul_f32 v[76:77], v[98:99], v[112:113] op_sel_hi:[0,1]
	v_pk_mul_f32 v[78:79], v[98:99], v[84:85] op_sel_hi:[0,1]
	v_pk_fma_f32 v[78:79], v[64:65], v[78:79], v[22:23]
	v_pk_fma_f32 v[76:77], v[66:67], v[76:77], v[20:21]
	v_pk_fma_f32 v[82:83], v[60:61], v[82:83], v[18:19]
	v_pk_fma_f32 v[80:81], v[62:63], v[80:81], v[16:17]
	v_cvt_pk_bf16_f32 v76, v76, v77
	v_cvt_pk_bf16_f32 v77, v78, v79
	v_cvt_pk_bf16_f32 v78, v80, v81
	v_cvt_pk_bf16_f32 v79, v82, v83
	global_store_dwordx4 v[96:97], v[76:79], off offset:2048
	v_pk_mul_f32 v[80:81], v[94:95], v[98:99] op_sel_hi:[1,0]
	v_pk_mul_f32 v[82:83], v[90:91], v[98:99] op_sel_hi:[1,0]
	v_pk_mul_f32 v[76:77], v[92:93], v[98:99] op_sel_hi:[1,0]
	v_pk_mul_f32 v[78:79], v[88:89], v[98:99] op_sel_hi:[1,0]
	v_pk_fma_f32 v[76:77], v[74:75], v[76:77], v[28:29]
	v_pk_fma_f32 v[78:79], v[72:73], v[78:79], v[30:31]
	v_pk_fma_f32 v[82:83], v[68:69], v[82:83], v[26:27]
	v_pk_fma_f32 v[80:81], v[70:71], v[80:81], v[24:25]
	v_cvt_pk_bf16_f32 v76, v76, v77
	v_cvt_pk_bf16_f32 v77, v78, v79
	v_cvt_pk_bf16_f32 v78, v80, v81
	v_cvt_pk_bf16_f32 v79, v82, v83
	global_store_dwordx4 v[96:97], v[76:79], off offset:3072
	s_waitcnt vmcnt(11)
	v_lshlrev_b32_e32 v97, 16, v179
	v_lshlrev_b32_e32 v96, 16, v178
	v_and_b32_e32 v77, 0xffff0000, v179
	v_and_b32_e32 v76, 0xffff0000, v178
	v_lshlrev_b32_e32 v101, 16, v181
	v_lshlrev_b32_e32 v100, 16, v180
	v_and_b32_e32 v79, 0xffff0000, v181
	v_and_b32_e32 v78, 0xffff0000, v180
	v_pk_mul_f32 v[98:99], v[76:77], v[76:77]
	v_pk_mul_f32 v[102:103], v[78:79], v[78:79]
	s_waitcnt vmcnt(8)
	v_lshlrev_b32_e32 v92, 16, v190
	v_and_b32_e32 v93, 0xffff0000, v190
	v_pk_fma_f32 v[98:99], v[96:97], v[96:97], v[98:99]
	v_pk_fma_f32 v[102:103], v[100:101], v[100:101], v[102:103]
	v_lshlrev_b32_e32 v105, 16, v183
	v_lshlrev_b32_e32 v104, 16, v182
	v_and_b32_e32 v81, 0xffff0000, v183
	v_and_b32_e32 v80, 0xffff0000, v182
	v_lshlrev_b32_e32 v109, 16, v185
	v_lshlrev_b32_e32 v108, 16, v184
	v_and_b32_e32 v83, 0xffff0000, v185
	v_and_b32_e32 v82, 0xffff0000, v184
	v_pk_mul_f32 v[106:107], v[80:81], v[80:81]
	v_pk_mul_f32 v[110:111], v[82:83], v[82:83]
	v_mul_f32_e32 v116, v92, v92
	v_mul_f32_e32 v117, v93, v93
	v_pk_add_f32 v[98:99], v[98:99], v[98:99] op_sel:[0,1] op_sel_hi:[1,0]
	v_pk_add_f32 v[102:103], v[102:103], v[102:103] op_sel:[0,1] op_sel_hi:[1,0]
	v_lshlrev_b32_e32 v88, 16, v191
	v_and_b32_e32 v89, 0xffff0000, v191
	v_pk_fma_f32 v[106:107], v[104:105], v[104:105], v[106:107]
	v_pk_fma_f32 v[110:111], v[108:109], v[108:109], v[110:111]
	v_mov_b32_e32 v99, v116
	v_mov_b32_e32 v103, v117
	v_mul_f32_e32 v118, v88, v88
	v_mul_f32_e32 v119, v89, v89
	v_pk_add_f32 v[98:99], v[98:99], v[102:103]
	v_pk_add_f32 v[102:103], v[106:107], v[106:107] op_sel:[0,1] op_sel_hi:[1,0]
	v_pk_add_f32 v[106:107], v[110:111], v[110:111] op_sel:[0,1] op_sel_hi:[1,0]
	v_mov_b32_e32 v103, v118
	v_mov_b32_e32 v107, v119
	v_lshlrev_b32_e32 v112, 16, v186
	v_and_b32_e32 v113, 0xffff0000, v186
	v_lshlrev_b32_e32 v84, 16, v187
	v_and_b32_e32 v85, 0xffff0000, v187
	v_pk_add_f32 v[102:103], v[102:103], v[106:107]
	v_lshlrev_b32_e32 v94, 16, v192
	v_and_b32_e32 v95, 0xffff0000, v192
	v_pk_add_f32 v[98:99], v[98:99], v[102:103]
	v_mul_f32_e32 v102, v113, v113
	v_mul_f32_e32 v106, v85, v85
	v_mul_f32_e32 v120, v94, v94
	v_mul_f32_e32 v121, v95, v95
	v_pk_fma_f32 v[102:103], v[112:113], v[112:113], v[102:103] op_sel_hi:[1,1,0]
	v_pk_fma_f32 v[106:107], v[84:85], v[84:85], v[106:107] op_sel_hi:[1,1,0]
	v_lshlrev_b32_e32 v114, 16, v188
	v_and_b32_e32 v115, 0xffff0000, v188
	v_lshlrev_b32_e32 v86, 16, v189
	v_and_b32_e32 v87, 0xffff0000, v189
	v_mov_b32_e32 v103, v120
	v_mov_b32_e32 v107, v121
	v_lshlrev_b32_e32 v90, 16, v193
	v_and_b32_e32 v91, 0xffff0000, v193
	s_add_i32 s100, s4, -3
	s_ashr_i32 s101, s100, 31
	s_lshl_b64 s[100:101], s[100:101], 12
	v_lshl_add_u64 v[210:211], v[32:33], 0, s[100:101]
	s_nop 0
	global_load_dwordx4 v[178:181], v[210:211], off
	global_load_dwordx4 v[182:185], v[210:211], off offset:1024
	global_load_dwordx4 v[186:189], v[210:211], off offset:2048
	global_load_dwordx4 v[190:193], v[210:211], off offset:3072
	v_pk_add_f32 v[102:103], v[102:103], v[106:107]
	v_mul_f32_e32 v106, v115, v115
	v_mul_f32_e32 v110, v87, v87
	v_mul_f32_e32 v122, v90, v90
	v_mul_f32_e32 v123, v91, v91
	v_pk_fma_f32 v[106:107], v[114:115], v[114:115], v[106:107] op_sel_hi:[1,1,0]
	v_pk_fma_f32 v[110:111], v[86:87], v[86:87], v[110:111] op_sel_hi:[1,1,0]
	v_mov_b32_e32 v107, v122
	v_mov_b32_e32 v111, v123
	v_pk_add_f32 v[106:107], v[106:107], v[110:111]
	s_nop 0
	v_pk_add_f32 v[102:103], v[102:103], v[106:107]
	s_nop 0
	v_pk_add_f32 v[98:99], v[98:99], v[102:103]
	s_nop 0
	v_add_f32_e32 v98, v98, v99
	v_mbcnt_lo_u32_b32 v99, -1, 0
	v_mbcnt_hi_u32_b32 v99, -1, v99
	s_nop 0
	v_lshlrev_b32_e32 v99, 2, v99
	v_xor_b32_e32 v99, 4, v99
	ds_bpermute_b32 v99, v99, v98
	s_waitcnt lgkmcnt(0)
	v_add_f32_e32 v98, v98, v99
	v_mbcnt_lo_u32_b32 v99, -1, 0
	v_mbcnt_hi_u32_b32 v99, -1, v99
	s_nop 0
	v_lshlrev_b32_e32 v99, 2, v99
	v_xor_b32_e32 v99, 8, v99
	ds_bpermute_b32 v99, v99, v98
	s_waitcnt lgkmcnt(0)
	v_add_f32_e32 v98, v98, v99
	v_mbcnt_lo_u32_b32 v99, -1, 0
	v_mbcnt_hi_u32_b32 v99, -1, v99
	s_nop 0
	v_lshlrev_b32_e32 v99, 2, v99
	v_xor_b32_e32 v99, 16, v99
	ds_bpermute_b32 v99, v99, v98
	s_waitcnt lgkmcnt(0)
	v_add_f32_e32 v98, v98, v99
	v_mbcnt_lo_u32_b32 v99, -1, 0
	v_mbcnt_hi_u32_b32 v99, -1, v99
	s_nop 0
	v_lshlrev_b32_e32 v99, 2, v99
	v_xor_b32_e32 v99, 32, v99
	ds_bpermute_b32 v99, v99, v98
	s_waitcnt lgkmcnt(0)
	v_add_f32_e32 v98, v98, v99
	v_mbcnt_lo_u32_b32 v99, -1, 0
	v_mbcnt_hi_u32_b32 v99, -1, v99
	s_nop 0
	v_lshlrev_b32_e32 v99, 2, v99
	v_xor_b32_e32 v99, 64, v99
	ds_bpermute_b32 v99, v99, v98
	s_waitcnt lgkmcnt(0)
	v_add_f32_e32 v98, v98, v99
	v_mbcnt_lo_u32_b32 v99, -1, 0
	v_mbcnt_hi_u32_b32 v99, -1, v99
	s_nop 0
	v_lshlrev_b32_e32 v99, 2, v99
	v_xor_b32_e32 v99, 0x80, v99
	ds_bpermute_b32 v99, v99, v98
	s_waitcnt lgkmcnt(0)
	v_add_f32_e32 v98, v98, v99
	v_fmamk_f32 v98, v98, 0x3a000000, v224
	v_cmp_gt_f32_e32 vcc, s41, v98
	v_mul_f32_e32 v99, 0x4f800000, v98
	s_nop 0
	v_cndmask_b32_e32 v98, v98, v99, vcc
	v_sqrt_f32_e32 v99, v98
	s_nop 0
	v_add_u32_e32 v102, -1, v99
	v_fma_f32 v103, -v102, v99, v98
	v_cmp_ge_f32_e64 s[0:1], 0, v103
	v_add_u32_e32 v103, 1, v99
	s_nop 0
	v_cndmask_b32_e64 v102, v99, v102, s[0:1]
	v_fma_f32 v99, -v103, v99, v98
	v_cmp_lt_f32_e64 s[0:1], 0, v99
	s_nop 1
	v_cndmask_b32_e64 v99, v102, v103, s[0:1]
	v_mul_f32_e32 v102, 0x37800000, v99
	v_cndmask_b32_e32 v99, v99, v102, vcc
	v_cmp_class_f32_e32 vcc, v98, v225
	s_nop 1
	v_cndmask_b32_e32 v98, v99, v98, vcc
	v_div_scale_f32 v99, s[0:1], v98, v98, 1.0
	v_rcp_f32_e32 v102, v99
	s_add_i32 s0, s4, -4
	s_ashr_i32 s1, s0, 31
	v_fma_f32 v103, -v99, v102, 1.0
	v_fmac_f32_e32 v102, v103, v102
	v_div_scale_f32 v103, vcc, 1.0, v98, 1.0
	v_mul_f32_e32 v106, v103, v102
	v_fma_f32 v107, -v99, v106, v103
	v_fmac_f32_e32 v106, v107, v102
	v_fma_f32 v99, -v99, v106, v103
	v_div_fmas_f32 v99, v99, v102, v106
	v_div_fixup_f32 v98, v99, v98, 1.0
	v_mov_b32_e32 v102, v96
	v_mov_b32_e32 v103, v76
	v_mov_b32_e32 v76, v97
	v_pk_mul_f32 v[102:103], v[98:99], v[102:103] op_sel_hi:[0,1]
	v_pk_mul_f32 v[76:77], v[98:99], v[76:77] op_sel_hi:[0,1]
	v_pk_fma_f32 v[96:97], v[48:49], v[76:77], v[6:7]
	v_pk_fma_f32 v[76:77], v[50:51], v[102:103], v[4:5]
	v_mov_b32_e32 v102, v100
	v_mov_b32_e32 v103, v78
	v_mov_b32_e32 v78, v101
	v_pk_mul_f32 v[102:103], v[98:99], v[102:103] op_sel_hi:[0,1]
	v_pk_mul_f32 v[78:79], v[98:99], v[78:79] op_sel_hi:[0,1]
	v_pk_fma_f32 v[100:101], v[44:45], v[78:79], v[2:3]
	v_pk_fma_f32 v[78:79], v[46:47], v[102:103], v[0:1]
	v_cvt_pk_bf16_f32 v76, v76, v77
	v_cvt_pk_bf16_f32 v77, v96, v97
	v_cvt_pk_bf16_f32 v78, v78, v79
	v_cvt_pk_bf16_f32 v79, v100, v101
	v_lshl_add_u64 v[96:97], v[34:35], 0, s[60:61]
	global_store_dwordx4 v[96:97], v[76:79], off
	s_lshl_b64 s[60:61], s[0:1], 12
	s_nop 0
	v_mov_b32_e32 v77, v80
	v_mov_b32_e32 v80, v105
	v_mov_b32_e32 v76, v104
	v_pk_mul_f32 v[78:79], v[98:99], v[80:81] op_sel_hi:[0,1]
	v_mov_b32_e32 v80, v108
	v_mov_b32_e32 v81, v82
	v_mov_b32_e32 v82, v109
	v_pk_mul_f32 v[76:77], v[98:99], v[76:77] op_sel_hi:[0,1]
	v_pk_mul_f32 v[80:81], v[98:99], v[80:81] op_sel_hi:[0,1]
	v_pk_mul_f32 v[82:83], v[98:99], v[82:83] op_sel_hi:[0,1]
	v_pk_fma_f32 v[78:79], v[56:57], v[78:79], v[14:15]
	v_pk_fma_f32 v[76:77], v[58:59], v[76:77], v[12:13]
	v_pk_fma_f32 v[82:83], v[52:53], v[82:83], v[10:11]
	v_pk_fma_f32 v[80:81], v[54:55], v[80:81], v[8:9]
	v_cvt_pk_bf16_f32 v76, v76, v77
	v_cvt_pk_bf16_f32 v77, v78, v79
	v_cvt_pk_bf16_f32 v78, v80, v81
	v_cvt_pk_bf16_f32 v79, v82, v83
	global_store_dwordx4 v[96:97], v[76:79], off offset:1024
	v_pk_mul_f32 v[80:81], v[98:99], v[114:115] op_sel_hi:[0,1]
	v_pk_mul_f32 v[82:83], v[98:99], v[86:87] op_sel_hi:[0,1]
	v_pk_mul_f32 v[76:77], v[98:99], v[112:113] op_sel_hi:[0,1]
	v_pk_mul_f32 v[78:79], v[98:99], v[84:85] op_sel_hi:[0,1]
	v_pk_fma_f32 v[78:79], v[64:65], v[78:79], v[22:23]
	v_pk_fma_f32 v[76:77], v[66:67], v[76:77], v[20:21]
	v_pk_fma_f32 v[82:83], v[60:61], v[82:83], v[18:19]
	v_pk_fma_f32 v[80:81], v[62:63], v[80:81], v[16:17]
	v_cvt_pk_bf16_f32 v76, v76, v77
	v_cvt_pk_bf16_f32 v77, v78, v79
	v_cvt_pk_bf16_f32 v78, v80, v81
	v_cvt_pk_bf16_f32 v79, v82, v83
	global_store_dwordx4 v[96:97], v[76:79], off offset:2048
	v_pk_mul_f32 v[80:81], v[94:95], v[98:99] op_sel_hi:[1,0]
	v_pk_mul_f32 v[82:83], v[90:91], v[98:99] op_sel_hi:[1,0]
	v_pk_mul_f32 v[76:77], v[92:93], v[98:99] op_sel_hi:[1,0]
	v_pk_mul_f32 v[78:79], v[88:89], v[98:99] op_sel_hi:[1,0]
	v_pk_fma_f32 v[76:77], v[74:75], v[76:77], v[28:29]
	v_pk_fma_f32 v[78:79], v[72:73], v[78:79], v[30:31]
	v_pk_fma_f32 v[82:83], v[68:69], v[82:83], v[26:27]
	v_pk_fma_f32 v[80:81], v[70:71], v[80:81], v[24:25]
	v_cvt_pk_bf16_f32 v76, v76, v77
	v_cvt_pk_bf16_f32 v77, v78, v79
	v_cvt_pk_bf16_f32 v78, v80, v81
	v_cvt_pk_bf16_f32 v79, v82, v83
	global_store_dwordx4 v[96:97], v[76:79], off offset:3072
	s_waitcnt vmcnt(11)
	v_lshlrev_b32_e32 v97, 16, v195
	v_lshlrev_b32_e32 v96, 16, v194
	v_and_b32_e32 v77, 0xffff0000, v195
	v_and_b32_e32 v76, 0xffff0000, v194
	v_lshlrev_b32_e32 v101, 16, v197
	v_lshlrev_b32_e32 v100, 16, v196
	v_and_b32_e32 v79, 0xffff0000, v197
	v_and_b32_e32 v78, 0xffff0000, v196
	v_pk_mul_f32 v[98:99], v[76:77], v[76:77]
	v_pk_mul_f32 v[102:103], v[78:79], v[78:79]
	s_waitcnt vmcnt(8)
	v_lshlrev_b32_e32 v92, 16, v206
	v_and_b32_e32 v93, 0xffff0000, v206
	v_pk_fma_f32 v[98:99], v[96:97], v[96:97], v[98:99]
	v_pk_fma_f32 v[102:103], v[100:101], v[100:101], v[102:103]
	v_lshlrev_b32_e32 v105, 16, v199
	v_lshlrev_b32_e32 v104, 16, v198
	v_and_b32_e32 v81, 0xffff0000, v199
	v_and_b32_e32 v80, 0xffff0000, v198
	v_lshlrev_b32_e32 v109, 16, v201
	v_lshlrev_b32_e32 v108, 16, v200
	v_and_b32_e32 v83, 0xffff0000, v201
	v_and_b32_e32 v82, 0xffff0000, v200
	v_pk_mul_f32 v[106:107], v[80:81], v[80:81]
	v_pk_mul_f32 v[110:111], v[82:83], v[82:83]
	v_mul_f32_e32 v116, v92, v92
	v_mul_f32_e32 v117, v93, v93
	v_pk_add_f32 v[98:99], v[98:99], v[98:99] op_sel:[0,1] op_sel_hi:[1,0]
	v_pk_add_f32 v[102:103], v[102:103], v[102:103] op_sel:[0,1] op_sel_hi:[1,0]
	v_lshlrev_b32_e32 v88, 16, v207
	v_and_b32_e32 v89, 0xffff0000, v207
	v_pk_fma_f32 v[106:107], v[104:105], v[104:105], v[106:107]
	v_pk_fma_f32 v[110:111], v[108:109], v[108:109], v[110:111]
	v_mov_b32_e32 v99, v116
	v_mov_b32_e32 v103, v117
	v_mul_f32_e32 v118, v88, v88
	v_mul_f32_e32 v119, v89, v89
	v_pk_add_f32 v[98:99], v[98:99], v[102:103]
	v_pk_add_f32 v[102:103], v[106:107], v[106:107] op_sel:[0,1] op_sel_hi:[1,0]
	v_pk_add_f32 v[106:107], v[110:111], v[110:111] op_sel:[0,1] op_sel_hi:[1,0]
	v_mov_b32_e32 v103, v118
	v_mov_b32_e32 v107, v119
	v_lshlrev_b32_e32 v112, 16, v202
	v_and_b32_e32 v113, 0xffff0000, v202
	v_lshlrev_b32_e32 v84, 16, v203
	v_and_b32_e32 v85, 0xffff0000, v203
	v_pk_add_f32 v[102:103], v[102:103], v[106:107]
	v_lshlrev_b32_e32 v94, 16, v208
	v_and_b32_e32 v95, 0xffff0000, v208
	v_pk_add_f32 v[98:99], v[98:99], v[102:103]
	v_mul_f32_e32 v102, v113, v113
	v_mul_f32_e32 v106, v85, v85
	v_mul_f32_e32 v120, v94, v94
	v_mul_f32_e32 v121, v95, v95
	v_pk_fma_f32 v[102:103], v[112:113], v[112:113], v[102:103] op_sel_hi:[1,1,0]
	v_pk_fma_f32 v[106:107], v[84:85], v[84:85], v[106:107] op_sel_hi:[1,1,0]
	v_lshlrev_b32_e32 v114, 16, v204
	v_and_b32_e32 v115, 0xffff0000, v204
	v_lshlrev_b32_e32 v86, 16, v205
	v_and_b32_e32 v87, 0xffff0000, v205
	v_mov_b32_e32 v103, v120
	v_mov_b32_e32 v107, v121
	v_lshlrev_b32_e32 v90, 16, v209
	v_and_b32_e32 v91, 0xffff0000, v209
	s_add_i32 s100, s4, -2
	s_ashr_i32 s101, s100, 31
	s_lshl_b64 s[100:101], s[100:101], 12
	v_lshl_add_u64 v[210:211], v[32:33], 0, s[100:101]
	s_nop 0
	global_load_dwordx4 v[194:197], v[210:211], off
	global_load_dwordx4 v[198:201], v[210:211], off offset:1024
	global_load_dwordx4 v[202:205], v[210:211], off offset:2048
	global_load_dwordx4 v[206:209], v[210:211], off offset:3072
	v_pk_add_f32 v[102:103], v[102:103], v[106:107]
	v_mul_f32_e32 v106, v115, v115
	v_mul_f32_e32 v110, v87, v87
	v_mul_f32_e32 v122, v90, v90
	v_mul_f32_e32 v123, v91, v91
	v_pk_fma_f32 v[106:107], v[114:115], v[114:115], v[106:107] op_sel_hi:[1,1,0]
	v_pk_fma_f32 v[110:111], v[86:87], v[86:87], v[110:111] op_sel_hi:[1,1,0]
	v_mov_b32_e32 v107, v122
	v_mov_b32_e32 v111, v123
	v_pk_add_f32 v[106:107], v[106:107], v[110:111]
	s_nop 0
	v_pk_add_f32 v[102:103], v[102:103], v[106:107]
	s_nop 0
	v_pk_add_f32 v[98:99], v[98:99], v[102:103]
	s_nop 0
	v_add_f32_e32 v98, v98, v99
	v_mbcnt_lo_u32_b32 v99, -1, 0
	v_mbcnt_hi_u32_b32 v99, -1, v99
	s_nop 0
	v_lshlrev_b32_e32 v99, 2, v99
	v_xor_b32_e32 v99, 4, v99
	ds_bpermute_b32 v99, v99, v98
	s_waitcnt lgkmcnt(0)
	v_add_f32_e32 v98, v98, v99
	v_mbcnt_lo_u32_b32 v99, -1, 0
	v_mbcnt_hi_u32_b32 v99, -1, v99
	s_nop 0
	v_lshlrev_b32_e32 v99, 2, v99
	v_xor_b32_e32 v99, 8, v99
	ds_bpermute_b32 v99, v99, v98
	s_waitcnt lgkmcnt(0)
	v_add_f32_e32 v98, v98, v99
	v_mbcnt_lo_u32_b32 v99, -1, 0
	v_mbcnt_hi_u32_b32 v99, -1, v99
	s_nop 0
	v_lshlrev_b32_e32 v99, 2, v99
	v_xor_b32_e32 v99, 16, v99
	ds_bpermute_b32 v99, v99, v98
	s_waitcnt lgkmcnt(0)
	v_add_f32_e32 v98, v98, v99
	v_mbcnt_lo_u32_b32 v99, -1, 0
	v_mbcnt_hi_u32_b32 v99, -1, v99
	s_nop 0
	v_lshlrev_b32_e32 v99, 2, v99
	v_xor_b32_e32 v99, 32, v99
	ds_bpermute_b32 v99, v99, v98
	s_waitcnt lgkmcnt(0)
	v_add_f32_e32 v98, v98, v99
	v_mbcnt_lo_u32_b32 v99, -1, 0
	v_mbcnt_hi_u32_b32 v99, -1, v99
	s_nop 0
	v_lshlrev_b32_e32 v99, 2, v99
	v_xor_b32_e32 v99, 64, v99
	ds_bpermute_b32 v99, v99, v98
	s_waitcnt lgkmcnt(0)
	v_add_f32_e32 v98, v98, v99
	v_mbcnt_lo_u32_b32 v99, -1, 0
	v_mbcnt_hi_u32_b32 v99, -1, v99
	s_nop 0
	v_lshlrev_b32_e32 v99, 2, v99
	v_xor_b32_e32 v99, 0x80, v99
	ds_bpermute_b32 v99, v99, v98
	s_waitcnt lgkmcnt(0)
	v_add_f32_e32 v98, v98, v99
	v_fmamk_f32 v98, v98, 0x3a000000, v224
	v_cmp_gt_f32_e32 vcc, s41, v98
	v_mul_f32_e32 v99, 0x4f800000, v98
	s_nop 0
	v_cndmask_b32_e32 v98, v98, v99, vcc
	v_sqrt_f32_e32 v99, v98
	s_nop 0
	v_add_u32_e32 v102, -1, v99
	v_fma_f32 v103, -v102, v99, v98
	v_cmp_ge_f32_e64 s[0:1], 0, v103
	v_add_u32_e32 v103, 1, v99
	s_nop 0
	v_cndmask_b32_e64 v102, v99, v102, s[0:1]
	v_fma_f32 v99, -v103, v99, v98
	v_cmp_lt_f32_e64 s[0:1], 0, v99
	s_nop 1
	v_cndmask_b32_e64 v99, v102, v103, s[0:1]
	v_mul_f32_e32 v102, 0x37800000, v99
	v_cndmask_b32_e32 v99, v99, v102, vcc
	v_cmp_class_f32_e32 vcc, v98, v225
	s_nop 1
	v_cndmask_b32_e32 v98, v99, v98, vcc
	v_div_scale_f32 v99, s[0:1], v98, v98, 1.0
	v_rcp_f32_e32 v102, v99
	s_add_i32 s0, s4, -3
	s_ashr_i32 s1, s0, 31
	v_fma_f32 v103, -v99, v102, 1.0
	v_fmac_f32_e32 v102, v103, v102
	v_div_scale_f32 v103, vcc, 1.0, v98, 1.0
	v_mul_f32_e32 v106, v103, v102
	v_fma_f32 v107, -v99, v106, v103
	v_fmac_f32_e32 v106, v107, v102
	v_fma_f32 v99, -v99, v106, v103
	v_div_fmas_f32 v99, v99, v102, v106
	v_div_fixup_f32 v98, v99, v98, 1.0
	v_mov_b32_e32 v102, v96
	v_mov_b32_e32 v103, v76
	v_mov_b32_e32 v76, v97
	v_pk_mul_f32 v[102:103], v[98:99], v[102:103] op_sel_hi:[0,1]
	v_pk_mul_f32 v[76:77], v[98:99], v[76:77] op_sel_hi:[0,1]
	v_pk_fma_f32 v[96:97], v[48:49], v[76:77], v[6:7]
	v_pk_fma_f32 v[76:77], v[50:51], v[102:103], v[4:5]
	v_mov_b32_e32 v102, v100
	v_mov_b32_e32 v103, v78
	v_mov_b32_e32 v78, v101
	v_pk_mul_f32 v[102:103], v[98:99], v[102:103] op_sel_hi:[0,1]
	v_pk_mul_f32 v[78:79], v[98:99], v[78:79] op_sel_hi:[0,1]
	v_pk_fma_f32 v[100:101], v[44:45], v[78:79], v[2:3]
	v_pk_fma_f32 v[78:79], v[46:47], v[102:103], v[0:1]
	v_cvt_pk_bf16_f32 v76, v76, v77
	v_cvt_pk_bf16_f32 v77, v96, v97
	v_cvt_pk_bf16_f32 v78, v78, v79
	v_cvt_pk_bf16_f32 v79, v100, v101
	v_lshl_add_u64 v[96:97], v[34:35], 0, s[60:61]
	global_store_dwordx4 v[96:97], v[76:79], off
	s_lshl_b64 s[60:61], s[0:1], 12
	s_nop 0
	v_mov_b32_e32 v77, v80
	v_mov_b32_e32 v80, v105
	v_mov_b32_e32 v76, v104
	v_pk_mul_f32 v[78:79], v[98:99], v[80:81] op_sel_hi:[0,1]
	v_mov_b32_e32 v80, v108
	v_mov_b32_e32 v81, v82
	v_mov_b32_e32 v82, v109
	v_pk_mul_f32 v[76:77], v[98:99], v[76:77] op_sel_hi:[0,1]
	v_pk_mul_f32 v[80:81], v[98:99], v[80:81] op_sel_hi:[0,1]
	v_pk_mul_f32 v[82:83], v[98:99], v[82:83] op_sel_hi:[0,1]
	v_pk_fma_f32 v[78:79], v[56:57], v[78:79], v[14:15]
	v_pk_fma_f32 v[76:77], v[58:59], v[76:77], v[12:13]
	v_pk_fma_f32 v[82:83], v[52:53], v[82:83], v[10:11]
	v_pk_fma_f32 v[80:81], v[54:55], v[80:81], v[8:9]
	v_cvt_pk_bf16_f32 v76, v76, v77
	v_cvt_pk_bf16_f32 v77, v78, v79
	v_cvt_pk_bf16_f32 v78, v80, v81
	v_cvt_pk_bf16_f32 v79, v82, v83
	global_store_dwordx4 v[96:97], v[76:79], off offset:1024
	v_pk_mul_f32 v[80:81], v[98:99], v[114:115] op_sel_hi:[0,1]
	v_pk_mul_f32 v[82:83], v[98:99], v[86:87] op_sel_hi:[0,1]
	v_pk_mul_f32 v[76:77], v[98:99], v[112:113] op_sel_hi:[0,1]
	v_pk_mul_f32 v[78:79], v[98:99], v[84:85] op_sel_hi:[0,1]
	v_pk_fma_f32 v[78:79], v[64:65], v[78:79], v[22:23]
	v_pk_fma_f32 v[76:77], v[66:67], v[76:77], v[20:21]
	v_pk_fma_f32 v[82:83], v[60:61], v[82:83], v[18:19]
	v_pk_fma_f32 v[80:81], v[62:63], v[80:81], v[16:17]
	v_cvt_pk_bf16_f32 v76, v76, v77
	v_cvt_pk_bf16_f32 v77, v78, v79
	v_cvt_pk_bf16_f32 v78, v80, v81
	v_cvt_pk_bf16_f32 v79, v82, v83
	global_store_dwordx4 v[96:97], v[76:79], off offset:2048
	v_pk_mul_f32 v[80:81], v[94:95], v[98:99] op_sel_hi:[1,0]
	v_pk_mul_f32 v[82:83], v[90:91], v[98:99] op_sel_hi:[1,0]
	v_pk_mul_f32 v[76:77], v[92:93], v[98:99] op_sel_hi:[1,0]
	v_pk_mul_f32 v[78:79], v[88:89], v[98:99] op_sel_hi:[1,0]
	v_pk_fma_f32 v[76:77], v[74:75], v[76:77], v[28:29]
	v_pk_fma_f32 v[78:79], v[72:73], v[78:79], v[30:31]
	v_pk_fma_f32 v[82:83], v[68:69], v[82:83], v[26:27]
	v_pk_fma_f32 v[80:81], v[70:71], v[80:81], v[24:25]
	v_cvt_pk_bf16_f32 v76, v76, v77
	v_cvt_pk_bf16_f32 v77, v78, v79
	v_cvt_pk_bf16_f32 v78, v80, v81
	v_cvt_pk_bf16_f32 v79, v82, v83
	global_store_dwordx4 v[96:97], v[76:79], off offset:3072
	s_waitcnt vmcnt(11)
	v_lshlrev_b32_e32 v97, 16, v179
	v_lshlrev_b32_e32 v96, 16, v178
	v_and_b32_e32 v77, 0xffff0000, v179
	v_and_b32_e32 v76, 0xffff0000, v178
	v_lshlrev_b32_e32 v101, 16, v181
	v_lshlrev_b32_e32 v100, 16, v180
	v_and_b32_e32 v79, 0xffff0000, v181
	v_and_b32_e32 v78, 0xffff0000, v180
	v_pk_mul_f32 v[98:99], v[76:77], v[76:77]
	v_pk_mul_f32 v[102:103], v[78:79], v[78:79]
	s_waitcnt vmcnt(8)
	v_lshlrev_b32_e32 v92, 16, v190
	v_and_b32_e32 v93, 0xffff0000, v190
	v_pk_fma_f32 v[98:99], v[96:97], v[96:97], v[98:99]
	v_pk_fma_f32 v[102:103], v[100:101], v[100:101], v[102:103]
	v_lshlrev_b32_e32 v105, 16, v183
	v_lshlrev_b32_e32 v104, 16, v182
	v_and_b32_e32 v81, 0xffff0000, v183
	v_and_b32_e32 v80, 0xffff0000, v182
	v_lshlrev_b32_e32 v109, 16, v185
	v_lshlrev_b32_e32 v108, 16, v184
	v_and_b32_e32 v83, 0xffff0000, v185
	v_and_b32_e32 v82, 0xffff0000, v184
	v_pk_mul_f32 v[106:107], v[80:81], v[80:81]
	v_pk_mul_f32 v[110:111], v[82:83], v[82:83]
	v_mul_f32_e32 v116, v92, v92
	v_mul_f32_e32 v117, v93, v93
	v_pk_add_f32 v[98:99], v[98:99], v[98:99] op_sel:[0,1] op_sel_hi:[1,0]
	v_pk_add_f32 v[102:103], v[102:103], v[102:103] op_sel:[0,1] op_sel_hi:[1,0]
	v_lshlrev_b32_e32 v88, 16, v191
	v_and_b32_e32 v89, 0xffff0000, v191
	v_pk_fma_f32 v[106:107], v[104:105], v[104:105], v[106:107]
	v_pk_fma_f32 v[110:111], v[108:109], v[108:109], v[110:111]
	v_mov_b32_e32 v99, v116
	v_mov_b32_e32 v103, v117
	v_mul_f32_e32 v118, v88, v88
	v_mul_f32_e32 v119, v89, v89
	v_pk_add_f32 v[98:99], v[98:99], v[102:103]
	v_pk_add_f32 v[102:103], v[106:107], v[106:107] op_sel:[0,1] op_sel_hi:[1,0]
	v_pk_add_f32 v[106:107], v[110:111], v[110:111] op_sel:[0,1] op_sel_hi:[1,0]
	v_mov_b32_e32 v103, v118
	v_mov_b32_e32 v107, v119
	v_lshlrev_b32_e32 v112, 16, v186
	v_and_b32_e32 v113, 0xffff0000, v186
	v_lshlrev_b32_e32 v84, 16, v187
	v_and_b32_e32 v85, 0xffff0000, v187
	v_pk_add_f32 v[102:103], v[102:103], v[106:107]
	v_lshlrev_b32_e32 v94, 16, v192
	v_and_b32_e32 v95, 0xffff0000, v192
	v_pk_add_f32 v[98:99], v[98:99], v[102:103]
	v_mul_f32_e32 v102, v113, v113
	v_mul_f32_e32 v106, v85, v85
	v_mul_f32_e32 v120, v94, v94
	v_mul_f32_e32 v121, v95, v95
	v_pk_fma_f32 v[102:103], v[112:113], v[112:113], v[102:103] op_sel_hi:[1,1,0]
	v_pk_fma_f32 v[106:107], v[84:85], v[84:85], v[106:107] op_sel_hi:[1,1,0]
	v_lshlrev_b32_e32 v114, 16, v188
	v_and_b32_e32 v115, 0xffff0000, v188
	v_lshlrev_b32_e32 v86, 16, v189
	v_and_b32_e32 v87, 0xffff0000, v189
	v_mov_b32_e32 v103, v120
	v_mov_b32_e32 v107, v121
	v_lshlrev_b32_e32 v90, 16, v193
	v_and_b32_e32 v91, 0xffff0000, v193
	s_add_i32 s100, s4, -1
	s_ashr_i32 s101, s100, 31
	s_lshl_b64 s[100:101], s[100:101], 12
	v_lshl_add_u64 v[210:211], v[32:33], 0, s[100:101]
	s_nop 0
	global_load_dwordx4 v[178:181], v[210:211], off
	global_load_dwordx4 v[182:185], v[210:211], off offset:1024
	global_load_dwordx4 v[186:189], v[210:211], off offset:2048
	global_load_dwordx4 v[190:193], v[210:211], off offset:3072
	v_pk_add_f32 v[102:103], v[102:103], v[106:107]
	v_mul_f32_e32 v106, v115, v115
	v_mul_f32_e32 v110, v87, v87
	v_mul_f32_e32 v122, v90, v90
	v_mul_f32_e32 v123, v91, v91
	v_pk_fma_f32 v[106:107], v[114:115], v[114:115], v[106:107] op_sel_hi:[1,1,0]
	v_pk_fma_f32 v[110:111], v[86:87], v[86:87], v[110:111] op_sel_hi:[1,1,0]
	v_mov_b32_e32 v107, v122
	v_mov_b32_e32 v111, v123
	v_pk_add_f32 v[106:107], v[106:107], v[110:111]
	s_nop 0
	v_pk_add_f32 v[102:103], v[102:103], v[106:107]
	s_nop 0
	v_pk_add_f32 v[98:99], v[98:99], v[102:103]
	s_nop 0
	v_add_f32_e32 v98, v98, v99
	v_mbcnt_lo_u32_b32 v99, -1, 0
	v_mbcnt_hi_u32_b32 v99, -1, v99
	s_nop 0
	v_lshlrev_b32_e32 v99, 2, v99
	v_xor_b32_e32 v99, 4, v99
	ds_bpermute_b32 v99, v99, v98
	s_waitcnt lgkmcnt(0)
	v_add_f32_e32 v98, v98, v99
	v_mbcnt_lo_u32_b32 v99, -1, 0
	v_mbcnt_hi_u32_b32 v99, -1, v99
	s_nop 0
	v_lshlrev_b32_e32 v99, 2, v99
	v_xor_b32_e32 v99, 8, v99
	ds_bpermute_b32 v99, v99, v98
	s_waitcnt lgkmcnt(0)
	v_add_f32_e32 v98, v98, v99
	v_mbcnt_lo_u32_b32 v99, -1, 0
	v_mbcnt_hi_u32_b32 v99, -1, v99
	s_nop 0
	v_lshlrev_b32_e32 v99, 2, v99
	v_xor_b32_e32 v99, 16, v99
	ds_bpermute_b32 v99, v99, v98
	s_waitcnt lgkmcnt(0)
	v_add_f32_e32 v98, v98, v99
	v_mbcnt_lo_u32_b32 v99, -1, 0
	v_mbcnt_hi_u32_b32 v99, -1, v99
	s_nop 0
	v_lshlrev_b32_e32 v99, 2, v99
	v_xor_b32_e32 v99, 32, v99
	ds_bpermute_b32 v99, v99, v98
	s_waitcnt lgkmcnt(0)
	v_add_f32_e32 v98, v98, v99
	v_mbcnt_lo_u32_b32 v99, -1, 0
	v_mbcnt_hi_u32_b32 v99, -1, v99
	s_nop 0
	v_lshlrev_b32_e32 v99, 2, v99
	v_xor_b32_e32 v99, 64, v99
	ds_bpermute_b32 v99, v99, v98
	s_waitcnt lgkmcnt(0)
	v_add_f32_e32 v98, v98, v99
	v_mbcnt_lo_u32_b32 v99, -1, 0
	v_mbcnt_hi_u32_b32 v99, -1, v99
	s_nop 0
	v_lshlrev_b32_e32 v99, 2, v99
	v_xor_b32_e32 v99, 0x80, v99
	ds_bpermute_b32 v99, v99, v98
	s_waitcnt lgkmcnt(0)
	v_add_f32_e32 v98, v98, v99
	v_fmamk_f32 v98, v98, 0x3a000000, v224
	v_cmp_gt_f32_e32 vcc, s41, v98
	v_mul_f32_e32 v99, 0x4f800000, v98
	s_nop 0
	v_cndmask_b32_e32 v98, v98, v99, vcc
	v_sqrt_f32_e32 v99, v98
	s_nop 0
	v_add_u32_e32 v102, -1, v99
	v_fma_f32 v103, -v102, v99, v98
	v_cmp_ge_f32_e64 s[0:1], 0, v103
	v_add_u32_e32 v103, 1, v99
	s_nop 0
	v_cndmask_b32_e64 v102, v99, v102, s[0:1]
	v_fma_f32 v99, -v103, v99, v98
	v_cmp_lt_f32_e64 s[0:1], 0, v99
	s_nop 1
	v_cndmask_b32_e64 v99, v102, v103, s[0:1]
	v_mul_f32_e32 v102, 0x37800000, v99
	v_cndmask_b32_e32 v99, v99, v102, vcc
	v_cmp_class_f32_e32 vcc, v98, v225
	s_nop 1
	v_cndmask_b32_e32 v98, v99, v98, vcc
	v_div_scale_f32 v99, s[0:1], v98, v98, 1.0
	v_rcp_f32_e32 v102, v99
	s_add_i32 s0, s4, -2
	s_ashr_i32 s1, s0, 31
	v_fma_f32 v103, -v99, v102, 1.0
	v_fmac_f32_e32 v102, v103, v102
	v_div_scale_f32 v103, vcc, 1.0, v98, 1.0
	v_mul_f32_e32 v106, v103, v102
	v_fma_f32 v107, -v99, v106, v103
	v_fmac_f32_e32 v106, v107, v102
	v_fma_f32 v99, -v99, v106, v103
	v_div_fmas_f32 v99, v99, v102, v106
	v_div_fixup_f32 v98, v99, v98, 1.0
	v_mov_b32_e32 v102, v96
	v_mov_b32_e32 v103, v76
	v_mov_b32_e32 v76, v97
	v_pk_mul_f32 v[102:103], v[98:99], v[102:103] op_sel_hi:[0,1]
	v_pk_mul_f32 v[76:77], v[98:99], v[76:77] op_sel_hi:[0,1]
	v_pk_fma_f32 v[96:97], v[48:49], v[76:77], v[6:7]
	v_pk_fma_f32 v[76:77], v[50:51], v[102:103], v[4:5]
	v_mov_b32_e32 v102, v100
	v_mov_b32_e32 v103, v78
	v_mov_b32_e32 v78, v101
	v_pk_mul_f32 v[102:103], v[98:99], v[102:103] op_sel_hi:[0,1]
	v_pk_mul_f32 v[78:79], v[98:99], v[78:79] op_sel_hi:[0,1]
	v_pk_fma_f32 v[100:101], v[44:45], v[78:79], v[2:3]
	v_pk_fma_f32 v[78:79], v[46:47], v[102:103], v[0:1]
	v_cvt_pk_bf16_f32 v76, v76, v77
	v_cvt_pk_bf16_f32 v77, v96, v97
	v_cvt_pk_bf16_f32 v78, v78, v79
	v_cvt_pk_bf16_f32 v79, v100, v101
	v_lshl_add_u64 v[96:97], v[34:35], 0, s[60:61]
	global_store_dwordx4 v[96:97], v[76:79], off
	s_lshl_b64 s[60:61], s[0:1], 12
	s_nop 0
	v_mov_b32_e32 v77, v80
	v_mov_b32_e32 v80, v105
	v_mov_b32_e32 v76, v104
	v_pk_mul_f32 v[78:79], v[98:99], v[80:81] op_sel_hi:[0,1]
	v_mov_b32_e32 v80, v108
	v_mov_b32_e32 v81, v82
	v_mov_b32_e32 v82, v109
	v_pk_mul_f32 v[76:77], v[98:99], v[76:77] op_sel_hi:[0,1]
	v_pk_mul_f32 v[80:81], v[98:99], v[80:81] op_sel_hi:[0,1]
	v_pk_mul_f32 v[82:83], v[98:99], v[82:83] op_sel_hi:[0,1]
	v_pk_fma_f32 v[78:79], v[56:57], v[78:79], v[14:15]
	v_pk_fma_f32 v[76:77], v[58:59], v[76:77], v[12:13]
	v_pk_fma_f32 v[82:83], v[52:53], v[82:83], v[10:11]
	v_pk_fma_f32 v[80:81], v[54:55], v[80:81], v[8:9]
	v_cvt_pk_bf16_f32 v76, v76, v77
	v_cvt_pk_bf16_f32 v77, v78, v79
	v_cvt_pk_bf16_f32 v78, v80, v81
	v_cvt_pk_bf16_f32 v79, v82, v83
	global_store_dwordx4 v[96:97], v[76:79], off offset:1024
	v_pk_mul_f32 v[80:81], v[98:99], v[114:115] op_sel_hi:[0,1]
	v_pk_mul_f32 v[82:83], v[98:99], v[86:87] op_sel_hi:[0,1]
	v_pk_mul_f32 v[76:77], v[98:99], v[112:113] op_sel_hi:[0,1]
	v_pk_mul_f32 v[78:79], v[98:99], v[84:85] op_sel_hi:[0,1]
	v_pk_fma_f32 v[78:79], v[64:65], v[78:79], v[22:23]
	v_pk_fma_f32 v[76:77], v[66:67], v[76:77], v[20:21]
	v_pk_fma_f32 v[82:83], v[60:61], v[82:83], v[18:19]
	v_pk_fma_f32 v[80:81], v[62:63], v[80:81], v[16:17]
	v_cvt_pk_bf16_f32 v76, v76, v77
	v_cvt_pk_bf16_f32 v77, v78, v79
	v_cvt_pk_bf16_f32 v78, v80, v81
	v_cvt_pk_bf16_f32 v79, v82, v83
	global_store_dwordx4 v[96:97], v[76:79], off offset:2048
	v_pk_mul_f32 v[80:81], v[94:95], v[98:99] op_sel_hi:[1,0]
	v_pk_mul_f32 v[82:83], v[90:91], v[98:99] op_sel_hi:[1,0]
	v_pk_mul_f32 v[76:77], v[92:93], v[98:99] op_sel_hi:[1,0]
	v_pk_mul_f32 v[78:79], v[88:89], v[98:99] op_sel_hi:[1,0]
	v_pk_fma_f32 v[76:77], v[74:75], v[76:77], v[28:29]
	v_pk_fma_f32 v[78:79], v[72:73], v[78:79], v[30:31]
	v_pk_fma_f32 v[82:83], v[68:69], v[82:83], v[26:27]
	v_pk_fma_f32 v[80:81], v[70:71], v[80:81], v[24:25]
	v_cvt_pk_bf16_f32 v76, v76, v77
	v_cvt_pk_bf16_f32 v77, v78, v79
	v_cvt_pk_bf16_f32 v78, v80, v81
	v_cvt_pk_bf16_f32 v79, v82, v83
	global_store_dwordx4 v[96:97], v[76:79], off offset:3072
	s_waitcnt vmcnt(11)
	v_lshlrev_b32_e32 v97, 16, v195
	v_lshlrev_b32_e32 v96, 16, v194
	v_and_b32_e32 v77, 0xffff0000, v195
	v_and_b32_e32 v76, 0xffff0000, v194
	v_lshlrev_b32_e32 v101, 16, v197
	v_lshlrev_b32_e32 v100, 16, v196
	v_and_b32_e32 v79, 0xffff0000, v197
	v_and_b32_e32 v78, 0xffff0000, v196
	v_pk_mul_f32 v[98:99], v[76:77], v[76:77]
	v_pk_mul_f32 v[102:103], v[78:79], v[78:79]
	s_waitcnt vmcnt(8)
	v_lshlrev_b32_e32 v92, 16, v206
	v_and_b32_e32 v93, 0xffff0000, v206
	v_pk_fma_f32 v[98:99], v[96:97], v[96:97], v[98:99]
	v_pk_fma_f32 v[102:103], v[100:101], v[100:101], v[102:103]
	v_lshlrev_b32_e32 v105, 16, v199
	v_lshlrev_b32_e32 v104, 16, v198
	v_and_b32_e32 v81, 0xffff0000, v199
	v_and_b32_e32 v80, 0xffff0000, v198
	v_lshlrev_b32_e32 v109, 16, v201
	v_lshlrev_b32_e32 v108, 16, v200
	v_and_b32_e32 v83, 0xffff0000, v201
	v_and_b32_e32 v82, 0xffff0000, v200
	v_pk_mul_f32 v[106:107], v[80:81], v[80:81]
	v_pk_mul_f32 v[110:111], v[82:83], v[82:83]
	v_mul_f32_e32 v116, v92, v92
	v_mul_f32_e32 v117, v93, v93
	v_pk_add_f32 v[98:99], v[98:99], v[98:99] op_sel:[0,1] op_sel_hi:[1,0]
	v_pk_add_f32 v[102:103], v[102:103], v[102:103] op_sel:[0,1] op_sel_hi:[1,0]
	v_lshlrev_b32_e32 v88, 16, v207
	v_and_b32_e32 v89, 0xffff0000, v207
	v_pk_fma_f32 v[106:107], v[104:105], v[104:105], v[106:107]
	v_pk_fma_f32 v[110:111], v[108:109], v[108:109], v[110:111]
	v_mov_b32_e32 v99, v116
	v_mov_b32_e32 v103, v117
	v_mul_f32_e32 v118, v88, v88
	v_mul_f32_e32 v119, v89, v89
	v_pk_add_f32 v[98:99], v[98:99], v[102:103]
	v_pk_add_f32 v[102:103], v[106:107], v[106:107] op_sel:[0,1] op_sel_hi:[1,0]
	v_pk_add_f32 v[106:107], v[110:111], v[110:111] op_sel:[0,1] op_sel_hi:[1,0]
	v_mov_b32_e32 v103, v118
	v_mov_b32_e32 v107, v119
	v_lshlrev_b32_e32 v112, 16, v202
	v_and_b32_e32 v113, 0xffff0000, v202
	v_lshlrev_b32_e32 v84, 16, v203
	v_and_b32_e32 v85, 0xffff0000, v203
	v_pk_add_f32 v[102:103], v[102:103], v[106:107]
	v_lshlrev_b32_e32 v94, 16, v208
	v_and_b32_e32 v95, 0xffff0000, v208
	v_pk_add_f32 v[98:99], v[98:99], v[102:103]
	v_mul_f32_e32 v102, v113, v113
	v_mul_f32_e32 v106, v85, v85
	v_mul_f32_e32 v120, v94, v94
	v_mul_f32_e32 v121, v95, v95
	v_pk_fma_f32 v[102:103], v[112:113], v[112:113], v[102:103] op_sel_hi:[1,1,0]
	v_pk_fma_f32 v[106:107], v[84:85], v[84:85], v[106:107] op_sel_hi:[1,1,0]
	v_lshlrev_b32_e32 v114, 16, v204
	v_and_b32_e32 v115, 0xffff0000, v204
	v_lshlrev_b32_e32 v86, 16, v205
	v_and_b32_e32 v87, 0xffff0000, v205
	v_mov_b32_e32 v103, v120
	v_mov_b32_e32 v107, v121
	v_lshlrev_b32_e32 v90, 16, v209
	v_and_b32_e32 v91, 0xffff0000, v209
	s_add_i32 s100, s4, 0
	s_ashr_i32 s101, s100, 31
	s_lshl_b64 s[100:101], s[100:101], 12
	v_lshl_add_u64 v[210:211], v[32:33], 0, s[100:101]
	s_nop 0
	global_load_dwordx4 v[194:197], v[210:211], off
	global_load_dwordx4 v[198:201], v[210:211], off offset:1024
	global_load_dwordx4 v[202:205], v[210:211], off offset:2048
	global_load_dwordx4 v[206:209], v[210:211], off offset:3072
	v_pk_add_f32 v[102:103], v[102:103], v[106:107]
	v_mul_f32_e32 v106, v115, v115
	v_mul_f32_e32 v110, v87, v87
	v_mul_f32_e32 v122, v90, v90
	v_mul_f32_e32 v123, v91, v91
	v_pk_fma_f32 v[106:107], v[114:115], v[114:115], v[106:107] op_sel_hi:[1,1,0]
	v_pk_fma_f32 v[110:111], v[86:87], v[86:87], v[110:111] op_sel_hi:[1,1,0]
	v_mov_b32_e32 v107, v122
	v_mov_b32_e32 v111, v123
	v_pk_add_f32 v[106:107], v[106:107], v[110:111]
	s_nop 0
	v_pk_add_f32 v[102:103], v[102:103], v[106:107]
	s_nop 0
	v_pk_add_f32 v[98:99], v[98:99], v[102:103]
	s_nop 0
	v_add_f32_e32 v98, v98, v99
	v_mbcnt_lo_u32_b32 v99, -1, 0
	v_mbcnt_hi_u32_b32 v99, -1, v99
	s_nop 0
	v_lshlrev_b32_e32 v99, 2, v99
	v_xor_b32_e32 v99, 4, v99
	ds_bpermute_b32 v99, v99, v98
	s_waitcnt lgkmcnt(0)
	v_add_f32_e32 v98, v98, v99
	v_mbcnt_lo_u32_b32 v99, -1, 0
	v_mbcnt_hi_u32_b32 v99, -1, v99
	s_nop 0
	v_lshlrev_b32_e32 v99, 2, v99
	v_xor_b32_e32 v99, 8, v99
	ds_bpermute_b32 v99, v99, v98
	s_waitcnt lgkmcnt(0)
	v_add_f32_e32 v98, v98, v99
	v_mbcnt_lo_u32_b32 v99, -1, 0
	v_mbcnt_hi_u32_b32 v99, -1, v99
	s_nop 0
	v_lshlrev_b32_e32 v99, 2, v99
	v_xor_b32_e32 v99, 16, v99
	ds_bpermute_b32 v99, v99, v98
	s_waitcnt lgkmcnt(0)
	v_add_f32_e32 v98, v98, v99
	v_mbcnt_lo_u32_b32 v99, -1, 0
	v_mbcnt_hi_u32_b32 v99, -1, v99
	s_nop 0
	v_lshlrev_b32_e32 v99, 2, v99
	v_xor_b32_e32 v99, 32, v99
	ds_bpermute_b32 v99, v99, v98
	s_waitcnt lgkmcnt(0)
	v_add_f32_e32 v98, v98, v99
	v_mbcnt_lo_u32_b32 v99, -1, 0
	v_mbcnt_hi_u32_b32 v99, -1, v99
	s_nop 0
	v_lshlrev_b32_e32 v99, 2, v99
	v_xor_b32_e32 v99, 64, v99
	ds_bpermute_b32 v99, v99, v98
	s_waitcnt lgkmcnt(0)
	v_add_f32_e32 v98, v98, v99
	v_mbcnt_lo_u32_b32 v99, -1, 0
	v_mbcnt_hi_u32_b32 v99, -1, v99
	s_nop 0
	v_lshlrev_b32_e32 v99, 2, v99
	v_xor_b32_e32 v99, 0x80, v99
	ds_bpermute_b32 v99, v99, v98
	s_waitcnt lgkmcnt(0)
	v_add_f32_e32 v98, v98, v99
	v_fmamk_f32 v98, v98, 0x3a000000, v224
	v_cmp_gt_f32_e32 vcc, s41, v98
	v_mul_f32_e32 v99, 0x4f800000, v98
	s_nop 0
	v_cndmask_b32_e32 v98, v98, v99, vcc
	v_sqrt_f32_e32 v99, v98
	s_nop 0
	v_add_u32_e32 v102, -1, v99
	v_fma_f32 v103, -v102, v99, v98
	v_cmp_ge_f32_e64 s[0:1], 0, v103
	v_add_u32_e32 v103, 1, v99
	s_nop 0
	v_cndmask_b32_e64 v102, v99, v102, s[0:1]
	v_fma_f32 v99, -v103, v99, v98
	v_cmp_lt_f32_e64 s[0:1], 0, v99
	s_nop 1
	v_cndmask_b32_e64 v99, v102, v103, s[0:1]
	v_mul_f32_e32 v102, 0x37800000, v99
	v_cndmask_b32_e32 v99, v99, v102, vcc
	v_cmp_class_f32_e32 vcc, v98, v225
	s_nop 1
	v_cndmask_b32_e32 v98, v99, v98, vcc
	v_div_scale_f32 v99, s[0:1], v98, v98, 1.0
	v_rcp_f32_e32 v102, v99
	s_add_i32 s0, s4, -1
	s_ashr_i32 s1, s0, 31
	v_fma_f32 v103, -v99, v102, 1.0
	v_fmac_f32_e32 v102, v103, v102
	v_div_scale_f32 v103, vcc, 1.0, v98, 1.0
	v_mul_f32_e32 v106, v103, v102
	v_fma_f32 v107, -v99, v106, v103
	v_fmac_f32_e32 v106, v107, v102
	v_fma_f32 v99, -v99, v106, v103
	v_div_fmas_f32 v99, v99, v102, v106
	v_div_fixup_f32 v98, v99, v98, 1.0
	v_mov_b32_e32 v102, v96
	v_mov_b32_e32 v103, v76
	v_mov_b32_e32 v76, v97
	v_pk_mul_f32 v[102:103], v[98:99], v[102:103] op_sel_hi:[0,1]
	v_pk_mul_f32 v[76:77], v[98:99], v[76:77] op_sel_hi:[0,1]
	v_pk_fma_f32 v[96:97], v[48:49], v[76:77], v[6:7]
	v_pk_fma_f32 v[76:77], v[50:51], v[102:103], v[4:5]
	v_mov_b32_e32 v102, v100
	v_mov_b32_e32 v103, v78
	v_mov_b32_e32 v78, v101
	v_pk_mul_f32 v[102:103], v[98:99], v[102:103] op_sel_hi:[0,1]
	v_pk_mul_f32 v[78:79], v[98:99], v[78:79] op_sel_hi:[0,1]
	v_pk_fma_f32 v[100:101], v[44:45], v[78:79], v[2:3]
	v_pk_fma_f32 v[78:79], v[46:47], v[102:103], v[0:1]
	v_cvt_pk_bf16_f32 v76, v76, v77
	v_cvt_pk_bf16_f32 v77, v96, v97
	v_cvt_pk_bf16_f32 v78, v78, v79
	v_cvt_pk_bf16_f32 v79, v100, v101
	v_lshl_add_u64 v[96:97], v[34:35], 0, s[60:61]
	global_store_dwordx4 v[96:97], v[76:79], off
	s_lshl_b64 s[60:61], s[0:1], 12
	s_nop 0
	v_mov_b32_e32 v77, v80
	v_mov_b32_e32 v80, v105
	v_mov_b32_e32 v76, v104
	v_pk_mul_f32 v[78:79], v[98:99], v[80:81] op_sel_hi:[0,1]
	v_mov_b32_e32 v80, v108
	v_mov_b32_e32 v81, v82
	v_mov_b32_e32 v82, v109
	v_pk_mul_f32 v[76:77], v[98:99], v[76:77] op_sel_hi:[0,1]
	v_pk_mul_f32 v[80:81], v[98:99], v[80:81] op_sel_hi:[0,1]
	v_pk_mul_f32 v[82:83], v[98:99], v[82:83] op_sel_hi:[0,1]
	v_pk_fma_f32 v[78:79], v[56:57], v[78:79], v[14:15]
	v_pk_fma_f32 v[76:77], v[58:59], v[76:77], v[12:13]
	v_pk_fma_f32 v[82:83], v[52:53], v[82:83], v[10:11]
	v_pk_fma_f32 v[80:81], v[54:55], v[80:81], v[8:9]
	v_cvt_pk_bf16_f32 v76, v76, v77
	v_cvt_pk_bf16_f32 v77, v78, v79
	v_cvt_pk_bf16_f32 v78, v80, v81
	v_cvt_pk_bf16_f32 v79, v82, v83
	global_store_dwordx4 v[96:97], v[76:79], off offset:1024
	v_pk_mul_f32 v[80:81], v[98:99], v[114:115] op_sel_hi:[0,1]
	v_pk_mul_f32 v[82:83], v[98:99], v[86:87] op_sel_hi:[0,1]
	v_pk_mul_f32 v[76:77], v[98:99], v[112:113] op_sel_hi:[0,1]
	v_pk_mul_f32 v[78:79], v[98:99], v[84:85] op_sel_hi:[0,1]
	v_pk_fma_f32 v[78:79], v[64:65], v[78:79], v[22:23]
	v_pk_fma_f32 v[76:77], v[66:67], v[76:77], v[20:21]
	v_pk_fma_f32 v[82:83], v[60:61], v[82:83], v[18:19]
	v_pk_fma_f32 v[80:81], v[62:63], v[80:81], v[16:17]
	v_cvt_pk_bf16_f32 v76, v76, v77
	v_cvt_pk_bf16_f32 v77, v78, v79
	v_cvt_pk_bf16_f32 v78, v80, v81
	v_cvt_pk_bf16_f32 v79, v82, v83
	global_store_dwordx4 v[96:97], v[76:79], off offset:2048
	v_pk_mul_f32 v[80:81], v[94:95], v[98:99] op_sel_hi:[1,0]
	v_pk_mul_f32 v[82:83], v[90:91], v[98:99] op_sel_hi:[1,0]
	v_pk_mul_f32 v[76:77], v[92:93], v[98:99] op_sel_hi:[1,0]
	v_pk_mul_f32 v[78:79], v[88:89], v[98:99] op_sel_hi:[1,0]
	v_pk_fma_f32 v[76:77], v[74:75], v[76:77], v[28:29]
	v_pk_fma_f32 v[78:79], v[72:73], v[78:79], v[30:31]
	v_pk_fma_f32 v[82:83], v[68:69], v[82:83], v[26:27]
	v_pk_fma_f32 v[80:81], v[70:71], v[80:81], v[24:25]
	v_cvt_pk_bf16_f32 v76, v76, v77
	v_cvt_pk_bf16_f32 v77, v78, v79
	v_cvt_pk_bf16_f32 v78, v80, v81
	v_cvt_pk_bf16_f32 v79, v82, v83
	global_store_dwordx4 v[96:97], v[76:79], off offset:3072
	s_waitcnt vmcnt(11)
	v_lshlrev_b32_e32 v97, 16, v179
	v_lshlrev_b32_e32 v96, 16, v178
	v_and_b32_e32 v77, 0xffff0000, v179
	v_and_b32_e32 v76, 0xffff0000, v178
	v_lshlrev_b32_e32 v101, 16, v181
	v_lshlrev_b32_e32 v100, 16, v180
	v_and_b32_e32 v79, 0xffff0000, v181
	v_and_b32_e32 v78, 0xffff0000, v180
	v_pk_mul_f32 v[98:99], v[76:77], v[76:77]
	v_pk_mul_f32 v[102:103], v[78:79], v[78:79]
	s_waitcnt vmcnt(8)
	v_lshlrev_b32_e32 v92, 16, v190
	v_and_b32_e32 v93, 0xffff0000, v190
	v_pk_fma_f32 v[98:99], v[96:97], v[96:97], v[98:99]
	v_pk_fma_f32 v[102:103], v[100:101], v[100:101], v[102:103]
	v_lshlrev_b32_e32 v105, 16, v183
	v_lshlrev_b32_e32 v104, 16, v182
	v_and_b32_e32 v81, 0xffff0000, v183
	v_and_b32_e32 v80, 0xffff0000, v182
	v_lshlrev_b32_e32 v109, 16, v185
	v_lshlrev_b32_e32 v108, 16, v184
	v_and_b32_e32 v83, 0xffff0000, v185
	v_and_b32_e32 v82, 0xffff0000, v184
	v_pk_mul_f32 v[106:107], v[80:81], v[80:81]
	v_pk_mul_f32 v[110:111], v[82:83], v[82:83]
	v_mul_f32_e32 v116, v92, v92
	v_mul_f32_e32 v117, v93, v93
	v_pk_add_f32 v[98:99], v[98:99], v[98:99] op_sel:[0,1] op_sel_hi:[1,0]
	v_pk_add_f32 v[102:103], v[102:103], v[102:103] op_sel:[0,1] op_sel_hi:[1,0]
	v_lshlrev_b32_e32 v88, 16, v191
	v_and_b32_e32 v89, 0xffff0000, v191
	v_pk_fma_f32 v[106:107], v[104:105], v[104:105], v[106:107]
	v_pk_fma_f32 v[110:111], v[108:109], v[108:109], v[110:111]
	v_mov_b32_e32 v99, v116
	v_mov_b32_e32 v103, v117
	v_mul_f32_e32 v118, v88, v88
	v_mul_f32_e32 v119, v89, v89
	v_pk_add_f32 v[98:99], v[98:99], v[102:103]
	v_pk_add_f32 v[102:103], v[106:107], v[106:107] op_sel:[0,1] op_sel_hi:[1,0]
	v_pk_add_f32 v[106:107], v[110:111], v[110:111] op_sel:[0,1] op_sel_hi:[1,0]
	v_mov_b32_e32 v103, v118
	v_mov_b32_e32 v107, v119
	v_lshlrev_b32_e32 v112, 16, v186
	v_and_b32_e32 v113, 0xffff0000, v186
	v_lshlrev_b32_e32 v84, 16, v187
	v_and_b32_e32 v85, 0xffff0000, v187
	v_pk_add_f32 v[102:103], v[102:103], v[106:107]
	v_lshlrev_b32_e32 v94, 16, v192
	v_and_b32_e32 v95, 0xffff0000, v192
	v_pk_add_f32 v[98:99], v[98:99], v[102:103]
	v_mul_f32_e32 v102, v113, v113
	v_mul_f32_e32 v106, v85, v85
	v_mul_f32_e32 v120, v94, v94
	v_mul_f32_e32 v121, v95, v95
	v_pk_fma_f32 v[102:103], v[112:113], v[112:113], v[102:103] op_sel_hi:[1,1,0]
	v_pk_fma_f32 v[106:107], v[84:85], v[84:85], v[106:107] op_sel_hi:[1,1,0]
	v_lshlrev_b32_e32 v114, 16, v188
	v_and_b32_e32 v115, 0xffff0000, v188
	v_lshlrev_b32_e32 v86, 16, v189
	v_and_b32_e32 v87, 0xffff0000, v189
	v_mov_b32_e32 v103, v120
	v_mov_b32_e32 v107, v121
	v_lshlrev_b32_e32 v90, 16, v193
	v_and_b32_e32 v91, 0xffff0000, v193
	v_pk_add_f32 v[102:103], v[102:103], v[106:107]
	v_mul_f32_e32 v106, v115, v115
	v_mul_f32_e32 v110, v87, v87
	v_mul_f32_e32 v122, v90, v90
	v_mul_f32_e32 v123, v91, v91
	v_pk_fma_f32 v[106:107], v[114:115], v[114:115], v[106:107] op_sel_hi:[1,1,0]
	v_pk_fma_f32 v[110:111], v[86:87], v[86:87], v[110:111] op_sel_hi:[1,1,0]
	v_mov_b32_e32 v107, v122
	v_mov_b32_e32 v111, v123
	v_pk_add_f32 v[106:107], v[106:107], v[110:111]
	s_nop 0
	v_pk_add_f32 v[102:103], v[102:103], v[106:107]
	s_nop 0
	v_pk_add_f32 v[98:99], v[98:99], v[102:103]
	s_nop 0
	v_add_f32_e32 v98, v98, v99
	v_mbcnt_lo_u32_b32 v99, -1, 0
	v_mbcnt_hi_u32_b32 v99, -1, v99
	s_nop 0
	v_lshlrev_b32_e32 v99, 2, v99
	v_xor_b32_e32 v99, 4, v99
	ds_bpermute_b32 v99, v99, v98
	s_waitcnt lgkmcnt(0)
	v_add_f32_e32 v98, v98, v99
	v_mbcnt_lo_u32_b32 v99, -1, 0
	v_mbcnt_hi_u32_b32 v99, -1, v99
	s_nop 0
	v_lshlrev_b32_e32 v99, 2, v99
	v_xor_b32_e32 v99, 8, v99
	ds_bpermute_b32 v99, v99, v98
	s_waitcnt lgkmcnt(0)
	v_add_f32_e32 v98, v98, v99
	v_mbcnt_lo_u32_b32 v99, -1, 0
	v_mbcnt_hi_u32_b32 v99, -1, v99
	s_nop 0
	v_lshlrev_b32_e32 v99, 2, v99
	v_xor_b32_e32 v99, 16, v99
	ds_bpermute_b32 v99, v99, v98
	s_waitcnt lgkmcnt(0)
	v_add_f32_e32 v98, v98, v99
	v_mbcnt_lo_u32_b32 v99, -1, 0
	v_mbcnt_hi_u32_b32 v99, -1, v99
	s_nop 0
	v_lshlrev_b32_e32 v99, 2, v99
	v_xor_b32_e32 v99, 32, v99
	ds_bpermute_b32 v99, v99, v98
	s_waitcnt lgkmcnt(0)
	v_add_f32_e32 v98, v98, v99
	v_mbcnt_lo_u32_b32 v99, -1, 0
	v_mbcnt_hi_u32_b32 v99, -1, v99
	s_nop 0
	v_lshlrev_b32_e32 v99, 2, v99
	v_xor_b32_e32 v99, 64, v99
	ds_bpermute_b32 v99, v99, v98
	s_waitcnt lgkmcnt(0)
	v_add_f32_e32 v98, v98, v99
	v_mbcnt_lo_u32_b32 v99, -1, 0
	v_mbcnt_hi_u32_b32 v99, -1, v99
	s_nop 0
	v_lshlrev_b32_e32 v99, 2, v99
	v_xor_b32_e32 v99, 0x80, v99
	ds_bpermute_b32 v99, v99, v98
	s_waitcnt lgkmcnt(0)
	v_add_f32_e32 v98, v98, v99
	v_fmamk_f32 v98, v98, 0x3a000000, v224
	v_cmp_gt_f32_e32 vcc, s41, v98
	v_mul_f32_e32 v99, 0x4f800000, v98
	s_nop 0
	v_cndmask_b32_e32 v98, v98, v99, vcc
	v_sqrt_f32_e32 v99, v98
	s_nop 0
	v_add_u32_e32 v102, -1, v99
	v_fma_f32 v103, -v102, v99, v98
	v_cmp_ge_f32_e64 s[0:1], 0, v103
	v_add_u32_e32 v103, 1, v99
	s_nop 0
	v_cndmask_b32_e64 v102, v99, v102, s[0:1]
	v_fma_f32 v99, -v103, v99, v98
	v_cmp_lt_f32_e64 s[0:1], 0, v99
	s_nop 1
	v_cndmask_b32_e64 v99, v102, v103, s[0:1]
	v_mul_f32_e32 v102, 0x37800000, v99
	v_cndmask_b32_e32 v99, v99, v102, vcc
	v_cmp_class_f32_e32 vcc, v98, v225
	s_nop 1
	v_cndmask_b32_e32 v98, v99, v98, vcc
	v_div_scale_f32 v99, s[0:1], v98, v98, 1.0
	v_rcp_f32_e32 v102, v99
	s_nop 0
	v_fma_f32 v103, -v99, v102, 1.0
	v_fmac_f32_e32 v102, v103, v102
	v_div_scale_f32 v103, vcc, 1.0, v98, 1.0
	v_mul_f32_e32 v106, v103, v102
	v_fma_f32 v107, -v99, v106, v103
	v_fmac_f32_e32 v106, v107, v102
	v_fma_f32 v99, -v99, v106, v103
	v_div_fmas_f32 v99, v99, v102, v106
	v_div_fixup_f32 v98, v99, v98, 1.0
	v_mov_b32_e32 v102, v96
	v_mov_b32_e32 v103, v76
	v_mov_b32_e32 v76, v97
	v_pk_mul_f32 v[102:103], v[98:99], v[102:103] op_sel_hi:[0,1]
	v_pk_mul_f32 v[76:77], v[98:99], v[76:77] op_sel_hi:[0,1]
	v_pk_fma_f32 v[96:97], v[48:49], v[76:77], v[6:7]
	v_pk_fma_f32 v[76:77], v[50:51], v[102:103], v[4:5]
	v_mov_b32_e32 v102, v100
	v_mov_b32_e32 v103, v78
	v_mov_b32_e32 v78, v101
	v_pk_mul_f32 v[102:103], v[98:99], v[102:103] op_sel_hi:[0,1]
	v_pk_mul_f32 v[78:79], v[98:99], v[78:79] op_sel_hi:[0,1]
	v_pk_fma_f32 v[100:101], v[44:45], v[78:79], v[2:3]
	v_pk_fma_f32 v[78:79], v[46:47], v[102:103], v[0:1]
	v_cvt_pk_bf16_f32 v76, v76, v77
	v_cvt_pk_bf16_f32 v77, v96, v97
	v_cvt_pk_bf16_f32 v78, v78, v79
	v_cvt_pk_bf16_f32 v79, v100, v101
	v_lshl_add_u64 v[96:97], v[34:35], 0, s[60:61]
	global_store_dwordx4 v[96:97], v[76:79], off
	s_lshl_b64 s[60:61], s[4:5], 12
	s_add_i32 s4, s4, s10
	v_mov_b32_e32 v77, v80
	v_mov_b32_e32 v80, v105
	v_mov_b32_e32 v76, v104
	v_pk_mul_f32 v[78:79], v[98:99], v[80:81] op_sel_hi:[0,1]
	v_mov_b32_e32 v80, v108
	v_mov_b32_e32 v81, v82
	v_mov_b32_e32 v82, v109
	v_pk_mul_f32 v[76:77], v[98:99], v[76:77] op_sel_hi:[0,1]
	v_pk_mul_f32 v[80:81], v[98:99], v[80:81] op_sel_hi:[0,1]
	v_pk_mul_f32 v[82:83], v[98:99], v[82:83] op_sel_hi:[0,1]
	v_pk_fma_f32 v[78:79], v[56:57], v[78:79], v[14:15]
	v_pk_fma_f32 v[76:77], v[58:59], v[76:77], v[12:13]
	v_pk_fma_f32 v[82:83], v[52:53], v[82:83], v[10:11]
	v_pk_fma_f32 v[80:81], v[54:55], v[80:81], v[8:9]
	v_cvt_pk_bf16_f32 v76, v76, v77
	v_cvt_pk_bf16_f32 v77, v78, v79
	v_cvt_pk_bf16_f32 v78, v80, v81
	v_cvt_pk_bf16_f32 v79, v82, v83
	global_store_dwordx4 v[96:97], v[76:79], off offset:1024
	v_pk_mul_f32 v[80:81], v[98:99], v[114:115] op_sel_hi:[0,1]
	v_pk_mul_f32 v[82:83], v[98:99], v[86:87] op_sel_hi:[0,1]
	v_pk_mul_f32 v[76:77], v[98:99], v[112:113] op_sel_hi:[0,1]
	v_pk_mul_f32 v[78:79], v[98:99], v[84:85] op_sel_hi:[0,1]
	v_pk_fma_f32 v[78:79], v[64:65], v[78:79], v[22:23]
	v_pk_fma_f32 v[76:77], v[66:67], v[76:77], v[20:21]
	v_pk_fma_f32 v[82:83], v[60:61], v[82:83], v[18:19]
	v_pk_fma_f32 v[80:81], v[62:63], v[80:81], v[16:17]
	v_cvt_pk_bf16_f32 v76, v76, v77
	v_cvt_pk_bf16_f32 v77, v78, v79
	v_cvt_pk_bf16_f32 v78, v80, v81
	v_cvt_pk_bf16_f32 v79, v82, v83
	global_store_dwordx4 v[96:97], v[76:79], off offset:2048
	v_pk_mul_f32 v[80:81], v[94:95], v[98:99] op_sel_hi:[1,0]
	v_pk_mul_f32 v[82:83], v[90:91], v[98:99] op_sel_hi:[1,0]
	v_pk_mul_f32 v[76:77], v[92:93], v[98:99] op_sel_hi:[1,0]
	v_pk_mul_f32 v[78:79], v[88:89], v[98:99] op_sel_hi:[1,0]
	v_pk_fma_f32 v[76:77], v[74:75], v[76:77], v[28:29]
	v_pk_fma_f32 v[78:79], v[72:73], v[78:79], v[30:31]
	v_pk_fma_f32 v[82:83], v[68:69], v[82:83], v[26:27]
	v_pk_fma_f32 v[80:81], v[70:71], v[80:81], v[24:25]
	v_cvt_pk_bf16_f32 v76, v76, v77
	v_cvt_pk_bf16_f32 v77, v78, v79
	v_cvt_pk_bf16_f32 v78, v80, v81
	v_cvt_pk_bf16_f32 v79, v82, v83
	global_store_dwordx4 v[96:97], v[76:79], off offset:3072
	s_cmpk_lt_i32 s56, 0x800
	s_waitcnt vmcnt(7)
	v_lshlrev_b32_e32 v97, 16, v195
	v_lshlrev_b32_e32 v96, 16, v194
	v_and_b32_e32 v77, 0xffff0000, v195
	v_and_b32_e32 v76, 0xffff0000, v194
	v_lshlrev_b32_e32 v101, 16, v197
	v_lshlrev_b32_e32 v100, 16, v196
	v_and_b32_e32 v79, 0xffff0000, v197
	v_and_b32_e32 v78, 0xffff0000, v196
	v_pk_mul_f32 v[98:99], v[76:77], v[76:77]
	v_pk_mul_f32 v[102:103], v[78:79], v[78:79]
	s_waitcnt vmcnt(4)
	v_lshlrev_b32_e32 v92, 16, v206
	v_and_b32_e32 v93, 0xffff0000, v206
	v_pk_fma_f32 v[98:99], v[96:97], v[96:97], v[98:99]
	v_pk_fma_f32 v[102:103], v[100:101], v[100:101], v[102:103]
	v_lshlrev_b32_e32 v105, 16, v199
	v_lshlrev_b32_e32 v104, 16, v198
	v_and_b32_e32 v81, 0xffff0000, v199
	v_and_b32_e32 v80, 0xffff0000, v198
	v_lshlrev_b32_e32 v109, 16, v201
	v_lshlrev_b32_e32 v108, 16, v200
	v_and_b32_e32 v83, 0xffff0000, v201
	v_and_b32_e32 v82, 0xffff0000, v200
	v_pk_mul_f32 v[106:107], v[80:81], v[80:81]
	v_pk_mul_f32 v[110:111], v[82:83], v[82:83]
	v_mul_f32_e32 v116, v92, v92
	v_mul_f32_e32 v117, v93, v93
	v_pk_add_f32 v[98:99], v[98:99], v[98:99] op_sel:[0,1] op_sel_hi:[1,0]
	v_pk_add_f32 v[102:103], v[102:103], v[102:103] op_sel:[0,1] op_sel_hi:[1,0]
	v_lshlrev_b32_e32 v88, 16, v207
	v_and_b32_e32 v89, 0xffff0000, v207
	v_pk_fma_f32 v[106:107], v[104:105], v[104:105], v[106:107]
	v_pk_fma_f32 v[110:111], v[108:109], v[108:109], v[110:111]
	v_mov_b32_e32 v99, v116
	v_mov_b32_e32 v103, v117
	v_mul_f32_e32 v118, v88, v88
	v_mul_f32_e32 v119, v89, v89
	v_pk_add_f32 v[98:99], v[98:99], v[102:103]
	v_pk_add_f32 v[102:103], v[106:107], v[106:107] op_sel:[0,1] op_sel_hi:[1,0]
	v_pk_add_f32 v[106:107], v[110:111], v[110:111] op_sel:[0,1] op_sel_hi:[1,0]
	v_mov_b32_e32 v103, v118
	v_mov_b32_e32 v107, v119
	v_lshlrev_b32_e32 v112, 16, v202
	v_and_b32_e32 v113, 0xffff0000, v202
	v_lshlrev_b32_e32 v84, 16, v203
	v_and_b32_e32 v85, 0xffff0000, v203
	v_pk_add_f32 v[102:103], v[102:103], v[106:107]
	v_lshlrev_b32_e32 v94, 16, v208
	v_and_b32_e32 v95, 0xffff0000, v208
	v_pk_add_f32 v[98:99], v[98:99], v[102:103]
	v_mul_f32_e32 v102, v113, v113
	v_mul_f32_e32 v106, v85, v85
	v_mul_f32_e32 v120, v94, v94
	v_mul_f32_e32 v121, v95, v95
	v_pk_fma_f32 v[102:103], v[112:113], v[112:113], v[102:103] op_sel_hi:[1,1,0]
	v_pk_fma_f32 v[106:107], v[84:85], v[84:85], v[106:107] op_sel_hi:[1,1,0]
	v_lshlrev_b32_e32 v114, 16, v204
	v_and_b32_e32 v115, 0xffff0000, v204
	v_lshlrev_b32_e32 v86, 16, v205
	v_and_b32_e32 v87, 0xffff0000, v205
	v_mov_b32_e32 v103, v120
	v_mov_b32_e32 v107, v121
	v_lshlrev_b32_e32 v90, 16, v209
	v_and_b32_e32 v91, 0xffff0000, v209
	v_pk_add_f32 v[102:103], v[102:103], v[106:107]
	v_mul_f32_e32 v106, v115, v115
	v_mul_f32_e32 v110, v87, v87
	v_mul_f32_e32 v122, v90, v90
	v_mul_f32_e32 v123, v91, v91
	v_pk_fma_f32 v[106:107], v[114:115], v[114:115], v[106:107] op_sel_hi:[1,1,0]
	v_pk_fma_f32 v[110:111], v[86:87], v[86:87], v[110:111] op_sel_hi:[1,1,0]
	v_mov_b32_e32 v107, v122
	v_mov_b32_e32 v111, v123
	v_pk_add_f32 v[106:107], v[106:107], v[110:111]
	s_nop 0
	v_pk_add_f32 v[102:103], v[102:103], v[106:107]
	s_nop 0
	v_pk_add_f32 v[98:99], v[98:99], v[102:103]
	s_nop 0
	v_add_f32_e32 v98, v98, v99
	v_mbcnt_lo_u32_b32 v99, -1, 0
	v_mbcnt_hi_u32_b32 v99, -1, v99
	s_nop 0
	v_lshlrev_b32_e32 v99, 2, v99
	v_xor_b32_e32 v99, 4, v99
	ds_bpermute_b32 v99, v99, v98
	s_waitcnt lgkmcnt(0)
	v_add_f32_e32 v98, v98, v99
	v_mbcnt_lo_u32_b32 v99, -1, 0
	v_mbcnt_hi_u32_b32 v99, -1, v99
	s_nop 0
	v_lshlrev_b32_e32 v99, 2, v99
	v_xor_b32_e32 v99, 8, v99
	ds_bpermute_b32 v99, v99, v98
	s_waitcnt lgkmcnt(0)
	v_add_f32_e32 v98, v98, v99
	v_mbcnt_lo_u32_b32 v99, -1, 0
	v_mbcnt_hi_u32_b32 v99, -1, v99
	s_nop 0
	v_lshlrev_b32_e32 v99, 2, v99
	v_xor_b32_e32 v99, 16, v99
	ds_bpermute_b32 v99, v99, v98
	s_waitcnt lgkmcnt(0)
	v_add_f32_e32 v98, v98, v99
	v_mbcnt_lo_u32_b32 v99, -1, 0
	v_mbcnt_hi_u32_b32 v99, -1, v99
	s_nop 0
	v_lshlrev_b32_e32 v99, 2, v99
	v_xor_b32_e32 v99, 32, v99
	ds_bpermute_b32 v99, v99, v98
	s_waitcnt lgkmcnt(0)
	v_add_f32_e32 v98, v98, v99
	v_mbcnt_lo_u32_b32 v99, -1, 0
	v_mbcnt_hi_u32_b32 v99, -1, v99
	s_nop 0
	v_lshlrev_b32_e32 v99, 2, v99
	v_xor_b32_e32 v99, 64, v99
	ds_bpermute_b32 v99, v99, v98
	s_waitcnt lgkmcnt(0)
	v_add_f32_e32 v98, v98, v99
	v_mbcnt_lo_u32_b32 v99, -1, 0
	v_mbcnt_hi_u32_b32 v99, -1, v99
	s_nop 0
	v_lshlrev_b32_e32 v99, 2, v99
	v_xor_b32_e32 v99, 0x80, v99
	ds_bpermute_b32 v99, v99, v98
	s_waitcnt lgkmcnt(0)
	v_add_f32_e32 v98, v98, v99
	v_fmamk_f32 v98, v98, 0x3a000000, v224
	v_cmp_gt_f32_e32 vcc, s41, v98
	v_mul_f32_e32 v99, 0x4f800000, v98
	s_nop 0
	v_cndmask_b32_e32 v98, v98, v99, vcc
	v_sqrt_f32_e32 v99, v98
	s_nop 0
	v_add_u32_e32 v102, -1, v99
	v_fma_f32 v103, -v102, v99, v98
	v_cmp_ge_f32_e64 s[0:1], 0, v103
	v_add_u32_e32 v103, 1, v99
	s_nop 0
	v_cndmask_b32_e64 v102, v99, v102, s[0:1]
	v_fma_f32 v99, -v103, v99, v98
	v_cmp_lt_f32_e64 s[0:1], 0, v99
	s_nop 1
	v_cndmask_b32_e64 v99, v102, v103, s[0:1]
	v_mul_f32_e32 v102, 0x37800000, v99
	v_cndmask_b32_e32 v99, v99, v102, vcc
	v_cmp_class_f32_e32 vcc, v98, v225
	s_nop 1
	v_cndmask_b32_e32 v98, v99, v98, vcc
	v_div_scale_f32 v99, s[0:1], v98, v98, 1.0
	v_rcp_f32_e32 v102, v99
	s_nop 0
	v_fma_f32 v103, -v99, v102, 1.0
	v_fmac_f32_e32 v102, v103, v102
	v_div_scale_f32 v103, vcc, 1.0, v98, 1.0
	v_mul_f32_e32 v106, v103, v102
	v_fma_f32 v107, -v99, v106, v103
	v_fmac_f32_e32 v106, v107, v102
	v_fma_f32 v99, -v99, v106, v103
	v_div_fmas_f32 v99, v99, v102, v106
	v_div_fixup_f32 v98, v99, v98, 1.0
	v_mov_b32_e32 v103, v76
	v_mov_b32_e32 v76, v97
	v_mov_b32_e32 v102, v96
	v_pk_mul_f32 v[76:77], v[98:99], v[76:77] op_sel_hi:[0,1]
	v_pk_mul_f32 v[102:103], v[98:99], v[102:103] op_sel_hi:[0,1]
	v_pk_fma_f32 v[6:7], v[48:49], v[76:77], v[6:7]
	v_mov_b32_e32 v48, v100
	v_mov_b32_e32 v49, v78
	v_mov_b32_e32 v78, v101
	v_pk_fma_f32 v[4:5], v[50:51], v[102:103], v[4:5]
	v_pk_mul_f32 v[48:49], v[98:99], v[48:49] op_sel_hi:[0,1]
	v_pk_mul_f32 v[50:51], v[98:99], v[78:79] op_sel_hi:[0,1]
	v_pk_fma_f32 v[44:45], v[44:45], v[50:51], v[2:3]
	v_pk_fma_f32 v[2:3], v[46:47], v[48:49], v[0:1]
	v_cvt_pk_bf16_f32 v0, v4, v5
	v_cvt_pk_bf16_f32 v1, v6, v7
	v_cvt_pk_bf16_f32 v2, v2, v3
	v_cvt_pk_bf16_f32 v3, v44, v45
	v_lshl_add_u64 v[4:5], v[34:35], 0, s[60:61]
	global_store_dwordx4 v[4:5], v[0:3], off
	v_mov_b32_e32 v6, v108
	v_mov_b32_e32 v7, v82
	v_mov_b32_e32 v0, v104
	v_mov_b32_e32 v1, v80
	v_pk_mul_f32 v[0:1], v[98:99], v[0:1] op_sel_hi:[0,1]
	v_mov_b32_e32 v80, v105
	v_mov_b32_e32 v82, v109
	v_pk_mul_f32 v[2:3], v[98:99], v[80:81] op_sel_hi:[0,1]
	v_pk_fma_f32 v[0:1], v[58:59], v[0:1], v[12:13]
	v_pk_mul_f32 v[6:7], v[98:99], v[6:7] op_sel_hi:[0,1]
	v_pk_mul_f32 v[12:13], v[98:99], v[82:83] op_sel_hi:[0,1]
	v_pk_fma_f32 v[2:3], v[56:57], v[2:3], v[14:15]
	v_pk_fma_f32 v[10:11], v[52:53], v[12:13], v[10:11]
	v_pk_fma_f32 v[6:7], v[54:55], v[6:7], v[8:9]
	v_cvt_pk_bf16_f32 v0, v0, v1
	v_cvt_pk_bf16_f32 v1, v2, v3
	v_cvt_pk_bf16_f32 v2, v6, v7
	v_cvt_pk_bf16_f32 v3, v10, v11
	global_store_dwordx4 v[4:5], v[0:3], off offset:1024
	v_pk_mul_f32 v[6:7], v[98:99], v[114:115] op_sel_hi:[0,1]
	v_pk_mul_f32 v[8:9], v[98:99], v[86:87] op_sel_hi:[0,1]
	v_pk_mul_f32 v[0:1], v[98:99], v[112:113] op_sel_hi:[0,1]
	v_pk_mul_f32 v[2:3], v[98:99], v[84:85] op_sel_hi:[0,1]
	v_pk_fma_f32 v[2:3], v[64:65], v[2:3], v[22:23]
	v_pk_fma_f32 v[0:1], v[66:67], v[0:1], v[20:21]
	v_pk_fma_f32 v[8:9], v[60:61], v[8:9], v[18:19]
	v_pk_fma_f32 v[6:7], v[62:63], v[6:7], v[16:17]
	v_cvt_pk_bf16_f32 v0, v0, v1
	v_cvt_pk_bf16_f32 v1, v2, v3
	v_cvt_pk_bf16_f32 v2, v6, v7
	v_cvt_pk_bf16_f32 v3, v8, v9
	global_store_dwordx4 v[4:5], v[0:3], off offset:2048
	v_pk_mul_f32 v[6:7], v[94:95], v[98:99] op_sel_hi:[1,0]
	v_pk_mul_f32 v[8:9], v[90:91], v[98:99] op_sel_hi:[1,0]
	v_pk_mul_f32 v[0:1], v[92:93], v[98:99] op_sel_hi:[1,0]
	v_pk_mul_f32 v[2:3], v[88:89], v[98:99] op_sel_hi:[1,0]
	v_pk_fma_f32 v[0:1], v[74:75], v[0:1], v[28:29]
	v_pk_fma_f32 v[2:3], v[72:73], v[2:3], v[30:31]
	v_pk_fma_f32 v[8:9], v[68:69], v[8:9], v[26:27]
	v_pk_fma_f32 v[6:7], v[70:71], v[6:7], v[24:25]
	v_cvt_pk_bf16_f32 v0, v0, v1
	v_cvt_pk_bf16_f32 v1, v2, v3
	v_cvt_pk_bf16_f32 v2, v6, v7
	v_cvt_pk_bf16_f32 v3, v8, v9
	global_store_dwordx4 v[4:5], v[0:3], off offset:3072
	s_cbranch_scc1 .LBB0_919
